# GEMM loops: 8 phases merged into 4 super-phases (32 MFMA per segment, half the barriers), B1 reads hoisted, JIT vmcnt
# baseline (speedup 1.0000x reference)
.LBB0_265:
	s_lshl_b32 s4, s4, 5
	s_and_b32 s9, s4, 0x60
	s_mov_b64 s[4:5], 0x80
	s_add_i32 m0, s21, 0x18000
	v_lshl_add_u64 v[8:9], v[8:9], 0, s[4:5]
	s_lshl_b32 s8, s3, 13
	s_lshl_b32 s16, s9, 7
	s_waitcnt vmcnt(2)
	s_barrier
	global_load_lds_dwordx4 v[8:9], off
	v_lshl_add_u64 v[6:7], v[6:7], 0, s[4:5]
	s_add_i32 m0, s21, 0x1a000
	s_add_i32 s41, s21, 0x8000
	s_add_i32 s42, s21, 0xa000
	global_load_lds_dwordx4 v[6:7], off
	v_lshl_add_u64 v[4:5], v[4:5], 0, s[4:5]
	s_mov_b32 m0, s41
	s_add_u32 s6, s24, 0x80080
	global_load_lds_dwordx4 v[4:5], off
	v_lshl_add_u64 v[2:3], v[2:3], 0, s[4:5]
	s_mov_b32 m0, s42
	s_addc_u32 s7, s25, 0
	global_load_lds_dwordx4 v[2:3], off
	s_add_i32 m0, s21, 0x1c000
	v_lshl_add_u64 v[2:3], s[6:7], 0, v[134:135]
	global_load_lds_dwordx4 v[2:3], off
	v_lshl_add_u64 v[2:3], s[6:7], 0, v[130:131]
	s_add_i32 m0, s21, 0x1e000
	s_add_i32 s45, 0, 0x10000
	global_load_lds_dwordx4 v[2:3], off
	v_lshrrev_b32_e32 v3, 1, v11
	v_and_b32_e32 v3, 24, v3
	v_and_b32_e32 v2, 15, v11
	v_lshlrev_b32_e32 v4, 1, v3
	v_lshl_or_b32 v1, s3, 6, v2
	v_lshl_or_b32 v2, v2, 6, v4
	v_lshlrev_b32_e32 v4, 2, v11
	v_and_b32_e32 v4, 32, v4
	v_bitop3_b32 v5, v2, s8, v4 bitop3:0xde
	v_bitop3_b32 v150, v2, s16, v4 bitop3:0xde
	v_lshlrev_b32_e32 v2, 15, v15
	v_and_b32_e32 v2, 0xffff0000, v2
	v_or_b32_e32 v151, s9, v3
	v_lshl_add_u32 v2, v14, 12, v2
	v_and_b32_e32 v3, 1, v15
	v_lshl_or_b32 v2, v3, 6, v2
	v_lshl_add_u32 v138, v16, 1, v2
	v_lshlrev_b32_e32 v2, 15, v10
	v_and_b32_e32 v2, 0xffff0000, v2
	s_waitcnt vmcnt(6)
	v_lshl_add_u32 v2, v12, 12, v2
	v_and_b32_e32 v3, 1, v10
	v_lshl_or_b32 v2, v3, 6, v2
	s_add_i32 s46, 0, 0x14000
	s_sext_i32_i8 s52, s2
	s_ashr_i32 s43, s72, 31
	s_mov_b32 s44, s72
	v_mov_b32_e32 v139, v135
	v_lshl_add_u32 v140, v13, 1, v2
	v_mov_b32_e32 v141, v135
	v_mov_b64_e32 v[142:143], 0x780
	v_mov_b64_e32 v[144:145], 0x77f
	v_add_u32_e32 v152, s45, v150
	v_add_u32_e32 v153, 0, v5
	v_add_u32_e32 v154, s46, v150
	s_movk_i32 s47, 0x1e00
	s_barrier

.LBB0_269:
	ds_read_b128 v[146:149], v152
	ds_read_b128 v[156:159], v152 offset:1024
	ds_read_b128 v[160:163], v152 offset:2048
	ds_read_b128 v[164:167], v152 offset:3072
	s_add_u32 s24, s22, 0xfff80080
	s_addc_u32 s25, s23, -1
	s_cmp_eq_u32 s61, 28
	s_cselect_b32 s27, s9, s25
	s_cselect_b32 s26, s53, s24
	s_cselect_b32 s25, s7, s60
	s_cselect_b32 s24, s58, s59
	v_lshl_add_u64 v[202:203], s[22:23], 0, v[138:139]
	s_add_i32 m0, s21, 0xc000
	ds_read_b128 v[168:171], v153
	ds_read_b128 v[172:175], v153 offset:1024
	ds_read_b128 v[176:179], v153 offset:2048
	ds_read_b128 v[180:183], v153 offset:3072
	ds_read_b128 v[186:189], v153 offset:4096
	ds_read_b128 v[190:193], v153 offset:5120
	ds_read_b128 v[194:197], v153 offset:6144
	ds_read_b128 v[198:201], v153 offset:7168
	global_load_lds_dwordx4 v[202:203], off
	v_lshl_add_u64 v[202:203], s[22:23], 0, v[140:141]
	s_add_i32 m0, s21, 0xe000
	s_nop 0
	global_load_lds_dwordx4 v[202:203], off
	ds_read_b128 v[202:205], v154
	ds_read_b128 v[206:209], v154 offset:1024
	ds_read_b128 v[210:213], v154 offset:2048
	ds_read_b128 v[214:217], v154 offset:3072
	s_waitcnt vmcnt(8)
	s_waitcnt lgkmcnt(0)
	s_barrier
	s_setprio 1
	v_mfma_f32_16x16x32_bf16 v[126:129], v[146:149], v[168:171], v[126:129]
	v_mfma_f32_16x16x32_bf16 v[122:125], v[160:163], v[168:171], v[122:125]
	v_mfma_f32_16x16x32_bf16 v[118:121], v[146:149], v[176:179], v[118:121]
	v_mfma_f32_16x16x32_bf16 v[110:113], v[160:163], v[176:179], v[110:113]
	v_mfma_f32_16x16x32_bf16 v[102:105], v[146:149], v[186:189], v[102:105]
	v_mfma_f32_16x16x32_bf16 v[94:97], v[160:163], v[186:189], v[94:97]
	v_mfma_f32_16x16x32_bf16 v[86:89], v[146:149], v[194:197], v[86:89]
	v_mfma_f32_16x16x32_bf16 v[78:81], v[160:163], v[194:197], v[78:81]
	v_mfma_f32_16x16x32_bf16 v[126:129], v[156:159], v[172:175], v[126:129]
	v_mfma_f32_16x16x32_bf16 v[122:125], v[164:167], v[172:175], v[122:125]
	v_mfma_f32_16x16x32_bf16 v[118:121], v[156:159], v[180:183], v[118:121]
	v_mfma_f32_16x16x32_bf16 v[110:113], v[164:167], v[180:183], v[110:113]
	v_mfma_f32_16x16x32_bf16 v[102:105], v[156:159], v[190:193], v[102:105]
	v_mfma_f32_16x16x32_bf16 v[94:97], v[164:167], v[190:193], v[94:97]
	v_mfma_f32_16x16x32_bf16 v[86:89], v[156:159], v[198:201], v[86:89]
	v_mfma_f32_16x16x32_bf16 v[78:81], v[164:167], v[198:201], v[78:81]
	v_mfma_f32_16x16x32_bf16 v[114:117], v[202:205], v[168:171], v[114:117]
	v_mfma_f32_16x16x32_bf16 v[106:109], v[210:213], v[168:171], v[106:109]
	v_mfma_f32_16x16x32_bf16 v[98:101], v[202:205], v[176:179], v[98:101]
	v_mfma_f32_16x16x32_bf16 v[90:93], v[210:213], v[176:179], v[90:93]
	v_mfma_f32_16x16x32_bf16 v[82:85], v[202:205], v[186:189], v[82:85]
	v_mfma_f32_16x16x32_bf16 v[74:77], v[210:213], v[186:189], v[74:77]
	v_mfma_f32_16x16x32_bf16 v[70:73], v[202:205], v[194:197], v[70:73]
	v_mfma_f32_16x16x32_bf16 v[66:69], v[210:213], v[194:197], v[66:69]
	v_mfma_f32_16x16x32_bf16 v[114:117], v[206:209], v[172:175], v[114:117]
	v_mfma_f32_16x16x32_bf16 v[106:109], v[214:217], v[172:175], v[106:109]
	v_mfma_f32_16x16x32_bf16 v[98:101], v[206:209], v[180:183], v[98:101]
	v_mfma_f32_16x16x32_bf16 v[90:93], v[214:217], v[180:183], v[90:93]
	v_mfma_f32_16x16x32_bf16 v[82:85], v[206:209], v[190:193], v[82:85]
	v_mfma_f32_16x16x32_bf16 v[74:77], v[214:217], v[190:193], v[74:77]
	v_mfma_f32_16x16x32_bf16 v[70:73], v[206:209], v[198:201], v[70:73]
	v_mfma_f32_16x16x32_bf16 v[66:69], v[214:217], v[198:201], v[66:69]
	s_setprio 0
	s_barrier
	s_add_i32 s68, s45, s29
	v_lshl_add_u64 v[218:219], s[24:25], 0, v[134:135]
	s_mov_b32 m0, s68
	global_load_lds_dwordx4 v[218:219], off
	v_lshl_add_u64 v[220:221], s[24:25], 0, v[130:131]
	s_add_i32 m0, s68, 0x2000
	s_nop 0
	global_load_lds_dwordx4 v[220:221], off
	s_mov_b32 m0, s21
	v_lshl_add_u64 v[222:223], s[26:27], 0, v[136:137]
	ds_read_b128 v[168:171], v153 offset:16384
	ds_read_b128 v[172:175], v153 offset:17408
	ds_read_b128 v[176:179], v153 offset:18432
	ds_read_b128 v[180:183], v153 offset:19456
	ds_read_b128 v[186:189], v153 offset:20480
	ds_read_b128 v[190:193], v153 offset:21504
	ds_read_b128 v[194:197], v153 offset:22528
	ds_read_b128 v[198:201], v153 offset:23552
	global_load_lds_dwordx4 v[222:223], off
	v_lshl_add_u64 v[224:225], s[26:27], 0, v[132:133]
	s_mov_b32 m0, s34
	s_nop 0
	global_load_lds_dwordx4 v[224:225], off
	s_waitcnt vmcnt(6)
	s_waitcnt lgkmcnt(0)
	s_barrier
	s_setprio 1
	v_mfma_f32_16x16x32_bf16 v[62:65], v[146:149], v[168:171], v[62:65]
	v_mfma_f32_16x16x32_bf16 v[58:61], v[160:163], v[168:171], v[58:61]
	v_mfma_f32_16x16x32_bf16 v[54:57], v[146:149], v[176:179], v[54:57]
	v_mfma_f32_16x16x32_bf16 v[46:49], v[160:163], v[176:179], v[46:49]
	v_mfma_f32_16x16x32_bf16 v[38:41], v[146:149], v[186:189], v[38:41]
	v_mfma_f32_16x16x32_bf16 v[30:33], v[160:163], v[186:189], v[30:33]
	v_mfma_f32_16x16x32_bf16 v[22:25], v[146:149], v[194:197], v[22:25]
	v_mfma_f32_16x16x32_bf16 v[14:17], v[160:163], v[194:197], v[14:17]
	v_mfma_f32_16x16x32_bf16 v[62:65], v[156:159], v[172:175], v[62:65]
	v_mfma_f32_16x16x32_bf16 v[58:61], v[164:167], v[172:175], v[58:61]
	v_mfma_f32_16x16x32_bf16 v[54:57], v[156:159], v[180:183], v[54:57]
	v_mfma_f32_16x16x32_bf16 v[46:49], v[164:167], v[180:183], v[46:49]
	v_mfma_f32_16x16x32_bf16 v[38:41], v[156:159], v[190:193], v[38:41]
	v_mfma_f32_16x16x32_bf16 v[30:33], v[164:167], v[190:193], v[30:33]
	v_mfma_f32_16x16x32_bf16 v[22:25], v[156:159], v[198:201], v[22:25]
	v_mfma_f32_16x16x32_bf16 v[14:17], v[164:167], v[198:201], v[14:17]
	v_mfma_f32_16x16x32_bf16 v[50:53], v[202:205], v[168:171], v[50:53]
	v_mfma_f32_16x16x32_bf16 v[42:45], v[210:213], v[168:171], v[42:45]
	v_mfma_f32_16x16x32_bf16 v[34:37], v[202:205], v[176:179], v[34:37]
	v_mfma_f32_16x16x32_bf16 v[26:29], v[210:213], v[176:179], v[26:29]
	v_mfma_f32_16x16x32_bf16 v[18:21], v[202:205], v[186:189], v[18:21]
	v_mfma_f32_16x16x32_bf16 v[10:13], v[210:213], v[186:189], v[10:13]
	v_mfma_f32_16x16x32_bf16 v[6:9], v[202:205], v[194:197], v[6:9]
	v_mfma_f32_16x16x32_bf16 v[2:5], v[210:213], v[194:197], v[2:5]
	v_mfma_f32_16x16x32_bf16 v[50:53], v[206:209], v[172:175], v[50:53]
	v_mfma_f32_16x16x32_bf16 v[42:45], v[214:217], v[172:175], v[42:45]
	v_mfma_f32_16x16x32_bf16 v[34:37], v[206:209], v[180:183], v[34:37]
	v_mfma_f32_16x16x32_bf16 v[26:29], v[214:217], v[180:183], v[26:29]
	v_mfma_f32_16x16x32_bf16 v[18:21], v[206:209], v[190:193], v[18:21]
	v_mfma_f32_16x16x32_bf16 v[10:13], v[214:217], v[190:193], v[10:13]
	v_mfma_f32_16x16x32_bf16 v[6:9], v[206:209], v[198:201], v[6:9]
	v_mfma_f32_16x16x32_bf16 v[2:5], v[214:217], v[198:201], v[2:5]
	s_setprio 0
	s_barrier
	s_add_u32 s68, s24, 0x80000
	s_addc_u32 s69, s25, 0
	s_add_i32 s70, s46, s29
	v_lshl_add_u64 v[146:147], s[68:69], 0, v[134:135]
	s_mov_b32 m0, s70
	s_nop 0
	global_load_lds_dwordx4 v[146:147], off
	v_lshl_add_u64 v[146:147], s[68:69], 0, v[130:131]
	s_add_i32 m0, s70, 0x2000
	s_nop 0
	global_load_lds_dwordx4 v[146:147], off
	s_add_i32 s68, 0, 0x18000
	v_add_u32_e32 v155, s68, v150
	ds_read_b128 v[146:149], v155
	ds_read_b128 v[156:159], v155 offset:1024
	ds_read_b128 v[160:163], v155 offset:2048
	ds_read_b128 v[164:167], v155 offset:3072
	s_add_u32 s26, s26, 0x80000
	s_addc_u32 s27, s27, 0
	s_mov_b32 m0, s35
	v_lshl_add_u64 v[202:203], s[26:27], 0, v[136:137]
	ds_read_b128 v[168:171], v153 offset:32768
	ds_read_b128 v[172:175], v153 offset:33792
	ds_read_b128 v[176:179], v153 offset:34816
	ds_read_b128 v[180:183], v153 offset:35840
	ds_read_b128 v[186:189], v153 offset:36864
	ds_read_b128 v[190:193], v153 offset:37888
	ds_read_b128 v[194:197], v153 offset:38912
	ds_read_b128 v[198:201], v153 offset:39936
	global_load_lds_dwordx4 v[202:203], off
	v_lshl_add_u64 v[202:203], s[26:27], 0, v[132:133]
	s_mov_b32 m0, s36
	s_nop 0
	global_load_lds_dwordx4 v[202:203], off
	v_add_u32_e32 v214, 0x1c000, v150
	ds_read_b128 v[202:205], v214
	ds_read_b128 v[206:209], v214 offset:1024
	ds_read_b128 v[210:213], v214 offset:2048
	ds_read_b128 v[214:217], v214 offset:3072
	s_waitcnt vmcnt(8)
	s_waitcnt lgkmcnt(0)
	s_barrier
	s_setprio 1
	v_mfma_f32_16x16x32_bf16 v[126:129], v[146:149], v[168:171], v[126:129]
	v_mfma_f32_16x16x32_bf16 v[122:125], v[160:163], v[168:171], v[122:125]
	v_mfma_f32_16x16x32_bf16 v[118:121], v[146:149], v[176:179], v[118:121]
	v_mfma_f32_16x16x32_bf16 v[110:113], v[160:163], v[176:179], v[110:113]
	v_mfma_f32_16x16x32_bf16 v[102:105], v[146:149], v[186:189], v[102:105]
	v_mfma_f32_16x16x32_bf16 v[94:97], v[160:163], v[186:189], v[94:97]
	v_mfma_f32_16x16x32_bf16 v[86:89], v[146:149], v[194:197], v[86:89]
	v_mfma_f32_16x16x32_bf16 v[78:81], v[160:163], v[194:197], v[78:81]
	v_mfma_f32_16x16x32_bf16 v[126:129], v[156:159], v[172:175], v[126:129]
	v_mfma_f32_16x16x32_bf16 v[122:125], v[164:167], v[172:175], v[122:125]
	v_mfma_f32_16x16x32_bf16 v[118:121], v[156:159], v[180:183], v[118:121]
	v_mfma_f32_16x16x32_bf16 v[110:113], v[164:167], v[180:183], v[110:113]
	v_mfma_f32_16x16x32_bf16 v[102:105], v[156:159], v[190:193], v[102:105]
	v_mfma_f32_16x16x32_bf16 v[94:97], v[164:167], v[190:193], v[94:97]
	v_mfma_f32_16x16x32_bf16 v[86:89], v[156:159], v[198:201], v[86:89]
	v_mfma_f32_16x16x32_bf16 v[78:81], v[164:167], v[198:201], v[78:81]
	v_mfma_f32_16x16x32_bf16 v[114:117], v[202:205], v[168:171], v[114:117]
	v_mfma_f32_16x16x32_bf16 v[106:109], v[210:213], v[168:171], v[106:109]
	v_mfma_f32_16x16x32_bf16 v[98:101], v[202:205], v[176:179], v[98:101]
	v_mfma_f32_16x16x32_bf16 v[90:93], v[210:213], v[176:179], v[90:93]
	v_mfma_f32_16x16x32_bf16 v[82:85], v[202:205], v[186:189], v[82:85]
	v_mfma_f32_16x16x32_bf16 v[74:77], v[210:213], v[186:189], v[74:77]
	v_mfma_f32_16x16x32_bf16 v[70:73], v[202:205], v[194:197], v[70:73]
	v_mfma_f32_16x16x32_bf16 v[66:69], v[210:213], v[194:197], v[66:69]
	v_mfma_f32_16x16x32_bf16 v[114:117], v[206:209], v[172:175], v[114:117]
	v_mfma_f32_16x16x32_bf16 v[106:109], v[214:217], v[172:175], v[106:109]
	v_mfma_f32_16x16x32_bf16 v[98:101], v[206:209], v[180:183], v[98:101]
	v_mfma_f32_16x16x32_bf16 v[90:93], v[214:217], v[180:183], v[90:93]
	v_mfma_f32_16x16x32_bf16 v[82:85], v[206:209], v[190:193], v[82:85]
	v_mfma_f32_16x16x32_bf16 v[74:77], v[214:217], v[190:193], v[74:77]
	v_mfma_f32_16x16x32_bf16 v[70:73], v[206:209], v[198:201], v[70:73]
	v_mfma_f32_16x16x32_bf16 v[66:69], v[214:217], v[198:201], v[66:69]
	s_setprio 0
	s_barrier
	s_add_i32 s26, 0, 0x1c000
	s_add_i32 s27, s68, s29
	v_lshl_add_u64 v[218:219], v[218:219], 0, s[4:5]
	s_mov_b32 m0, s27
	global_load_lds_dwordx4 v[218:219], off
	v_lshl_add_u64 v[218:219], v[220:221], 0, s[4:5]
	s_add_i32 m0, s27, 0x2000
	s_nop 0
	global_load_lds_dwordx4 v[218:219], off
	s_mov_b32 m0, s41
	v_lshl_add_u64 v[218:219], v[222:223], 0, s[4:5]
	ds_read_b128 v[168:171], v153 offset:49152
	ds_read_b128 v[172:175], v153 offset:50176
	ds_read_b128 v[176:179], v153 offset:51200
	ds_read_b128 v[180:183], v153 offset:52224
	ds_read_b128 v[186:189], v153 offset:53248
	ds_read_b128 v[190:193], v153 offset:54272
	ds_read_b128 v[194:197], v153 offset:55296
	ds_read_b128 v[198:201], v153 offset:56320
	global_load_lds_dwordx4 v[218:219], off
	v_lshl_add_u64 v[218:219], v[224:225], 0, s[4:5]
	s_mov_b32 m0, s42
	s_nop 0
	global_load_lds_dwordx4 v[218:219], off
	s_add_u32 s24, s24, 0x80080
	s_addc_u32 s25, s25, 0
	s_add_i32 s26, s26, s29
	v_lshl_add_u64 v[218:219], s[24:25], 0, v[134:135]
	s_mov_b32 m0, s26
	s_nop 0
	global_load_lds_dwordx4 v[218:219], off
	v_lshl_add_u64 v[218:219], s[24:25], 0, v[130:131]
	s_add_i32 m0, s26, 0x2000
	s_nop 0
	global_load_lds_dwordx4 v[218:219], off
	s_waitcnt vmcnt(8)
	s_waitcnt lgkmcnt(0)
	s_barrier
	s_setprio 1
	v_mfma_f32_16x16x32_bf16 v[62:65], v[146:149], v[168:171], v[62:65]
	v_mfma_f32_16x16x32_bf16 v[58:61], v[160:163], v[168:171], v[58:61]
	v_mfma_f32_16x16x32_bf16 v[54:57], v[146:149], v[176:179], v[54:57]
	v_mfma_f32_16x16x32_bf16 v[46:49], v[160:163], v[176:179], v[46:49]
	v_mfma_f32_16x16x32_bf16 v[38:41], v[146:149], v[186:189], v[38:41]
	v_mfma_f32_16x16x32_bf16 v[30:33], v[160:163], v[186:189], v[30:33]
	v_mfma_f32_16x16x32_bf16 v[22:25], v[146:149], v[194:197], v[22:25]
	v_mfma_f32_16x16x32_bf16 v[14:17], v[160:163], v[194:197], v[14:17]
	v_mfma_f32_16x16x32_bf16 v[62:65], v[156:159], v[172:175], v[62:65]
	v_mfma_f32_16x16x32_bf16 v[58:61], v[164:167], v[172:175], v[58:61]
	v_mfma_f32_16x16x32_bf16 v[54:57], v[156:159], v[180:183], v[54:57]
	v_mfma_f32_16x16x32_bf16 v[46:49], v[164:167], v[180:183], v[46:49]
	v_mfma_f32_16x16x32_bf16 v[38:41], v[156:159], v[190:193], v[38:41]
	v_mfma_f32_16x16x32_bf16 v[30:33], v[164:167], v[190:193], v[30:33]
	v_mfma_f32_16x16x32_bf16 v[22:25], v[156:159], v[198:201], v[22:25]
	v_mfma_f32_16x16x32_bf16 v[14:17], v[164:167], v[198:201], v[14:17]
	v_mfma_f32_16x16x32_bf16 v[50:53], v[202:205], v[168:171], v[50:53]
	v_mfma_f32_16x16x32_bf16 v[42:45], v[210:213], v[168:171], v[42:45]
	v_mfma_f32_16x16x32_bf16 v[34:37], v[202:205], v[176:179], v[34:37]
	v_mfma_f32_16x16x32_bf16 v[26:29], v[210:213], v[176:179], v[26:29]
	v_mfma_f32_16x16x32_bf16 v[18:21], v[202:205], v[186:189], v[18:21]
	v_mfma_f32_16x16x32_bf16 v[10:13], v[210:213], v[186:189], v[10:13]
	v_mfma_f32_16x16x32_bf16 v[6:9], v[202:205], v[194:197], v[6:9]
	v_mfma_f32_16x16x32_bf16 v[2:5], v[210:213], v[194:197], v[2:5]
	v_mfma_f32_16x16x32_bf16 v[50:53], v[206:209], v[172:175], v[50:53]
	v_mfma_f32_16x16x32_bf16 v[42:45], v[214:217], v[172:175], v[42:45]
	v_mfma_f32_16x16x32_bf16 v[34:37], v[206:209], v[180:183], v[34:37]
	v_mfma_f32_16x16x32_bf16 v[26:29], v[214:217], v[180:183], v[26:29]
	v_mfma_f32_16x16x32_bf16 v[18:21], v[206:209], v[190:193], v[18:21]
	v_mfma_f32_16x16x32_bf16 v[10:13], v[214:217], v[190:193], v[10:13]
	v_mfma_f32_16x16x32_bf16 v[6:9], v[206:209], v[198:201], v[6:9]
	v_mfma_f32_16x16x32_bf16 v[2:5], v[214:217], v[198:201], v[2:5]
	s_setprio 0
	s_add_i32 s61, s61, 2
	s_add_u32 s22, s22, 0x100
	s_addc_u32 s23, s23, 0
	s_add_u32 s59, s59, 0x100
	s_addc_u32 s60, s60, 0
	s_cmp_gt_u32 s61, 29
	s_barrier
	s_cbranch_scc0 .LBB0_269
	v_lshl_or_b32 v148, s52, 8, v151
	v_lshl_add_u32 v155, s20, 8, v1
	v_ashrrev_i32_e32 v149, 31, v148
	v_mov_b64_e32 v[146:147], s[54:55]
	v_mad_i64_i32 v[156:157], s[22:23], v155, s47, v[146:147]
	v_lshlrev_b64 v[148:149], 1, v[148:149]
	v_lshl_add_u64 v[156:157], v[156:157], 0, v[148:149]
	v_cvt_pk_bf16_f32 v126, v126, v127
	v_cvt_pk_bf16_f32 v127, v128, v129
	v_cvt_pk_bf16_f32 v128, v122, v123
	v_cvt_pk_bf16_f32 v129, v124, v125
	global_store_dwordx4 v[156:157], v[126:129], off
	v_cvt_pk_bf16_f32 v114, v114, v115
	v_cvt_pk_bf16_f32 v115, v116, v117
	v_cvt_pk_bf16_f32 v116, v106, v107
	v_or_b32_e32 v106, 16, v155
	v_mad_i64_i32 v[106:107], s[22:23], v106, s47, v[146:147]
	v_cvt_pk_bf16_f32 v117, v108, v109
	global_store_dwordx4 v[156:157], v[114:117], off offset:256
	s_and_b64 vcc, exec, s[2:3]
	s_mov_b32 s52, s6
	v_lshl_add_u64 v[114:115], v[106:107], 0, v[148:149]
	v_cvt_pk_bf16_f32 v106, v118, v119
	v_cvt_pk_bf16_f32 v107, v120, v121
	v_cvt_pk_bf16_f32 v108, v110, v111
	v_cvt_pk_bf16_f32 v109, v112, v113
	global_store_dwordx4 v[114:115], v[106:109], off
	v_cvt_pk_bf16_f32 v98, v98, v99
	v_cvt_pk_bf16_f32 v99, v100, v101
	v_cvt_pk_bf16_f32 v100, v90, v91
	v_or_b32_e32 v90, 32, v155
	v_mad_i64_i32 v[90:91], s[22:23], v90, s47, v[146:147]
	v_cvt_pk_bf16_f32 v101, v92, v93
	global_store_dwordx4 v[114:115], v[98:101], off offset:256
	s_mov_b32 s20, s8
	s_mov_b64 s[24:25], s[18:19]
	v_lshl_add_u64 v[98:99], v[90:91], 0, v[148:149]
	v_cvt_pk_bf16_f32 v90, v102, v103
	v_cvt_pk_bf16_f32 v91, v104, v105
	v_cvt_pk_bf16_f32 v92, v94, v95
	v_cvt_pk_bf16_f32 v93, v96, v97
	global_store_dwordx4 v[98:99], v[90:93], off
	v_cvt_pk_bf16_f32 v82, v82, v83
	v_cvt_pk_bf16_f32 v83, v84, v85
	v_cvt_pk_bf16_f32 v84, v74, v75
	v_or_b32_e32 v74, 48, v155
	v_mad_i64_i32 v[74:75], s[22:23], v74, s47, v[146:147]
	v_cvt_pk_bf16_f32 v85, v76, v77
	global_store_dwordx4 v[98:99], v[82:85], off offset:256
	s_nop 1
	v_lshl_add_u64 v[82:83], v[74:75], 0, v[148:149]
	v_cvt_pk_bf16_f32 v74, v86, v87
	v_cvt_pk_bf16_f32 v75, v88, v89
	v_cvt_pk_bf16_f32 v76, v78, v79
	v_cvt_pk_bf16_f32 v77, v80, v81
	global_store_dwordx4 v[82:83], v[74:77], off
	v_cvt_pk_bf16_f32 v70, v70, v71
	v_cvt_pk_bf16_f32 v71, v72, v73
	v_cvt_pk_bf16_f32 v72, v66, v67
	v_add_u32_e32 v66, 0x80, v155
	v_mad_i64_i32 v[66:67], s[22:23], v66, s47, v[146:147]
	v_lshl_add_u64 v[66:67], v[66:67], 0, v[148:149]
	v_cvt_pk_bf16_f32 v73, v68, v69
	global_store_dwordx4 v[82:83], v[70:73], off offset:256
	v_cvt_pk_bf16_f32 v62, v62, v63
	v_cvt_pk_bf16_f32 v63, v64, v65
	v_cvt_pk_bf16_f32 v64, v58, v59
	v_cvt_pk_bf16_f32 v65, v60, v61
	global_store_dwordx4 v[66:67], v[62:65], off
	v_cvt_pk_bf16_f32 v50, v50, v51
	v_cvt_pk_bf16_f32 v51, v52, v53
	v_cvt_pk_bf16_f32 v52, v42, v43
	v_add_u32_e32 v42, 0x90, v155
	v_mad_i64_i32 v[42:43], s[22:23], v42, s47, v[146:147]
	v_cvt_pk_bf16_f32 v53, v44, v45
	global_store_dwordx4 v[66:67], v[50:53], off offset:256
	s_nop 1
	v_lshl_add_u64 v[50:51], v[42:43], 0, v[148:149]
	v_cvt_pk_bf16_f32 v42, v54, v55
	v_cvt_pk_bf16_f32 v43, v56, v57
	v_cvt_pk_bf16_f32 v44, v46, v47
	v_cvt_pk_bf16_f32 v45, v48, v49
	global_store_dwordx4 v[50:51], v[42:45], off
	v_cvt_pk_bf16_f32 v34, v34, v35
	v_cvt_pk_bf16_f32 v35, v36, v37
	v_cvt_pk_bf16_f32 v36, v26, v27
	v_add_u32_e32 v26, 0xa0, v155
	v_mad_i64_i32 v[26:27], s[22:23], v26, s47, v[146:147]
	v_cvt_pk_bf16_f32 v37, v28, v29
	global_store_dwordx4 v[50:51], v[34:37], off offset:256
	s_nop 1
	v_lshl_add_u64 v[34:35], v[26:27], 0, v[148:149]
	v_cvt_pk_bf16_f32 v26, v38, v39
	v_cvt_pk_bf16_f32 v27, v40, v41
	v_cvt_pk_bf16_f32 v28, v30, v31
	v_cvt_pk_bf16_f32 v29, v32, v33
	global_store_dwordx4 v[34:35], v[26:29], off
	v_cvt_pk_bf16_f32 v18, v18, v19
	v_cvt_pk_bf16_f32 v19, v20, v21
	v_cvt_pk_bf16_f32 v20, v10, v11
	v_add_u32_e32 v10, 0xb0, v155
	v_mad_i64_i32 v[10:11], s[22:23], v10, s47, v[146:147]
	v_cvt_pk_bf16_f32 v21, v12, v13
	global_store_dwordx4 v[34:35], v[18:21], off offset:256
	s_mov_b64 s[22:23], s[16:17]
	s_nop 0
	v_lshl_add_u64 v[18:19], v[10:11], 0, v[148:149]
	v_cvt_pk_bf16_f32 v10, v22, v23
	v_cvt_pk_bf16_f32 v11, v24, v25
	v_cvt_pk_bf16_f32 v12, v14, v15
	v_cvt_pk_bf16_f32 v13, v16, v17
	global_store_dwordx4 v[18:19], v[10:13], off
	v_cvt_pk_bf16_f32 v6, v6, v7
	v_cvt_pk_bf16_f32 v7, v8, v9
	v_cvt_pk_bf16_f32 v8, v2, v3
	v_cvt_pk_bf16_f32 v9, v4, v5
	global_store_dwordx4 v[18:19], v[6:9], off offset:256
	s_cbranch_vccz .LBB0_266
	s_waitcnt vmcnt(0)
	s_cmpk_gt_u32 s28, 0xff
	s_cbranch_scc1 .LBB0_273
	s_barrier

.LBB0_447:
	s_lshl_b32 s4, s4, 5
	s_mov_b64 s[6:7], 0x80
	s_and_b32 s4, s4, 0x60
	s_add_i32 m0, s46, 0x18000
	v_lshl_add_u64 v[8:9], v[8:9], 0, s[6:7]
	s_lshl_b32 s16, s5, 13
	s_lshl_b32 s17, s4, 7
	s_waitcnt vmcnt(2)
	s_barrier
	global_load_lds_dwordx4 v[8:9], off
	v_lshl_add_u64 v[6:7], v[6:7], 0, s[6:7]
	s_add_i32 m0, s46, 0x1a000
	s_add_i32 s53, s46, 0x8000
	s_add_i32 s58, s46, 0xa000
	global_load_lds_dwordx4 v[6:7], off
	v_lshl_add_u64 v[4:5], v[4:5], 0, s[6:7]
	s_mov_b32 m0, s53
	s_add_u32 s8, s30, 0x20080
	global_load_lds_dwordx4 v[4:5], off
	v_lshl_add_u64 v[2:3], v[2:3], 0, s[6:7]
	s_mov_b32 m0, s58
	s_addc_u32 s9, s31, 0
	global_load_lds_dwordx4 v[2:3], off
	s_add_i32 m0, s46, 0x1c000
	v_lshl_add_u64 v[2:3], s[8:9], 0, v[132:133]
	global_load_lds_dwordx4 v[2:3], off
	v_lshl_add_u64 v[2:3], s[8:9], 0, v[136:137]
	s_add_i32 m0, s46, 0x1e000
	s_sext_i32_i8 s70, s2
	global_load_lds_dwordx4 v[2:3], off
	v_lshrrev_b32_e32 v3, 1, v10
	v_and_b32_e32 v3, 24, v3
	v_and_b32_e32 v2, 15, v10
	v_lshlrev_b32_e32 v4, 1, v3
	v_lshl_or_b32 v1, s5, 6, v2
	v_lshl_or_b32 v2, v2, 6, v4
	v_lshlrev_b32_e32 v4, 2, v10
	v_and_b32_e32 v4, 32, v4
	v_bitop3_b32 v5, v2, s16, v4 bitop3:0xde
	v_bitop3_b32 v148, v2, s17, v4 bitop3:0xde
	v_or_b32_e32 v149, s4, v3
	v_lshrrev_b32_e32 v3, 1, v11
	v_mul_lo_u32 v2, v13, s3
	s_mov_b32 s2, 0xf000
	v_mad_u64_u32 v[2:3], s[4:5], v3, s2, v[2:3]
	v_or_b32_e32 v2, v2, v12
	v_add_lshl_u32 v2, v2, v14, 1
	v_mov_b32_e32 v3, v133
	s_mov_b64 s[4:5], 0xf0080
	v_lshl_add_u64 v[138:139], v[2:3], 0, s[4:5]
	v_lshrrev_b32_e32 v3, 1, v15
	v_mul_lo_u32 v2, v16, s3
	v_mad_u64_u32 v[2:3], s[2:3], v3, s2, v[2:3]
	s_waitcnt vmcnt(6)
	v_or_b32_e32 v2, v2, v17
	v_add_lshl_u32 v2, v2, v18, 1
	v_mov_b32_e32 v3, v133
	s_add_i32 s61, 0, 0x10000
	s_add_i32 s71, 0, 0x14000
	s_ashr_i32 s59, s72, 31
	s_mov_b32 s60, s72
	v_lshl_add_u64 v[140:141], v[2:3], 0, s[4:5]
	v_mov_b64_e32 v[142:143], 0x400
	v_mov_b64_e32 v[144:145], 0x3ff
	v_add_u32_e32 v150, s61, v148
	v_add_u32_e32 v151, 0, v5
	v_add_u32_e32 v152, s71, v148
	s_mov_b64 s[8:9], 0x80000
	s_mov_b32 s74, 0x80000
	s_mov_b64 s[16:17], 0x90000
	s_mov_b32 s75, 0x90000
	s_mov_b64 s[18:19], 0xa0000
	s_mov_b32 s76, 0xa0000
	s_mov_b64 s[20:21], 0xb0000
	s_mov_b32 s77, 0xb0000
	s_barrier

.LBB0_457:
	ds_read_b128 v[154:157], v150
	ds_read_b128 v[158:161], v150 offset:1024
	ds_read_b128 v[162:165], v150 offset:2048
	ds_read_b128 v[166:169], v150 offset:3072
	s_add_u32 s4, s28, 0x100
	s_addc_u32 s5, s29, 0
	s_cmp_eq_u32 s81, 4
	s_cselect_b32 s35, s25, s5
	s_cselect_b32 s34, s24, s4
	s_cselect_b32 s31, s23, s80
	s_cselect_b32 s30, s78, s79
	v_lshl_add_u64 v[146:147], s[28:29], 0, v[138:139]
	s_add_i32 m0, s46, 0xc000
	ds_read_b128 v[170:173], v151
	ds_read_b128 v[174:177], v151 offset:1024
	ds_read_b128 v[178:181], v151 offset:2048
	ds_read_b128 v[186:189], v151 offset:3072
	ds_read_b128 v[190:193], v151 offset:4096
	ds_read_b128 v[194:197], v151 offset:5120
	ds_read_b128 v[198:201], v151 offset:6144
	ds_read_b128 v[202:205], v151 offset:7168
	global_load_lds_dwordx4 v[146:147], off
	v_lshl_add_u64 v[146:147], s[28:29], 0, v[140:141]
	s_add_i32 m0, s46, 0xe000
	s_nop 0
	global_load_lds_dwordx4 v[146:147], off
	ds_read_b128 v[206:209], v152
	ds_read_b128 v[210:213], v152 offset:1024
	ds_read_b128 v[214:217], v152 offset:2048
	ds_read_b128 v[218:221], v152 offset:3072
	s_waitcnt vmcnt(8)
	s_waitcnt lgkmcnt(0)
	s_barrier
	s_setprio 1
	v_mfma_f32_16x16x32_bf16 v[126:129], v[154:157], v[170:173], v[126:129]
	v_mfma_f32_16x16x32_bf16 v[122:125], v[162:165], v[170:173], v[122:125]
	v_mfma_f32_16x16x32_bf16 v[114:117], v[154:157], v[178:181], v[114:117]
	v_mfma_f32_16x16x32_bf16 v[106:109], v[162:165], v[178:181], v[106:109]
	v_mfma_f32_16x16x32_bf16 v[98:101], v[154:157], v[190:193], v[98:101]
	v_mfma_f32_16x16x32_bf16 v[90:93], v[162:165], v[190:193], v[90:93]
	v_mfma_f32_16x16x32_bf16 v[82:85], v[154:157], v[198:201], v[82:85]
	v_mfma_f32_16x16x32_bf16 v[74:77], v[162:165], v[198:201], v[74:77]
	v_mfma_f32_16x16x32_bf16 v[126:129], v[158:161], v[174:177], v[126:129]
	v_mfma_f32_16x16x32_bf16 v[122:125], v[166:169], v[174:177], v[122:125]
	v_mfma_f32_16x16x32_bf16 v[114:117], v[158:161], v[186:189], v[114:117]
	v_mfma_f32_16x16x32_bf16 v[106:109], v[166:169], v[186:189], v[106:109]
	v_mfma_f32_16x16x32_bf16 v[98:101], v[158:161], v[194:197], v[98:101]
	v_mfma_f32_16x16x32_bf16 v[90:93], v[166:169], v[194:197], v[90:93]
	v_mfma_f32_16x16x32_bf16 v[82:85], v[158:161], v[202:205], v[82:85]
	v_mfma_f32_16x16x32_bf16 v[74:77], v[166:169], v[202:205], v[74:77]
	v_mfma_f32_16x16x32_bf16 v[118:121], v[206:209], v[170:173], v[118:121]
	v_mfma_f32_16x16x32_bf16 v[110:113], v[214:217], v[170:173], v[110:113]
	v_mfma_f32_16x16x32_bf16 v[102:105], v[206:209], v[178:181], v[102:105]
	v_mfma_f32_16x16x32_bf16 v[94:97], v[214:217], v[178:181], v[94:97]
	v_mfma_f32_16x16x32_bf16 v[86:89], v[206:209], v[190:193], v[86:89]
	v_mfma_f32_16x16x32_bf16 v[78:81], v[214:217], v[190:193], v[78:81]
	v_mfma_f32_16x16x32_bf16 v[70:73], v[206:209], v[198:201], v[70:73]
	v_mfma_f32_16x16x32_bf16 v[66:69], v[214:217], v[198:201], v[66:69]
	v_mfma_f32_16x16x32_bf16 v[118:121], v[210:213], v[174:177], v[118:121]
	v_mfma_f32_16x16x32_bf16 v[110:113], v[218:221], v[174:177], v[110:113]
	v_mfma_f32_16x16x32_bf16 v[102:105], v[210:213], v[186:189], v[102:105]
	v_mfma_f32_16x16x32_bf16 v[94:97], v[218:221], v[186:189], v[94:97]
	v_mfma_f32_16x16x32_bf16 v[86:89], v[210:213], v[194:197], v[86:89]
	v_mfma_f32_16x16x32_bf16 v[78:81], v[218:221], v[194:197], v[78:81]
	v_mfma_f32_16x16x32_bf16 v[70:73], v[210:213], v[202:205], v[70:73]
	v_mfma_f32_16x16x32_bf16 v[66:69], v[218:221], v[202:205], v[66:69]
	s_setprio 0
	s_barrier
	s_add_i32 s28, s61, s45
	v_lshl_add_u64 v[146:147], s[30:31], 0, v[132:133]
	s_mov_b32 m0, s28
	global_load_lds_dwordx4 v[146:147], off
	v_lshl_add_u64 v[182:183], s[30:31], 0, v[136:137]
	s_add_i32 m0, s28, 0x2000
	s_nop 0
	global_load_lds_dwordx4 v[182:183], off
	s_mov_b32 m0, s46
	v_lshl_add_u64 v[222:223], s[34:35], 0, v[130:131]
	ds_read_b128 v[170:173], v151 offset:16384
	ds_read_b128 v[174:177], v151 offset:17408
	ds_read_b128 v[178:181], v151 offset:18432
	ds_read_b128 v[186:189], v151 offset:19456
	ds_read_b128 v[190:193], v151 offset:20480
	ds_read_b128 v[194:197], v151 offset:21504
	ds_read_b128 v[198:201], v151 offset:22528
	ds_read_b128 v[202:205], v151 offset:23552
	global_load_lds_dwordx4 v[222:223], off
	v_lshl_add_u64 v[224:225], s[34:35], 0, v[134:135]
	s_mov_b32 m0, s47
	s_nop 0
	global_load_lds_dwordx4 v[224:225], off
	s_waitcnt vmcnt(6)
	s_waitcnt lgkmcnt(0)
	s_barrier
	s_setprio 1
	v_mfma_f32_16x16x32_bf16 v[62:65], v[154:157], v[170:173], v[62:65]
	v_mfma_f32_16x16x32_bf16 v[58:61], v[162:165], v[170:173], v[58:61]
	v_mfma_f32_16x16x32_bf16 v[54:57], v[154:157], v[178:181], v[54:57]
	v_mfma_f32_16x16x32_bf16 v[46:49], v[162:165], v[178:181], v[46:49]
	v_mfma_f32_16x16x32_bf16 v[38:41], v[154:157], v[190:193], v[38:41]
	v_mfma_f32_16x16x32_bf16 v[30:33], v[162:165], v[190:193], v[30:33]
	v_mfma_f32_16x16x32_bf16 v[22:25], v[154:157], v[198:201], v[22:25]
	v_mfma_f32_16x16x32_bf16 v[14:17], v[162:165], v[198:201], v[14:17]
	v_mfma_f32_16x16x32_bf16 v[62:65], v[158:161], v[174:177], v[62:65]
	v_mfma_f32_16x16x32_bf16 v[58:61], v[166:169], v[174:177], v[58:61]
	v_mfma_f32_16x16x32_bf16 v[54:57], v[158:161], v[186:189], v[54:57]
	v_mfma_f32_16x16x32_bf16 v[46:49], v[166:169], v[186:189], v[46:49]
	v_mfma_f32_16x16x32_bf16 v[38:41], v[158:161], v[194:197], v[38:41]
	v_mfma_f32_16x16x32_bf16 v[30:33], v[166:169], v[194:197], v[30:33]
	v_mfma_f32_16x16x32_bf16 v[22:25], v[158:161], v[202:205], v[22:25]
	v_mfma_f32_16x16x32_bf16 v[14:17], v[166:169], v[202:205], v[14:17]
	v_mfma_f32_16x16x32_bf16 v[50:53], v[206:209], v[170:173], v[50:53]
	v_mfma_f32_16x16x32_bf16 v[42:45], v[214:217], v[170:173], v[42:45]
	v_mfma_f32_16x16x32_bf16 v[34:37], v[206:209], v[178:181], v[34:37]
	v_mfma_f32_16x16x32_bf16 v[26:29], v[214:217], v[178:181], v[26:29]
	v_mfma_f32_16x16x32_bf16 v[18:21], v[206:209], v[190:193], v[18:21]
	v_mfma_f32_16x16x32_bf16 v[10:13], v[214:217], v[190:193], v[10:13]
	v_mfma_f32_16x16x32_bf16 v[6:9], v[206:209], v[198:201], v[6:9]
	v_mfma_f32_16x16x32_bf16 v[2:5], v[214:217], v[198:201], v[2:5]
	v_mfma_f32_16x16x32_bf16 v[50:53], v[210:213], v[174:177], v[50:53]
	v_mfma_f32_16x16x32_bf16 v[42:45], v[218:221], v[174:177], v[42:45]
	v_mfma_f32_16x16x32_bf16 v[34:37], v[210:213], v[186:189], v[34:37]
	v_mfma_f32_16x16x32_bf16 v[26:29], v[218:221], v[186:189], v[26:29]
	v_mfma_f32_16x16x32_bf16 v[18:21], v[210:213], v[194:197], v[18:21]
	v_mfma_f32_16x16x32_bf16 v[10:13], v[218:221], v[194:197], v[10:13]
	v_mfma_f32_16x16x32_bf16 v[6:9], v[210:213], v[202:205], v[6:9]
	v_mfma_f32_16x16x32_bf16 v[2:5], v[218:221], v[202:205], v[2:5]
	s_setprio 0
	s_barrier
	s_add_u32 s28, s30, 0x20000
	s_addc_u32 s29, s31, 0
	s_add_i32 s82, s71, s45
	v_lshl_add_u64 v[154:155], s[28:29], 0, v[132:133]
	s_mov_b32 m0, s82
	s_nop 0
	global_load_lds_dwordx4 v[154:155], off
	v_lshl_add_u64 v[154:155], s[28:29], 0, v[136:137]
	s_add_i32 m0, s82, 0x2000
	s_nop 0
	global_load_lds_dwordx4 v[154:155], off
	s_add_i32 s82, 0, 0x18000
	v_add_u32_e32 v153, s82, v148
	ds_read_b128 v[154:157], v153
	ds_read_b128 v[158:161], v153 offset:1024
	ds_read_b128 v[162:165], v153 offset:2048
	ds_read_b128 v[166:169], v153 offset:3072
	s_add_u32 s28, s34, 0xf0000
	s_addc_u32 s29, s35, 0
	s_mov_b32 m0, s50
	v_lshl_add_u64 v[206:207], s[28:29], 0, v[130:131]
	ds_read_b128 v[170:173], v151 offset:32768
	ds_read_b128 v[174:177], v151 offset:33792
	ds_read_b128 v[178:181], v151 offset:34816
	ds_read_b128 v[186:189], v151 offset:35840
	ds_read_b128 v[190:193], v151 offset:36864
	ds_read_b128 v[194:197], v151 offset:37888
	ds_read_b128 v[198:201], v151 offset:38912
	ds_read_b128 v[202:205], v151 offset:39936
	global_load_lds_dwordx4 v[206:207], off
	v_lshl_add_u64 v[206:207], s[28:29], 0, v[134:135]
	s_mov_b32 m0, s51
	s_nop 0
	global_load_lds_dwordx4 v[206:207], off
	v_add_u32_e32 v218, 0x1c000, v148
	ds_read_b128 v[206:209], v218
	ds_read_b128 v[210:213], v218 offset:1024
	ds_read_b128 v[214:217], v218 offset:2048
	ds_read_b128 v[218:221], v218 offset:3072
	s_waitcnt vmcnt(8)
	s_waitcnt lgkmcnt(0)
	s_barrier
	s_setprio 1
	v_mfma_f32_16x16x32_bf16 v[126:129], v[154:157], v[170:173], v[126:129]
	v_mfma_f32_16x16x32_bf16 v[122:125], v[162:165], v[170:173], v[122:125]
	v_mfma_f32_16x16x32_bf16 v[114:117], v[154:157], v[178:181], v[114:117]
	v_mfma_f32_16x16x32_bf16 v[106:109], v[162:165], v[178:181], v[106:109]
	v_mfma_f32_16x16x32_bf16 v[98:101], v[154:157], v[190:193], v[98:101]
	v_mfma_f32_16x16x32_bf16 v[90:93], v[162:165], v[190:193], v[90:93]
	v_mfma_f32_16x16x32_bf16 v[82:85], v[154:157], v[198:201], v[82:85]
	v_mfma_f32_16x16x32_bf16 v[74:77], v[162:165], v[198:201], v[74:77]
	v_mfma_f32_16x16x32_bf16 v[126:129], v[158:161], v[174:177], v[126:129]
	v_mfma_f32_16x16x32_bf16 v[122:125], v[166:169], v[174:177], v[122:125]
	v_mfma_f32_16x16x32_bf16 v[114:117], v[158:161], v[186:189], v[114:117]
	v_mfma_f32_16x16x32_bf16 v[106:109], v[166:169], v[186:189], v[106:109]
	v_mfma_f32_16x16x32_bf16 v[98:101], v[158:161], v[194:197], v[98:101]
	v_mfma_f32_16x16x32_bf16 v[90:93], v[166:169], v[194:197], v[90:93]
	v_mfma_f32_16x16x32_bf16 v[82:85], v[158:161], v[202:205], v[82:85]
	v_mfma_f32_16x16x32_bf16 v[74:77], v[166:169], v[202:205], v[74:77]
	v_mfma_f32_16x16x32_bf16 v[118:121], v[206:209], v[170:173], v[118:121]
	v_mfma_f32_16x16x32_bf16 v[110:113], v[214:217], v[170:173], v[110:113]
	v_mfma_f32_16x16x32_bf16 v[102:105], v[206:209], v[178:181], v[102:105]
	v_mfma_f32_16x16x32_bf16 v[94:97], v[214:217], v[178:181], v[94:97]
	v_mfma_f32_16x16x32_bf16 v[86:89], v[206:209], v[190:193], v[86:89]
	v_mfma_f32_16x16x32_bf16 v[78:81], v[214:217], v[190:193], v[78:81]
	v_mfma_f32_16x16x32_bf16 v[70:73], v[206:209], v[198:201], v[70:73]
	v_mfma_f32_16x16x32_bf16 v[66:69], v[214:217], v[198:201], v[66:69]
	v_mfma_f32_16x16x32_bf16 v[118:121], v[210:213], v[174:177], v[118:121]
	v_mfma_f32_16x16x32_bf16 v[110:113], v[218:221], v[174:177], v[110:113]
	v_mfma_f32_16x16x32_bf16 v[102:105], v[210:213], v[186:189], v[102:105]
	v_mfma_f32_16x16x32_bf16 v[94:97], v[218:221], v[186:189], v[94:97]
	v_mfma_f32_16x16x32_bf16 v[86:89], v[210:213], v[194:197], v[86:89]
	v_mfma_f32_16x16x32_bf16 v[78:81], v[218:221], v[194:197], v[78:81]
	v_mfma_f32_16x16x32_bf16 v[70:73], v[210:213], v[202:205], v[70:73]
	v_mfma_f32_16x16x32_bf16 v[66:69], v[218:221], v[202:205], v[66:69]
	s_setprio 0
	s_barrier
	s_add_i32 s34, 0, 0x1c000
	s_add_i32 s28, s82, s45
	v_lshl_add_u64 v[146:147], v[146:147], 0, s[6:7]
	s_mov_b32 m0, s28
	global_load_lds_dwordx4 v[146:147], off
	v_lshl_add_u64 v[146:147], v[182:183], 0, s[6:7]
	s_add_i32 m0, s28, 0x2000
	s_nop 0
	global_load_lds_dwordx4 v[146:147], off
	s_mov_b32 m0, s53
	v_lshl_add_u64 v[146:147], v[222:223], 0, s[6:7]
	ds_read_b128 v[170:173], v151 offset:49152
	ds_read_b128 v[174:177], v151 offset:50176
	ds_read_b128 v[178:181], v151 offset:51200
	ds_read_b128 v[186:189], v151 offset:52224
	ds_read_b128 v[190:193], v151 offset:53248
	ds_read_b128 v[194:197], v151 offset:54272
	ds_read_b128 v[198:201], v151 offset:55296
	ds_read_b128 v[202:205], v151 offset:56320
	global_load_lds_dwordx4 v[146:147], off
	v_lshl_add_u64 v[146:147], v[224:225], 0, s[6:7]
	s_mov_b32 m0, s58
	s_nop 0
	global_load_lds_dwordx4 v[146:147], off
	s_add_u32 s28, s30, 0x20080
	s_addc_u32 s29, s31, 0
	s_add_i32 s30, s34, s45
	v_lshl_add_u64 v[146:147], s[28:29], 0, v[132:133]
	s_mov_b32 m0, s30
	s_nop 0
	global_load_lds_dwordx4 v[146:147], off
	v_lshl_add_u64 v[146:147], s[28:29], 0, v[136:137]
	s_add_i32 m0, s30, 0x2000
	s_nop 0
	global_load_lds_dwordx4 v[146:147], off
	s_waitcnt vmcnt(8)
	s_waitcnt lgkmcnt(0)
	s_barrier
	s_setprio 1
	v_mfma_f32_16x16x32_bf16 v[62:65], v[154:157], v[170:173], v[62:65]
	v_mfma_f32_16x16x32_bf16 v[58:61], v[162:165], v[170:173], v[58:61]
	v_mfma_f32_16x16x32_bf16 v[54:57], v[154:157], v[178:181], v[54:57]
	v_mfma_f32_16x16x32_bf16 v[46:49], v[162:165], v[178:181], v[46:49]
	v_mfma_f32_16x16x32_bf16 v[38:41], v[154:157], v[190:193], v[38:41]
	v_mfma_f32_16x16x32_bf16 v[30:33], v[162:165], v[190:193], v[30:33]
	v_mfma_f32_16x16x32_bf16 v[22:25], v[154:157], v[198:201], v[22:25]
	v_mfma_f32_16x16x32_bf16 v[14:17], v[162:165], v[198:201], v[14:17]
	v_mfma_f32_16x16x32_bf16 v[62:65], v[158:161], v[174:177], v[62:65]
	v_mfma_f32_16x16x32_bf16 v[58:61], v[166:169], v[174:177], v[58:61]
	v_mfma_f32_16x16x32_bf16 v[54:57], v[158:161], v[186:189], v[54:57]
	v_mfma_f32_16x16x32_bf16 v[46:49], v[166:169], v[186:189], v[46:49]
	v_mfma_f32_16x16x32_bf16 v[38:41], v[158:161], v[194:197], v[38:41]
	v_mfma_f32_16x16x32_bf16 v[30:33], v[166:169], v[194:197], v[30:33]
	v_mfma_f32_16x16x32_bf16 v[22:25], v[158:161], v[202:205], v[22:25]
	v_mfma_f32_16x16x32_bf16 v[14:17], v[166:169], v[202:205], v[14:17]
	v_mfma_f32_16x16x32_bf16 v[50:53], v[206:209], v[170:173], v[50:53]
	v_mfma_f32_16x16x32_bf16 v[42:45], v[214:217], v[170:173], v[42:45]
	v_mfma_f32_16x16x32_bf16 v[34:37], v[206:209], v[178:181], v[34:37]
	v_mfma_f32_16x16x32_bf16 v[26:29], v[214:217], v[178:181], v[26:29]
	v_mfma_f32_16x16x32_bf16 v[18:21], v[206:209], v[190:193], v[18:21]
	v_mfma_f32_16x16x32_bf16 v[10:13], v[214:217], v[190:193], v[10:13]
	v_mfma_f32_16x16x32_bf16 v[6:9], v[206:209], v[198:201], v[6:9]
	v_mfma_f32_16x16x32_bf16 v[2:5], v[214:217], v[198:201], v[2:5]
	v_mfma_f32_16x16x32_bf16 v[50:53], v[210:213], v[174:177], v[50:53]
	v_mfma_f32_16x16x32_bf16 v[42:45], v[218:221], v[174:177], v[42:45]
	v_mfma_f32_16x16x32_bf16 v[34:37], v[210:213], v[186:189], v[34:37]
	v_mfma_f32_16x16x32_bf16 v[26:29], v[218:221], v[186:189], v[26:29]
	v_mfma_f32_16x16x32_bf16 v[18:21], v[210:213], v[194:197], v[18:21]
	v_mfma_f32_16x16x32_bf16 v[10:13], v[218:221], v[194:197], v[10:13]
	v_mfma_f32_16x16x32_bf16 v[6:9], v[210:213], v[202:205], v[6:9]
	v_mfma_f32_16x16x32_bf16 v[2:5], v[218:221], v[202:205], v[2:5]
	s_setprio 0
	s_add_i32 s81, s81, 2
	s_add_u32 s79, s79, 0x100
	s_addc_u32 s80, s80, 0
	s_cmp_gt_u32 s81, 5
	s_mov_b64 s[28:29], s[4:5]
	s_barrier
	s_cbranch_scc0 .LBB0_457
	v_lshl_add_u32 v154, s69, 8, v1
	v_lshl_or_b32 v146, s70, 8, v149
	v_ashrrev_i32_e32 v155, 31, v154
	v_ashrrev_i32_e32 v147, 31, v146
	v_lshlrev_b64 v[156:157], 12, v[154:155]
	v_lshl_add_u64 v[156:157], s[88:89], 0, v[156:157]
	v_lshlrev_b64 v[158:159], 1, v[146:147]
	v_lshl_add_u64 v[146:147], v[156:157], 0, v[158:159]
	v_cvt_pk_bf16_f32 v126, v126, v127
	v_cvt_pk_bf16_f32 v127, v128, v129
	v_cvt_pk_bf16_f32 v128, v122, v123
	v_cvt_pk_bf16_f32 v129, v124, v125
	global_store_dwordx4 v[146:147], v[126:129], off
	v_cvt_pk_bf16_f32 v118, v118, v119
	v_cvt_pk_bf16_f32 v119, v120, v121
	v_cvt_pk_bf16_f32 v120, v110, v111
	v_or_b32_e32 v110, 16, v154
	v_ashrrev_i32_e32 v111, 31, v110
	v_lshlrev_b64 v[110:111], 12, v[110:111]
	v_lshl_add_u64 v[110:111], s[88:89], 0, v[110:111]
	v_cvt_pk_bf16_f32 v121, v112, v113
	global_store_dwordx4 v[146:147], v[118:121], off offset:256
	s_mov_b32 s70, s22
	s_mov_b32 s69, s68
	v_lshl_add_u64 v[118:119], v[110:111], 0, v[158:159]
	v_cvt_pk_bf16_f32 v110, v114, v115
	v_cvt_pk_bf16_f32 v111, v116, v117
	v_cvt_pk_bf16_f32 v112, v106, v107
	v_cvt_pk_bf16_f32 v113, v108, v109
	global_store_dwordx4 v[118:119], v[110:113], off
	v_cvt_pk_bf16_f32 v102, v102, v103
	v_cvt_pk_bf16_f32 v103, v104, v105
	v_cvt_pk_bf16_f32 v104, v94, v95
	v_or_b32_e32 v94, 32, v154
	v_ashrrev_i32_e32 v95, 31, v94
	v_lshlrev_b64 v[94:95], 12, v[94:95]
	v_lshl_add_u64 v[94:95], s[88:89], 0, v[94:95]
	v_cvt_pk_bf16_f32 v105, v96, v97
	global_store_dwordx4 v[118:119], v[102:105], off offset:256
	s_mov_b64 s[30:31], s[26:27]
	s_mov_b64 s[28:29], s[24:25]
	v_lshl_add_u64 v[102:103], v[94:95], 0, v[158:159]
	v_cvt_pk_bf16_f32 v94, v98, v99
	v_cvt_pk_bf16_f32 v95, v100, v101
	v_cvt_pk_bf16_f32 v96, v90, v91
	v_cvt_pk_bf16_f32 v97, v92, v93
	global_store_dwordx4 v[102:103], v[94:97], off
	v_cvt_pk_bf16_f32 v86, v86, v87
	v_cvt_pk_bf16_f32 v87, v88, v89
	v_cvt_pk_bf16_f32 v88, v78, v79
	v_or_b32_e32 v78, 48, v154
	v_ashrrev_i32_e32 v79, 31, v78
	v_lshlrev_b64 v[78:79], 12, v[78:79]
	v_lshl_add_u64 v[78:79], s[88:89], 0, v[78:79]
	v_cvt_pk_bf16_f32 v89, v80, v81
	global_store_dwordx4 v[102:103], v[86:89], off offset:256
	s_nop 1
	v_lshl_add_u64 v[86:87], v[78:79], 0, v[158:159]
	v_cvt_pk_bf16_f32 v78, v82, v83
	v_cvt_pk_bf16_f32 v79, v84, v85
	v_cvt_pk_bf16_f32 v80, v74, v75
	v_cvt_pk_bf16_f32 v81, v76, v77
	global_store_dwordx4 v[86:87], v[78:81], off
	v_cvt_pk_bf16_f32 v70, v70, v71
	v_cvt_pk_bf16_f32 v71, v72, v73
	v_cvt_pk_bf16_f32 v72, v66, v67
	v_cvt_pk_bf16_f32 v73, v68, v69
	global_store_dwordx4 v[86:87], v[70:73], off offset:256
	v_cvt_pk_bf16_f32 v62, v62, v63
	v_cvt_pk_bf16_f32 v63, v64, v65
	v_cvt_pk_bf16_f32 v64, v58, v59
	v_add_co_u32_e32 v58, vcc, s74, v146
	v_lshl_add_u64 v[66:67], v[146:147], 0, s[8:9]
	s_nop 0
	v_addc_co_u32_e32 v59, vcc, 0, v147, vcc
	v_cvt_pk_bf16_f32 v65, v60, v61
	global_store_dwordx4 v[58:59], v[62:65], off
	v_cvt_pk_bf16_f32 v50, v50, v51
	v_cvt_pk_bf16_f32 v51, v52, v53
	v_cvt_pk_bf16_f32 v52, v42, v43
	v_cvt_pk_bf16_f32 v53, v44, v45
	global_store_dwordx4 v[66:67], v[50:53], off offset:256
	v_cvt_pk_bf16_f32 v42, v54, v55
	v_cvt_pk_bf16_f32 v43, v56, v57
	v_cvt_pk_bf16_f32 v44, v46, v47
	v_add_co_u32_e32 v46, vcc, s75, v146
	s_nop 0
	v_lshl_add_u64 v[50:51], v[146:147], 0, s[16:17]
	v_addc_co_u32_e32 v47, vcc, 0, v147, vcc
	v_cvt_pk_bf16_f32 v45, v48, v49
	global_store_dwordx4 v[46:47], v[42:45], off
	v_cvt_pk_bf16_f32 v34, v34, v35
	v_cvt_pk_bf16_f32 v35, v36, v37
	v_cvt_pk_bf16_f32 v36, v26, v27
	v_cvt_pk_bf16_f32 v37, v28, v29
	global_store_dwordx4 v[50:51], v[34:37], off offset:256
	v_cvt_pk_bf16_f32 v26, v38, v39
	v_cvt_pk_bf16_f32 v27, v40, v41
	v_cvt_pk_bf16_f32 v28, v30, v31
	v_add_co_u32_e32 v30, vcc, s76, v146
	s_nop 0
	v_lshl_add_u64 v[34:35], v[146:147], 0, s[18:19]
	v_addc_co_u32_e32 v31, vcc, 0, v147, vcc
	v_cvt_pk_bf16_f32 v29, v32, v33
	global_store_dwordx4 v[30:31], v[26:29], off
	v_cvt_pk_bf16_f32 v18, v18, v19
	v_cvt_pk_bf16_f32 v19, v20, v21
	v_cvt_pk_bf16_f32 v20, v10, v11
	v_cvt_pk_bf16_f32 v21, v12, v13
	global_store_dwordx4 v[34:35], v[18:21], off offset:256
	v_cvt_pk_bf16_f32 v10, v22, v23
	v_cvt_pk_bf16_f32 v11, v24, v25
	v_cvt_pk_bf16_f32 v12, v14, v15
	v_add_co_u32_e32 v14, vcc, s77, v146
	s_nop 0
	v_lshl_add_u64 v[18:19], v[146:147], 0, s[20:21]
	v_addc_co_u32_e32 v15, vcc, 0, v147, vcc
	s_and_b64 vcc, exec, s[2:3]
	v_cvt_pk_bf16_f32 v13, v16, v17
	global_store_dwordx4 v[14:15], v[10:13], off
	v_cvt_pk_bf16_f32 v6, v6, v7
	v_cvt_pk_bf16_f32 v7, v8, v9
	v_cvt_pk_bf16_f32 v8, v2, v3
	v_cvt_pk_bf16_f32 v9, v4, v5
	global_store_dwordx4 v[18:19], v[6:9], off offset:256
	s_cbranch_vccz .LBB0_448
	s_waitcnt vmcnt(0)
	s_cmpk_gt_u32 s36, 0xff
	s_cbranch_scc1 .LBB0_461
	s_barrier

.LBB0_685:
	s_add_u32 s18, s38, 0x1ca70400
	s_addc_u32 s19, s39, 0
	s_lshl_b32 s5, s5, 5
	s_mov_b64 s[20:21], 0x80
	s_and_b32 s7, s5, 0x60
	s_add_i32 m0, s41, 0x18000
	v_lshl_add_u64 v[8:9], v[8:9], 0, s[20:21]
	s_lshl_b32 s1, s4, 13
	s_lshl_b32 s5, s7, 7
	s_waitcnt vmcnt(2)
	s_barrier
	global_load_lds_dwordx4 v[8:9], off
	v_lshl_add_u64 v[6:7], v[6:7], 0, s[20:21]
	s_add_i32 m0, s41, 0x1a000
	s_add_i32 s47, s41, 0x8000
	s_add_i32 s48, s41, 0xa000
	global_load_lds_dwordx4 v[6:7], off
	v_lshl_add_u64 v[4:5], v[4:5], 0, s[20:21]
	s_mov_b32 m0, s47
	s_add_u32 s8, s28, 0x80080
	global_load_lds_dwordx4 v[4:5], off
	v_lshl_add_u64 v[2:3], v[2:3], 0, s[20:21]
	s_mov_b32 m0, s48
	s_addc_u32 s9, s29, 0
	global_load_lds_dwordx4 v[2:3], off
	s_add_i32 m0, s41, 0x1c000
	v_lshl_add_u64 v[2:3], s[8:9], 0, v[164:165]
	global_load_lds_dwordx4 v[2:3], off
	v_lshl_add_u64 v[2:3], s[8:9], 0, v[168:169]
	s_add_i32 m0, s41, 0x1e000
	s_add_i32 s59, 0, 0x10000
	global_load_lds_dwordx4 v[2:3], off
	v_bfe_u32 v3, v10, 4, 2
	v_and_b32_e32 v2, 15, v10
	v_lshlrev_b32_e32 v4, 4, v3
	v_lshl_or_b32 v1, s4, 6, v2
	v_lshl_or_b32 v2, v2, 6, v4
	v_lshlrev_b32_e32 v4, 2, v10
	v_and_b32_e32 v4, 32, v4
	v_bitop3_b32 v5, v2, s1, v4 bitop3:0xde
	v_bitop3_b32 v206, v2, s5, v4 bitop3:0xde
	v_cmp_eq_u32_e64 s[4:5], 0, v3
	v_lshl_or_b32 v207, v3, 2, s7
	v_lshrrev_b32_e32 v3, 1, v11
	v_mul_lo_u32 v2, v13, s6
	s_mov_b32 s1, 0xf000
	v_mad_u64_u32 v[2:3], s[8:9], v3, s1, v[2:3]
	v_or_b32_e32 v2, v2, v12
	v_add_lshl_u32 v2, v2, v14, 1
	v_mov_b32_e32 v3, v165
	s_mov_b64 s[8:9], 0xf0080
	v_lshl_add_u64 v[170:171], v[2:3], 0, s[8:9]
	v_lshrrev_b32_e32 v3, 1, v15
	v_mul_lo_u32 v2, v16, s6
	v_mad_u64_u32 v[2:3], s[6:7], v3, s1, v[2:3]
	v_or_b32_e32 v2, v2, v17
	s_waitcnt vmcnt(6)
	v_add_lshl_u32 v2, v2, v18, 1
	v_mov_b32_e32 v3, v165
	v_lshl_add_u64 v[172:173], v[2:3], 0, s[8:9]
	s_add_i32 s60, 0, 0x14000
	v_mbcnt_lo_u32_b32 v2, -1, 0
	s_mov_b32 s49, 0x8000
	s_ashr_i32 s50, s72, 31
	s_mov_b32 s51, s72
	s_ashr_i32 s58, s33, 31
	v_mov_b64_e32 v[174:175], 0x400
	v_mov_b64_e32 v[176:177], 0x3ff
	v_add_u32_e32 v208, s59, v206
	v_add_u32_e32 v209, 0, v5
	v_add_u32_e32 v210, s60, v206
	v_mbcnt_hi_u32_b32 v211, -1, v2
	s_movk_i32 s61, 0x3f80
	s_barrier
	s_branch .LBB0_687

.LBB0_696:
	ds_read_b128 v[82:85], v208
	ds_read_b128 v[86:89], v208 offset:1024
	ds_read_b128 v[94:97], v208 offset:2048
	ds_read_b128 v[102:105], v208 offset:3072
	s_add_u32 s8, s2, 0x100
	s_addc_u32 s9, s3, 0
	s_cmp_eq_u32 s68, 28
	s_cselect_b32 s31, s25, s9
	s_cselect_b32 s30, s24, s8
	s_cselect_b32 s29, s1, s63
	s_cselect_b32 s28, s23, s53
	v_lshl_add_u64 v[182:183], s[2:3], 0, v[170:171]
	s_add_i32 m0, s41, 0xc000
	ds_read_b128 v[146:149], v209
	ds_read_b128 v[150:153], v209 offset:1024
	ds_read_b128 v[154:157], v209 offset:2048
	ds_read_b128 v[158:161], v209 offset:3072
	ds_read_b128 v[178:181], v209 offset:4096
	ds_read_b128 v[186:189], v209 offset:5120
	ds_read_b128 v[190:193], v209 offset:6144
	ds_read_b128 v[194:197], v209 offset:7168
	global_load_lds_dwordx4 v[182:183], off
	v_lshl_add_u64 v[182:183], s[2:3], 0, v[172:173]
	s_add_i32 m0, s41, 0xe000
	s_nop 0
	global_load_lds_dwordx4 v[182:183], off
	ds_read_b128 v[198:201], v210
	ds_read_b128 v[202:205], v210 offset:1024
	ds_read_b128 v[212:215], v210 offset:2048
	ds_read_b128 v[216:219], v210 offset:3072
	s_waitcnt vmcnt(8)
	s_waitcnt lgkmcnt(0)
	s_barrier
	s_setprio 1
	v_mfma_f32_16x16x32_bf16 v[142:145], v[82:85], v[146:149], v[142:145]
	v_mfma_f32_16x16x32_bf16 v[138:141], v[94:97], v[146:149], v[138:141]
	v_mfma_f32_16x16x32_bf16 v[126:129], v[82:85], v[154:157], v[126:129]
	v_mfma_f32_16x16x32_bf16 v[122:125], v[94:97], v[154:157], v[122:125]
	v_mfma_f32_16x16x32_bf16 v[110:113], v[82:85], v[178:181], v[110:113]
	v_mfma_f32_16x16x32_bf16 v[106:109], v[94:97], v[178:181], v[106:109]
	v_mfma_f32_16x16x32_bf16 v[78:81], v[82:85], v[190:193], v[78:81]
	v_mfma_f32_16x16x32_bf16 v[74:77], v[94:97], v[190:193], v[74:77]
	v_mfma_f32_16x16x32_bf16 v[142:145], v[86:89], v[150:153], v[142:145]
	v_mfma_f32_16x16x32_bf16 v[138:141], v[102:105], v[150:153], v[138:141]
	v_mfma_f32_16x16x32_bf16 v[126:129], v[86:89], v[158:161], v[126:129]
	v_mfma_f32_16x16x32_bf16 v[122:125], v[102:105], v[158:161], v[122:125]
	v_mfma_f32_16x16x32_bf16 v[110:113], v[86:89], v[186:189], v[110:113]
	v_mfma_f32_16x16x32_bf16 v[106:109], v[102:105], v[186:189], v[106:109]
	v_mfma_f32_16x16x32_bf16 v[78:81], v[86:89], v[194:197], v[78:81]
	v_mfma_f32_16x16x32_bf16 v[74:77], v[102:105], v[194:197], v[74:77]
	v_mfma_f32_16x16x32_bf16 v[134:137], v[198:201], v[146:149], v[134:137]
	v_mfma_f32_16x16x32_bf16 v[130:133], v[212:215], v[146:149], v[130:133]
	v_mfma_f32_16x16x32_bf16 v[118:121], v[198:201], v[154:157], v[118:121]
	v_mfma_f32_16x16x32_bf16 v[114:117], v[212:215], v[154:157], v[114:117]
	v_mfma_f32_16x16x32_bf16 v[98:101], v[198:201], v[178:181], v[98:101]
	v_mfma_f32_16x16x32_bf16 v[90:93], v[212:215], v[178:181], v[90:93]
	v_mfma_f32_16x16x32_bf16 v[70:73], v[198:201], v[190:193], v[70:73]
	v_mfma_f32_16x16x32_bf16 v[66:69], v[212:215], v[190:193], v[66:69]
	v_mfma_f32_16x16x32_bf16 v[134:137], v[202:205], v[150:153], v[134:137]
	v_mfma_f32_16x16x32_bf16 v[130:133], v[216:219], v[150:153], v[130:133]
	v_mfma_f32_16x16x32_bf16 v[118:121], v[202:205], v[158:161], v[118:121]
	v_mfma_f32_16x16x32_bf16 v[114:117], v[216:219], v[158:161], v[114:117]
	v_mfma_f32_16x16x32_bf16 v[98:101], v[202:205], v[186:189], v[98:101]
	v_mfma_f32_16x16x32_bf16 v[90:93], v[216:219], v[186:189], v[90:93]
	v_mfma_f32_16x16x32_bf16 v[70:73], v[202:205], v[194:197], v[70:73]
	v_mfma_f32_16x16x32_bf16 v[66:69], v[216:219], v[194:197], v[66:69]
	s_setprio 0
	s_barrier
	s_add_i32 s2, s59, s37
	v_lshl_add_u64 v[182:183], s[28:29], 0, v[164:165]
	s_mov_b32 m0, s2
	global_load_lds_dwordx4 v[182:183], off
	v_lshl_add_u64 v[220:221], s[28:29], 0, v[168:169]
	s_add_i32 m0, s2, 0x2000
	s_nop 0
	global_load_lds_dwordx4 v[220:221], off
	s_mov_b32 m0, s41
	v_lshl_add_u64 v[222:223], s[30:31], 0, v[162:163]
	ds_read_b128 v[146:149], v209 offset:16384
	ds_read_b128 v[150:153], v209 offset:17408
	ds_read_b128 v[154:157], v209 offset:18432
	ds_read_b128 v[158:161], v209 offset:19456
	ds_read_b128 v[178:181], v209 offset:20480
	ds_read_b128 v[186:189], v209 offset:21504
	ds_read_b128 v[190:193], v209 offset:22528
	ds_read_b128 v[194:197], v209 offset:23552
	global_load_lds_dwordx4 v[222:223], off
	v_lshl_add_u64 v[224:225], s[30:31], 0, v[166:167]
	s_mov_b32 m0, s42
	s_nop 0
	global_load_lds_dwordx4 v[224:225], off
	s_waitcnt vmcnt(6)
	s_waitcnt lgkmcnt(0)
	s_barrier
	s_setprio 1
	v_mfma_f32_16x16x32_bf16 v[62:65], v[82:85], v[146:149], v[62:65]
	v_mfma_f32_16x16x32_bf16 v[58:61], v[94:97], v[146:149], v[58:61]
	v_mfma_f32_16x16x32_bf16 v[46:49], v[82:85], v[154:157], v[46:49]
	v_mfma_f32_16x16x32_bf16 v[42:45], v[94:97], v[154:157], v[42:45]
	v_mfma_f32_16x16x32_bf16 v[30:33], v[82:85], v[178:181], v[30:33]
	v_mfma_f32_16x16x32_bf16 v[26:29], v[94:97], v[178:181], v[26:29]
	v_mfma_f32_16x16x32_bf16 v[14:17], v[82:85], v[190:193], v[14:17]
	v_mfma_f32_16x16x32_bf16 v[10:13], v[94:97], v[190:193], v[10:13]
	v_mfma_f32_16x16x32_bf16 v[62:65], v[86:89], v[150:153], v[62:65]
	v_mfma_f32_16x16x32_bf16 v[58:61], v[102:105], v[150:153], v[58:61]
	v_mfma_f32_16x16x32_bf16 v[46:49], v[86:89], v[158:161], v[46:49]
	v_mfma_f32_16x16x32_bf16 v[42:45], v[102:105], v[158:161], v[42:45]
	v_mfma_f32_16x16x32_bf16 v[30:33], v[86:89], v[186:189], v[30:33]
	v_mfma_f32_16x16x32_bf16 v[26:29], v[102:105], v[186:189], v[26:29]
	v_mfma_f32_16x16x32_bf16 v[14:17], v[86:89], v[194:197], v[14:17]
	v_mfma_f32_16x16x32_bf16 v[10:13], v[102:105], v[194:197], v[10:13]
	v_mfma_f32_16x16x32_bf16 v[54:57], v[198:201], v[146:149], v[54:57]
	v_mfma_f32_16x16x32_bf16 v[50:53], v[212:215], v[146:149], v[50:53]
	v_mfma_f32_16x16x32_bf16 v[38:41], v[198:201], v[154:157], v[38:41]
	v_mfma_f32_16x16x32_bf16 v[34:37], v[212:215], v[154:157], v[34:37]
	v_mfma_f32_16x16x32_bf16 v[22:25], v[198:201], v[178:181], v[22:25]
	v_mfma_f32_16x16x32_bf16 v[18:21], v[212:215], v[178:181], v[18:21]
	v_mfma_f32_16x16x32_bf16 v[6:9], v[198:201], v[190:193], v[6:9]
	v_mfma_f32_16x16x32_bf16 v[2:5], v[212:215], v[190:193], v[2:5]
	v_mfma_f32_16x16x32_bf16 v[54:57], v[202:205], v[150:153], v[54:57]
	v_mfma_f32_16x16x32_bf16 v[50:53], v[216:219], v[150:153], v[50:53]
	v_mfma_f32_16x16x32_bf16 v[38:41], v[202:205], v[158:161], v[38:41]
	v_mfma_f32_16x16x32_bf16 v[34:37], v[216:219], v[158:161], v[34:37]
	v_mfma_f32_16x16x32_bf16 v[22:25], v[202:205], v[186:189], v[22:25]
	v_mfma_f32_16x16x32_bf16 v[18:21], v[216:219], v[186:189], v[18:21]
	v_mfma_f32_16x16x32_bf16 v[6:9], v[202:205], v[194:197], v[6:9]
	v_mfma_f32_16x16x32_bf16 v[2:5], v[216:219], v[194:197], v[2:5]
	s_setprio 0
	s_barrier
	s_add_u32 s2, s28, 0x80000
	s_addc_u32 s3, s29, 0
	s_add_i32 s69, s60, s37
	v_lshl_add_u64 v[82:83], s[2:3], 0, v[164:165]
	s_mov_b32 m0, s69
	s_nop 0
	global_load_lds_dwordx4 v[82:83], off
	v_lshl_add_u64 v[82:83], s[2:3], 0, v[168:169]
	s_add_i32 m0, s69, 0x2000
	s_nop 0
	global_load_lds_dwordx4 v[82:83], off
	s_add_i32 s69, 0, 0x18000
	v_add_u32_e32 v102, s69, v206
	ds_read_b128 v[82:85], v102
	ds_read_b128 v[86:89], v102 offset:1024
	ds_read_b128 v[94:97], v102 offset:2048
	ds_read_b128 v[102:105], v102 offset:3072
	s_add_u32 s2, s30, 0xf0000
	s_addc_u32 s3, s31, 0
	s_mov_b32 m0, s43
	v_lshl_add_u64 v[198:199], s[2:3], 0, v[162:163]
	ds_read_b128 v[146:149], v209 offset:32768
	ds_read_b128 v[150:153], v209 offset:33792
	ds_read_b128 v[154:157], v209 offset:34816
	ds_read_b128 v[158:161], v209 offset:35840
	ds_read_b128 v[178:181], v209 offset:36864
	ds_read_b128 v[186:189], v209 offset:37888
	ds_read_b128 v[190:193], v209 offset:38912
	ds_read_b128 v[194:197], v209 offset:39936
	global_load_lds_dwordx4 v[198:199], off
	v_lshl_add_u64 v[198:199], s[2:3], 0, v[166:167]
	s_mov_b32 m0, s44
	s_nop 0
	global_load_lds_dwordx4 v[198:199], off
	v_add_u32_e32 v216, 0x1c000, v206
	ds_read_b128 v[198:201], v216
	ds_read_b128 v[202:205], v216 offset:1024
	ds_read_b128 v[212:215], v216 offset:2048
	ds_read_b128 v[216:219], v216 offset:3072
	s_waitcnt vmcnt(8)
	s_waitcnt lgkmcnt(0)
	s_barrier
	s_setprio 1
	v_mfma_f32_16x16x32_bf16 v[142:145], v[82:85], v[146:149], v[142:145]
	v_mfma_f32_16x16x32_bf16 v[138:141], v[94:97], v[146:149], v[138:141]
	v_mfma_f32_16x16x32_bf16 v[126:129], v[82:85], v[154:157], v[126:129]
	v_mfma_f32_16x16x32_bf16 v[122:125], v[94:97], v[154:157], v[122:125]
	v_mfma_f32_16x16x32_bf16 v[110:113], v[82:85], v[178:181], v[110:113]
	v_mfma_f32_16x16x32_bf16 v[106:109], v[94:97], v[178:181], v[106:109]
	v_mfma_f32_16x16x32_bf16 v[78:81], v[82:85], v[190:193], v[78:81]
	v_mfma_f32_16x16x32_bf16 v[74:77], v[94:97], v[190:193], v[74:77]
	v_mfma_f32_16x16x32_bf16 v[142:145], v[86:89], v[150:153], v[142:145]
	v_mfma_f32_16x16x32_bf16 v[138:141], v[102:105], v[150:153], v[138:141]
	v_mfma_f32_16x16x32_bf16 v[126:129], v[86:89], v[158:161], v[126:129]
	v_mfma_f32_16x16x32_bf16 v[122:125], v[102:105], v[158:161], v[122:125]
	v_mfma_f32_16x16x32_bf16 v[110:113], v[86:89], v[186:189], v[110:113]
	v_mfma_f32_16x16x32_bf16 v[106:109], v[102:105], v[186:189], v[106:109]
	v_mfma_f32_16x16x32_bf16 v[78:81], v[86:89], v[194:197], v[78:81]
	v_mfma_f32_16x16x32_bf16 v[74:77], v[102:105], v[194:197], v[74:77]
	v_mfma_f32_16x16x32_bf16 v[134:137], v[198:201], v[146:149], v[134:137]
	v_mfma_f32_16x16x32_bf16 v[130:133], v[212:215], v[146:149], v[130:133]
	v_mfma_f32_16x16x32_bf16 v[118:121], v[198:201], v[154:157], v[118:121]
	v_mfma_f32_16x16x32_bf16 v[114:117], v[212:215], v[154:157], v[114:117]
	v_mfma_f32_16x16x32_bf16 v[98:101], v[198:201], v[178:181], v[98:101]
	v_mfma_f32_16x16x32_bf16 v[90:93], v[212:215], v[178:181], v[90:93]
	v_mfma_f32_16x16x32_bf16 v[70:73], v[198:201], v[190:193], v[70:73]
	v_mfma_f32_16x16x32_bf16 v[66:69], v[212:215], v[190:193], v[66:69]
	v_mfma_f32_16x16x32_bf16 v[134:137], v[202:205], v[150:153], v[134:137]
	v_mfma_f32_16x16x32_bf16 v[130:133], v[216:219], v[150:153], v[130:133]
	v_mfma_f32_16x16x32_bf16 v[118:121], v[202:205], v[158:161], v[118:121]
	v_mfma_f32_16x16x32_bf16 v[114:117], v[216:219], v[158:161], v[114:117]
	v_mfma_f32_16x16x32_bf16 v[98:101], v[202:205], v[186:189], v[98:101]
	v_mfma_f32_16x16x32_bf16 v[90:93], v[216:219], v[186:189], v[90:93]
	v_mfma_f32_16x16x32_bf16 v[70:73], v[202:205], v[194:197], v[70:73]
	v_mfma_f32_16x16x32_bf16 v[66:69], v[216:219], v[194:197], v[66:69]
	s_setprio 0
	s_barrier
	s_add_i32 s30, 0, 0x1c000
	s_add_i32 s2, s69, s37
	v_lshl_add_u64 v[182:183], v[182:183], 0, s[20:21]
	s_mov_b32 m0, s2
	global_load_lds_dwordx4 v[182:183], off
	v_lshl_add_u64 v[182:183], v[220:221], 0, s[20:21]
	s_add_i32 m0, s2, 0x2000
	s_nop 0
	global_load_lds_dwordx4 v[182:183], off
	s_mov_b32 m0, s47
	v_lshl_add_u64 v[182:183], v[222:223], 0, s[20:21]
	ds_read_b128 v[146:149], v209 offset:49152
	ds_read_b128 v[150:153], v209 offset:50176
	ds_read_b128 v[154:157], v209 offset:51200
	ds_read_b128 v[158:161], v209 offset:52224
	ds_read_b128 v[178:181], v209 offset:53248
	ds_read_b128 v[186:189], v209 offset:54272
	ds_read_b128 v[190:193], v209 offset:55296
	ds_read_b128 v[194:197], v209 offset:56320
	global_load_lds_dwordx4 v[182:183], off
	v_lshl_add_u64 v[182:183], v[224:225], 0, s[20:21]
	s_mov_b32 m0, s48
	s_nop 0
	global_load_lds_dwordx4 v[182:183], off
	s_add_u32 s2, s28, 0x80080
	s_addc_u32 s3, s29, 0
	s_add_i32 s28, s30, s37
	v_lshl_add_u64 v[182:183], s[2:3], 0, v[164:165]
	s_mov_b32 m0, s28
	s_nop 0
	global_load_lds_dwordx4 v[182:183], off
	v_lshl_add_u64 v[182:183], s[2:3], 0, v[168:169]
	s_add_i32 m0, s28, 0x2000
	s_nop 0
	global_load_lds_dwordx4 v[182:183], off
	s_waitcnt vmcnt(8)
	s_waitcnt lgkmcnt(0)
	s_barrier
	s_setprio 1
	v_mfma_f32_16x16x32_bf16 v[62:65], v[82:85], v[146:149], v[62:65]
	v_mfma_f32_16x16x32_bf16 v[58:61], v[94:97], v[146:149], v[58:61]
	v_mfma_f32_16x16x32_bf16 v[46:49], v[82:85], v[154:157], v[46:49]
	v_mfma_f32_16x16x32_bf16 v[42:45], v[94:97], v[154:157], v[42:45]
	v_mfma_f32_16x16x32_bf16 v[30:33], v[82:85], v[178:181], v[30:33]
	v_mfma_f32_16x16x32_bf16 v[26:29], v[94:97], v[178:181], v[26:29]
	v_mfma_f32_16x16x32_bf16 v[14:17], v[82:85], v[190:193], v[14:17]
	v_mfma_f32_16x16x32_bf16 v[10:13], v[94:97], v[190:193], v[10:13]
	v_mfma_f32_16x16x32_bf16 v[62:65], v[86:89], v[150:153], v[62:65]
	v_mfma_f32_16x16x32_bf16 v[58:61], v[102:105], v[150:153], v[58:61]
	v_mfma_f32_16x16x32_bf16 v[46:49], v[86:89], v[158:161], v[46:49]
	v_mfma_f32_16x16x32_bf16 v[42:45], v[102:105], v[158:161], v[42:45]
	v_mfma_f32_16x16x32_bf16 v[30:33], v[86:89], v[186:189], v[30:33]
	v_mfma_f32_16x16x32_bf16 v[26:29], v[102:105], v[186:189], v[26:29]
	v_mfma_f32_16x16x32_bf16 v[14:17], v[86:89], v[194:197], v[14:17]
	v_mfma_f32_16x16x32_bf16 v[10:13], v[102:105], v[194:197], v[10:13]
	v_mfma_f32_16x16x32_bf16 v[54:57], v[198:201], v[146:149], v[54:57]
	v_mfma_f32_16x16x32_bf16 v[50:53], v[212:215], v[146:149], v[50:53]
	v_mfma_f32_16x16x32_bf16 v[38:41], v[198:201], v[154:157], v[38:41]
	v_mfma_f32_16x16x32_bf16 v[34:37], v[212:215], v[154:157], v[34:37]
	v_mfma_f32_16x16x32_bf16 v[22:25], v[198:201], v[178:181], v[22:25]
	v_mfma_f32_16x16x32_bf16 v[18:21], v[212:215], v[178:181], v[18:21]
	v_mfma_f32_16x16x32_bf16 v[6:9], v[198:201], v[190:193], v[6:9]
	v_mfma_f32_16x16x32_bf16 v[2:5], v[212:215], v[190:193], v[2:5]
	v_mfma_f32_16x16x32_bf16 v[54:57], v[202:205], v[150:153], v[54:57]
	v_mfma_f32_16x16x32_bf16 v[50:53], v[216:219], v[150:153], v[50:53]
	v_mfma_f32_16x16x32_bf16 v[38:41], v[202:205], v[158:161], v[38:41]
	v_mfma_f32_16x16x32_bf16 v[34:37], v[216:219], v[158:161], v[34:37]
	v_mfma_f32_16x16x32_bf16 v[22:25], v[202:205], v[186:189], v[22:25]
	v_mfma_f32_16x16x32_bf16 v[18:21], v[216:219], v[186:189], v[18:21]
	v_mfma_f32_16x16x32_bf16 v[6:9], v[202:205], v[194:197], v[6:9]
	v_mfma_f32_16x16x32_bf16 v[2:5], v[216:219], v[194:197], v[2:5]
	s_setprio 0
	s_add_i32 s68, s68, 2
	s_add_u32 s53, s53, 0x100
	s_addc_u32 s63, s63, 0
	s_cmp_gt_u32 s68, 29
	s_mov_b64 s[2:3], s[8:9]
	s_barrier
	s_cbranch_scc0 .LBB0_696
	s_min_i32 s1, s52, 64
	s_ashr_i32 s1, s1, 3
	v_lshl_or_b32 v178, s0, 8, v207
	s_mul_hi_i32 s2, s1, 0xc000
	s_mul_i32 s1, s1, 0xc000
	s_add_u32 s0, s10, s1
	v_ashrrev_i32_e32 v179, 31, v178
	s_addc_u32 s1, s11, s2
	v_lshlrev_b64 v[198:199], 2, v[178:179]
	v_lshl_add_u32 v200, s52, 8, v1
	v_lshl_add_u64 v[82:83], s[0:1], 0, v[198:199]
	v_add_u32_e32 v94, 0xffffc000, v200
	v_ashrrev_i32_e32 v201, 31, v200
	v_cmp_gt_i32_e64 s[0:1], s46, v200
	v_add_co_u32_e32 v84, vcc, s46, v82
	s_nop 0
	v_cndmask_b32_e64 v95, 0, v201, s[0:1]
	v_cndmask_b32_e64 v94, v94, v200, s[0:1]
	v_mov_b32_e32 v152, s15
	v_mov_b32_e32 v153, s13
	v_mov_b32_e32 v154, s14
	v_mov_b32_e32 v155, s12
	v_addc_co_u32_e32 v85, vcc, 0, v83, vcc
	v_cndmask_b32_e64 v97, v152, v153, s[0:1]
	v_cndmask_b32_e64 v96, v154, v155, s[0:1]
	v_lshlrev_b64 v[94:95], 13, v[94:95]
	v_add_co_u32_e32 v82, vcc, s49, v82
	v_lshl_add_u64 v[94:95], v[96:97], 0, v[94:95]
	v_lshl_add_u64 v[146:147], v[94:95], 0, v[198:199]
	v_addc_co_u32_e32 v83, vcc, 0, v83, vcc
	global_load_dwordx4 v[86:89], v[84:85], off
	global_load_dwordx4 v[180:183], v[146:147], off
	global_load_dwordx4 v[186:189], v[82:83], off
	global_load_dwordx4 v[190:193], v[82:83], off offset:64
	global_load_dwordx4 v[194:197], v[82:83], off offset:512
	global_load_dwordx4 v[212:215], v[82:83], off offset:576
	v_lshl_add_u64 v[82:83], s[56:57], 0, v[198:199]
	global_load_dwordx4 v[216:219], v[82:83], off
	global_load_dwordx4 v[220:223], v[82:83], off offset:64
	global_load_dwordx4 v[224:227], v[82:83], off offset:512
	global_load_dwordx4 v[228:231], v[82:83], off offset:576
	global_load_dwordx4 v[232:235], v[146:147], off offset:64
	global_load_dwordx4 v[102:105], v[84:85], off offset:64
	global_load_dwordx4 v[94:97], v[84:85], off offset:512
	global_load_dwordx4 v[236:239], v[146:147], off offset:512
	global_load_dwordx4 v[240:243], v[146:147], off offset:576
	s_nop 0
	global_load_dwordx4 v[82:85], v[84:85], off offset:576
	v_or_b32_e32 v202, 16, v200
	v_add_u32_e32 v150, 0xffffc010, v200
	v_ashrrev_i32_e32 v203, 31, v202
	v_cmp_gt_i32_e32 vcc, s46, v202
	v_lshlrev_b64 v[146:147], 13, v[200:201]
	v_lshl_add_u64 v[146:147], s[66:67], 0, v[146:147]
	v_cndmask_b32_e32 v151, 0, v203, vcc
	v_cndmask_b32_e32 v150, v150, v202, vcc
	v_cndmask_b32_e32 v153, v152, v153, vcc
	v_cndmask_b32_e32 v152, v154, v155, vcc
	v_lshlrev_b64 v[150:151], 13, v[150:151]
	v_lshlrev_b64 v[148:149], 12, v[200:201]
	v_lshl_add_u64 v[204:205], v[146:147], 0, v[198:199]
	v_lshl_add_u64 v[146:147], v[152:153], 0, v[150:151]
	v_lshl_add_u64 v[148:149], s[88:89], 0, v[148:149]
	v_lshl_add_u64 v[146:147], v[146:147], 0, v[198:199]
	v_lshl_add_u64 v[244:245], v[178:179], 1, v[148:149]
	global_load_dwordx4 v[158:161], v[146:147], off
	global_load_dwordx4 v[154:157], v[146:147], off offset:64
	global_load_dwordx4 v[150:153], v[146:147], off offset:512
	s_nop 0
	global_load_dwordx4 v[146:149], v[146:147], off offset:576
	s_waitcnt vmcnt(0)
	v_pk_fma_f32 v[138:139], v[138:139], v[102:103], v[232:233]
	v_pk_fma_f32 v[144:145], v[144:145], v[88:89], v[182:183]
	v_pk_fma_f32 v[142:143], v[142:143], v[86:87], v[180:181]
	v_pk_add_f32 v[180:181], v[188:189], 1.0 op_sel_hi:[1,0]
	v_pk_add_f32 v[182:183], v[186:187], 1.0 op_sel_hi:[1,0]
	v_pk_add_f32 v[212:213], v[212:213], 1.0 op_sel_hi:[1,0]
	v_pk_add_f32 v[246:247], v[196:197], 1.0 op_sel_hi:[1,0]
	v_pk_add_f32 v[248:249], v[194:195], 1.0 op_sel_hi:[1,0]
	v_pk_mul_f32 v[194:195], v[218:219], v[180:181]
	v_pk_mul_f32 v[196:197], v[216:217], v[182:183]
	v_pk_mul_f32 v[180:181], v[228:229], v[212:213]
	v_mul_f32_e32 v212, v143, v143
	global_store_dwordx4 v[204:205], v[142:145], off
	v_fmac_f32_e32 v212, v142, v142
	v_pk_add_f32 v[188:189], v[190:191], 1.0 op_sel_hi:[1,0]
	v_pk_mul_f32 v[142:143], v[196:197], v[142:143]
	v_fmac_f32_e32 v212, v144, v144
	v_cvt_pk_bf16_f32 v142, v142, v143
	v_pk_add_f32 v[186:187], v[192:193], 1.0 op_sel_hi:[1,0]
	v_pk_mul_f32 v[192:193], v[220:221], v[188:189]
	v_fmac_f32_e32 v212, v145, v145
	v_pk_mul_f32 v[144:145], v[194:195], v[144:145]
	v_pk_fma_f32 v[140:141], v[140:141], v[104:105], v[234:235]
	v_cvt_pk_bf16_f32 v143, v144, v145
	global_store_dwordx2 v[244:245], v[142:143], off
	v_mul_f32_e32 v142, v139, v139
	global_store_dwordx4 v[204:205], v[138:141], off offset:64
	v_fmac_f32_e32 v142, v138, v138
	v_pk_mul_f32 v[190:191], v[222:223], v[186:187]
	v_pk_mul_f32 v[138:139], v[192:193], v[138:139]
	v_fmac_f32_e32 v142, v140, v140
	v_cvt_pk_bf16_f32 v138, v138, v139
	v_pk_fma_f32 v[134:135], v[134:135], v[94:95], v[236:237]
	v_fmac_f32_e32 v142, v141, v141
	v_pk_mul_f32 v[140:141], v[190:191], v[140:141]
	v_pk_fma_f32 v[136:137], v[136:137], v[96:97], v[238:239]
	v_cvt_pk_bf16_f32 v139, v140, v141
	global_store_dwordx2 v[244:245], v[138:139], off offset:32
	v_mul_f32_e32 v138, v135, v135
	v_fmac_f32_e32 v138, v134, v134
	v_pk_mul_f32 v[188:189], v[224:225], v[248:249]
	v_fmac_f32_e32 v138, v136, v136
	v_add_f32_e32 v142, v212, v142
	global_store_dwordx4 v[204:205], v[134:137], off offset:512
	v_fmac_f32_e32 v138, v137, v137
	v_add_f32_e32 v139, v142, v138
	v_pk_mul_f32 v[134:135], v[188:189], v[134:135]
	v_pk_mul_f32 v[186:187], v[226:227], v[246:247]
	v_cvt_pk_bf16_f32 v138, v134, v135
	v_pk_fma_f32 v[134:135], v[132:133], v[84:85], v[242:243]
	v_pk_fma_f32 v[132:133], v[130:131], v[82:83], v[240:241]
	v_xor_b32_e32 v131, 16, v211
	v_mul_f32_e32 v130, v133, v133
	v_fmac_f32_e32 v130, v132, v132
	v_fmac_f32_e32 v130, v134, v134
	v_fmac_f32_e32 v130, v135, v135
	v_add_f32_e32 v130, v139, v130
	v_and_b32_e32 v139, 64, v211
	v_add_u32_e32 v140, 64, v139
	v_cmp_lt_i32_e32 vcc, v131, v140
	v_pk_add_f32 v[214:215], v[214:215], 1.0 op_sel_hi:[1,0]
	v_pk_mul_f32 v[136:137], v[186:187], v[136:137]
	v_cndmask_b32_e32 v131, v211, v131, vcc
	v_lshlrev_b32_e32 v212, 2, v131
	ds_bpermute_b32 v131, v212, v130
	v_cvt_pk_bf16_f32 v139, v136, v137
	v_pk_mul_f32 v[182:183], v[230:231], v[214:215]
	global_store_dwordx2 v[244:245], v[138:139], off offset:256
	global_store_dwordx4 v[204:205], v[132:135], off offset:576
	s_waitcnt lgkmcnt(0)
	v_add_f32_e32 v130, v130, v131
	v_xor_b32_e32 v131, 32, v211
	v_cmp_lt_i32_e32 vcc, v131, v140
	v_pk_mul_f32 v[132:133], v[180:181], v[132:133]
	v_pk_mul_f32 v[134:135], v[182:183], v[134:135]
	v_cndmask_b32_e32 v131, v211, v131, vcc
	v_lshlrev_b32_e32 v213, 2, v131
	ds_bpermute_b32 v131, v213, v130
	v_cvt_pk_bf16_f32 v132, v132, v133
	v_cvt_pk_bf16_f32 v133, v134, v135
	global_store_dwordx2 v[244:245], v[132:133], off offset:288
	s_and_saveexec_b64 s[0:1], s[4:5]
	s_cbranch_execz .LBB0_699
	v_lshl_add_u64 v[132:133], v[200:201], 2, s[18:19]
	s_waitcnt lgkmcnt(0)
	v_add_f32_e32 v130, v130, v131
	global_atomic_add_f32 v[132:133], v130, off

.LBB0_795:
	v_lshrrev_b32_e32 v16, 1, v6
	v_and_b32_e32 v16, 24, v16
	v_readlane_b32 s20, v252, 16
	v_and_b32_e32 v7, 15, v6
	v_lshlrev_b32_e32 v17, 1, v16
	v_lshlrev_b32_e32 v6, 2, v6
	s_lshl_b32 s2, s2, 5
	v_readlane_b32 s21, v252, 17
	v_lshl_or_b32 v160, s3, 6, v7
	v_lshl_or_b32 v7, v7, 6, v17
	s_lshl_b32 s3, s3, 13
	v_and_b32_e32 v6, 32, v6
	s_and_b32 s2, s2, 0x60
	v_lshl_add_u64 v[8:9], s[20:21], 0, v[186:187]
	v_mov_b32_e32 v145, v187
	v_bitop3_b32 v17, v7, s3, v6 bitop3:0xde
	s_lshl_b32 s3, s2, 7
	v_lshl_add_u64 v[10:11], s[20:21], 0, v[144:145]
	v_mov_b32_e32 v149, v187
	v_bitop3_b32 v161, v7, s3, v6 bitop3:0xde
	s_add_i32 m0, s16, 0x18000
	v_lshl_add_u64 v[6:7], v[8:9], 0, s[0:1]
	v_lshl_add_u64 v[12:13], s[12:13], 0, v[148:149]
	v_mov_b32_e32 v147, v187
	s_waitcnt vmcnt(2)
	s_barrier
	global_load_lds_dwordx4 v[6:7], off
	v_lshl_add_u64 v[6:7], v[10:11], 0, s[0:1]
	s_add_i32 m0, s16, 0x1a000
	s_add_i32 s38, s16, 0x8000
	v_lshl_add_u64 v[14:15], s[12:13], 0, v[146:147]
	global_load_lds_dwordx4 v[6:7], off
	v_lshl_add_u64 v[6:7], v[12:13], 0, s[0:1]
	s_mov_b32 m0, s38
	s_add_i32 s39, s16, 0xa000
	v_readlane_b32 s14, v252, 18
	global_load_lds_dwordx4 v[6:7], off
	v_lshl_add_u64 v[6:7], v[14:15], 0, s[0:1]
	s_mov_b32 m0, s39
	v_readlane_b32 s15, v252, 19
	global_load_lds_dwordx4 v[6:7], off
	s_add_i32 m0, s16, 0x1c000
	v_lshl_add_u64 v[6:7], s[14:15], 0, v[186:187]
	global_load_lds_dwordx4 v[6:7], off
	v_lshl_add_u64 v[6:7], s[14:15], 0, v[144:145]
	s_add_i32 m0, s16, 0x1e000
	v_or_b32_e32 v162, s2, v16
	global_load_lds_dwordx4 v[6:7], off
	v_lshlrev_b32_e32 v6, 15, v4
	v_and_b32_e32 v6, 0xffff0000, v6
	v_lshl_add_u32 v3, v3, 12, v6
	v_and_b32_e32 v4, 1, v4
	v_lshl_or_b32 v3, v4, 6, v3
	v_lshl_add_u32 v150, v5, 1, v3
	v_lshlrev_b32_e32 v3, 15, v0
	v_and_b32_e32 v3, 0xffff0000, v3
	s_waitcnt vmcnt(6)
	v_lshl_add_u32 v1, v1, 12, v3
	v_and_b32_e32 v0, 1, v0
	v_lshl_or_b32 v0, v0, 6, v1
	v_readlane_b32 s2, v252, 10
	s_lshl_b32 s35, s47, 13
	v_mov_b32_e32 v151, v187
	v_lshl_add_u32 v152, v2, 1, v0
	v_mov_b32_e32 v153, v187
	s_mov_b32 s40, 0
	v_add_u32_e32 v163, 0, v17
	v_readlane_b32 s41, v252, 9
	s_mov_b32 s44, s2
	s_barrier
	v_readlane_b32 s3, v252, 11

.LBB0_803:
	s_add_u32 s4, s12, 0xfff80080
	s_addc_u32 s20, s13, -1
	s_add_i32 s58, 0, 0x10000
	v_add_u32_e32 v140, s58, v161
	ds_read_b128 v[128:131], v140
	ds_read_b128 v[132:135], v140 offset:1024
	ds_read_b128 v[136:139], v140 offset:2048
	ds_read_b128 v[140:143], v140 offset:3072
	s_cmp_eq_u32 s57, 28
	s_cselect_b32 s25, s15, s20
	s_cselect_b32 s24, s45, s4
	s_cselect_b32 s21, s3, s56
	s_cselect_b32 s20, s52, s53
	v_lshl_add_u64 v[158:159], s[12:13], 0, v[150:151]
	s_add_i32 m0, s16, 0xc000
	ds_read_b128 v[154:157], v163
	ds_read_b128 v[164:167], v163 offset:1024
	ds_read_b128 v[168:171], v163 offset:2048
	ds_read_b128 v[172:175], v163 offset:3072
	ds_read_b128 v[176:179], v163 offset:4096
	ds_read_b128 v[180:183], v163 offset:5120
	ds_read_b128 v[196:199], v163 offset:6144
	ds_read_b128 v[200:203], v163 offset:7168
	global_load_lds_dwordx4 v[158:159], off
	v_lshl_add_u64 v[158:159], s[12:13], 0, v[152:153]
	s_add_i32 m0, s16, 0xe000
	s_nop 0
	global_load_lds_dwordx4 v[158:159], off
	v_add_u32_e32 v216, 0x14000, v161
	ds_read_b128 v[204:207], v216
	ds_read_b128 v[208:211], v216 offset:1024
	ds_read_b128 v[212:215], v216 offset:2048
	ds_read_b128 v[216:219], v216 offset:3072
	s_waitcnt vmcnt(8)
	s_waitcnt lgkmcnt(0)
	s_barrier
	s_setprio 1
	v_mfma_f32_16x16x32_bf16 v[124:127], v[128:131], v[154:157], v[124:127]
	v_mfma_f32_16x16x32_bf16 v[120:123], v[136:139], v[154:157], v[120:123]
	v_mfma_f32_16x16x32_bf16 v[108:111], v[128:131], v[168:171], v[108:111]
	v_mfma_f32_16x16x32_bf16 v[104:107], v[136:139], v[168:171], v[104:107]
	v_mfma_f32_16x16x32_bf16 v[92:95], v[128:131], v[176:179], v[92:95]
	v_mfma_f32_16x16x32_bf16 v[88:91], v[136:139], v[176:179], v[88:91]
	v_mfma_f32_16x16x32_bf16 v[76:79], v[128:131], v[196:199], v[76:79]
	v_mfma_f32_16x16x32_bf16 v[72:75], v[136:139], v[196:199], v[72:75]
	v_mfma_f32_16x16x32_bf16 v[124:127], v[132:135], v[164:167], v[124:127]
	v_mfma_f32_16x16x32_bf16 v[120:123], v[140:143], v[164:167], v[120:123]
	v_mfma_f32_16x16x32_bf16 v[108:111], v[132:135], v[172:175], v[108:111]
	v_mfma_f32_16x16x32_bf16 v[104:107], v[140:143], v[172:175], v[104:107]
	v_mfma_f32_16x16x32_bf16 v[92:95], v[132:135], v[180:183], v[92:95]
	v_mfma_f32_16x16x32_bf16 v[88:91], v[140:143], v[180:183], v[88:91]
	v_mfma_f32_16x16x32_bf16 v[76:79], v[132:135], v[200:203], v[76:79]
	v_mfma_f32_16x16x32_bf16 v[72:75], v[140:143], v[200:203], v[72:75]
	v_mfma_f32_16x16x32_bf16 v[116:119], v[204:207], v[154:157], v[116:119]
	v_mfma_f32_16x16x32_bf16 v[112:115], v[212:215], v[154:157], v[112:115]
	v_mfma_f32_16x16x32_bf16 v[100:103], v[204:207], v[168:171], v[100:103]
	v_mfma_f32_16x16x32_bf16 v[96:99], v[212:215], v[168:171], v[96:99]
	v_mfma_f32_16x16x32_bf16 v[84:87], v[204:207], v[176:179], v[84:87]
	v_mfma_f32_16x16x32_bf16 v[80:83], v[212:215], v[176:179], v[80:83]
	v_mfma_f32_16x16x32_bf16 v[68:71], v[204:207], v[196:199], v[68:71]
	v_mfma_f32_16x16x32_bf16 v[64:67], v[212:215], v[196:199], v[64:67]
	v_mfma_f32_16x16x32_bf16 v[116:119], v[208:211], v[164:167], v[116:119]
	v_mfma_f32_16x16x32_bf16 v[112:115], v[216:219], v[164:167], v[112:115]
	v_mfma_f32_16x16x32_bf16 v[100:103], v[208:211], v[172:175], v[100:103]
	v_mfma_f32_16x16x32_bf16 v[96:99], v[216:219], v[172:175], v[96:99]
	v_mfma_f32_16x16x32_bf16 v[84:87], v[208:211], v[180:183], v[84:87]
	v_mfma_f32_16x16x32_bf16 v[80:83], v[216:219], v[180:183], v[80:83]
	v_mfma_f32_16x16x32_bf16 v[68:71], v[208:211], v[200:203], v[68:71]
	v_mfma_f32_16x16x32_bf16 v[64:67], v[216:219], v[200:203], v[64:67]
	s_setprio 0
	s_barrier
	s_add_i32 s4, 0, 0x14000
	s_add_i32 s58, s58, s27
	v_lshl_add_u64 v[158:159], s[20:21], 0, v[186:187]
	s_mov_b32 m0, s58
	v_lshl_add_u64 v[220:221], s[20:21], 0, v[144:145]
	global_load_lds_dwordx4 v[158:159], off
	s_add_i32 m0, s58, 0x2000
	s_nop 0
	global_load_lds_dwordx4 v[220:221], off
	s_mov_b32 m0, s16
	v_lshl_add_u64 v[222:223], s[24:25], 0, v[148:149]
	ds_read_b128 v[154:157], v163 offset:16384
	ds_read_b128 v[164:167], v163 offset:17408
	ds_read_b128 v[168:171], v163 offset:18432
	ds_read_b128 v[172:175], v163 offset:19456
	ds_read_b128 v[176:179], v163 offset:20480
	ds_read_b128 v[180:183], v163 offset:21504
	ds_read_b128 v[196:199], v163 offset:22528
	ds_read_b128 v[200:203], v163 offset:23552
	global_load_lds_dwordx4 v[222:223], off
	v_lshl_add_u64 v[224:225], s[24:25], 0, v[146:147]
	s_mov_b32 m0, s17
	s_nop 0
	global_load_lds_dwordx4 v[224:225], off
	s_waitcnt vmcnt(6)
	s_waitcnt lgkmcnt(0)
	s_barrier
	s_setprio 1
	v_mfma_f32_16x16x32_bf16 v[60:63], v[128:131], v[154:157], v[60:63]
	v_mfma_f32_16x16x32_bf16 v[56:59], v[136:139], v[154:157], v[56:59]
	v_mfma_f32_16x16x32_bf16 v[44:47], v[128:131], v[168:171], v[44:47]
	v_mfma_f32_16x16x32_bf16 v[40:43], v[136:139], v[168:171], v[40:43]
	v_mfma_f32_16x16x32_bf16 v[28:31], v[128:131], v[176:179], v[28:31]
	v_mfma_f32_16x16x32_bf16 v[24:27], v[136:139], v[176:179], v[24:27]
	v_mfma_f32_16x16x32_bf16 v[12:15], v[128:131], v[196:199], v[12:15]
	v_mfma_f32_16x16x32_bf16 v[8:11], v[136:139], v[196:199], v[8:11]
	v_mfma_f32_16x16x32_bf16 v[60:63], v[132:135], v[164:167], v[60:63]
	v_mfma_f32_16x16x32_bf16 v[56:59], v[140:143], v[164:167], v[56:59]
	v_mfma_f32_16x16x32_bf16 v[44:47], v[132:135], v[172:175], v[44:47]
	v_mfma_f32_16x16x32_bf16 v[40:43], v[140:143], v[172:175], v[40:43]
	v_mfma_f32_16x16x32_bf16 v[28:31], v[132:135], v[180:183], v[28:31]
	v_mfma_f32_16x16x32_bf16 v[24:27], v[140:143], v[180:183], v[24:27]
	v_mfma_f32_16x16x32_bf16 v[12:15], v[132:135], v[200:203], v[12:15]
	v_mfma_f32_16x16x32_bf16 v[8:11], v[140:143], v[200:203], v[8:11]
	v_mfma_f32_16x16x32_bf16 v[52:55], v[204:207], v[154:157], v[52:55]
	v_mfma_f32_16x16x32_bf16 v[48:51], v[212:215], v[154:157], v[48:51]
	v_mfma_f32_16x16x32_bf16 v[36:39], v[204:207], v[168:171], v[36:39]
	v_mfma_f32_16x16x32_bf16 v[32:35], v[212:215], v[168:171], v[32:35]
	v_mfma_f32_16x16x32_bf16 v[20:23], v[204:207], v[176:179], v[20:23]
	v_mfma_f32_16x16x32_bf16 v[16:19], v[212:215], v[176:179], v[16:19]
	v_mfma_f32_16x16x32_bf16 v[4:7], v[204:207], v[196:199], v[4:7]
	v_mfma_f32_16x16x32_bf16 v[0:3], v[212:215], v[196:199], v[0:3]
	v_mfma_f32_16x16x32_bf16 v[52:55], v[208:211], v[164:167], v[52:55]
	v_mfma_f32_16x16x32_bf16 v[48:51], v[216:219], v[164:167], v[48:51]
	v_mfma_f32_16x16x32_bf16 v[36:39], v[208:211], v[172:175], v[36:39]
	v_mfma_f32_16x16x32_bf16 v[32:35], v[216:219], v[172:175], v[32:35]
	v_mfma_f32_16x16x32_bf16 v[20:23], v[208:211], v[180:183], v[20:23]
	v_mfma_f32_16x16x32_bf16 v[16:19], v[216:219], v[180:183], v[16:19]
	v_mfma_f32_16x16x32_bf16 v[4:7], v[208:211], v[200:203], v[4:7]
	v_mfma_f32_16x16x32_bf16 v[0:3], v[216:219], v[200:203], v[0:3]
	s_setprio 0
	s_barrier
	s_add_u32 s58, s20, 0x80000
	s_addc_u32 s59, s21, 0
	s_add_i32 s4, s4, s27
	v_lshl_add_u64 v[128:129], s[58:59], 0, v[186:187]
	s_mov_b32 m0, s4
	s_nop 0
	global_load_lds_dwordx4 v[128:129], off
	v_lshl_add_u64 v[128:129], s[58:59], 0, v[144:145]
	s_add_i32 m0, s4, 0x2000
	s_nop 0
	global_load_lds_dwordx4 v[128:129], off
	s_add_i32 s4, 0, 0x18000
	v_add_u32_e32 v140, s4, v161
	ds_read_b128 v[128:131], v140
	ds_read_b128 v[132:135], v140 offset:1024
	ds_read_b128 v[136:139], v140 offset:2048
	ds_read_b128 v[140:143], v140 offset:3072
	s_add_u32 s24, s24, 0x80000
	s_addc_u32 s25, s25, 0
	s_mov_b32 m0, s30
	v_lshl_add_u64 v[204:205], s[24:25], 0, v[148:149]
	ds_read_b128 v[154:157], v163 offset:32768
	ds_read_b128 v[164:167], v163 offset:33792
	ds_read_b128 v[168:171], v163 offset:34816
	ds_read_b128 v[172:175], v163 offset:35840
	ds_read_b128 v[176:179], v163 offset:36864
	ds_read_b128 v[180:183], v163 offset:37888
	ds_read_b128 v[196:199], v163 offset:38912
	ds_read_b128 v[200:203], v163 offset:39936
	global_load_lds_dwordx4 v[204:205], off
	v_lshl_add_u64 v[204:205], s[24:25], 0, v[146:147]
	s_mov_b32 m0, s31
	s_nop 0
	global_load_lds_dwordx4 v[204:205], off
	v_add_u32_e32 v216, 0x1c000, v161
	ds_read_b128 v[204:207], v216
	ds_read_b128 v[208:211], v216 offset:1024
	ds_read_b128 v[212:215], v216 offset:2048
	ds_read_b128 v[216:219], v216 offset:3072
	s_waitcnt vmcnt(8)
	s_waitcnt lgkmcnt(0)
	s_barrier
	s_setprio 1
	v_mfma_f32_16x16x32_bf16 v[124:127], v[128:131], v[154:157], v[124:127]
	v_mfma_f32_16x16x32_bf16 v[120:123], v[136:139], v[154:157], v[120:123]
	v_mfma_f32_16x16x32_bf16 v[108:111], v[128:131], v[168:171], v[108:111]
	v_mfma_f32_16x16x32_bf16 v[104:107], v[136:139], v[168:171], v[104:107]
	v_mfma_f32_16x16x32_bf16 v[92:95], v[128:131], v[176:179], v[92:95]
	v_mfma_f32_16x16x32_bf16 v[88:91], v[136:139], v[176:179], v[88:91]
	v_mfma_f32_16x16x32_bf16 v[76:79], v[128:131], v[196:199], v[76:79]
	v_mfma_f32_16x16x32_bf16 v[72:75], v[136:139], v[196:199], v[72:75]
	v_mfma_f32_16x16x32_bf16 v[124:127], v[132:135], v[164:167], v[124:127]
	v_mfma_f32_16x16x32_bf16 v[120:123], v[140:143], v[164:167], v[120:123]
	v_mfma_f32_16x16x32_bf16 v[108:111], v[132:135], v[172:175], v[108:111]
	v_mfma_f32_16x16x32_bf16 v[104:107], v[140:143], v[172:175], v[104:107]
	v_mfma_f32_16x16x32_bf16 v[92:95], v[132:135], v[180:183], v[92:95]
	v_mfma_f32_16x16x32_bf16 v[88:91], v[140:143], v[180:183], v[88:91]
	v_mfma_f32_16x16x32_bf16 v[76:79], v[132:135], v[200:203], v[76:79]
	v_mfma_f32_16x16x32_bf16 v[72:75], v[140:143], v[200:203], v[72:75]
	v_mfma_f32_16x16x32_bf16 v[116:119], v[204:207], v[154:157], v[116:119]
	v_mfma_f32_16x16x32_bf16 v[112:115], v[212:215], v[154:157], v[112:115]
	v_mfma_f32_16x16x32_bf16 v[100:103], v[204:207], v[168:171], v[100:103]
	v_mfma_f32_16x16x32_bf16 v[96:99], v[212:215], v[168:171], v[96:99]
	v_mfma_f32_16x16x32_bf16 v[84:87], v[204:207], v[176:179], v[84:87]
	v_mfma_f32_16x16x32_bf16 v[80:83], v[212:215], v[176:179], v[80:83]
	v_mfma_f32_16x16x32_bf16 v[68:71], v[204:207], v[196:199], v[68:71]
	v_mfma_f32_16x16x32_bf16 v[64:67], v[212:215], v[196:199], v[64:67]
	v_mfma_f32_16x16x32_bf16 v[116:119], v[208:211], v[164:167], v[116:119]
	v_mfma_f32_16x16x32_bf16 v[112:115], v[216:219], v[164:167], v[112:115]
	v_mfma_f32_16x16x32_bf16 v[100:103], v[208:211], v[172:175], v[100:103]
	v_mfma_f32_16x16x32_bf16 v[96:99], v[216:219], v[172:175], v[96:99]
	v_mfma_f32_16x16x32_bf16 v[84:87], v[208:211], v[180:183], v[84:87]
	v_mfma_f32_16x16x32_bf16 v[80:83], v[216:219], v[180:183], v[80:83]
	v_mfma_f32_16x16x32_bf16 v[68:71], v[208:211], v[200:203], v[68:71]
	v_mfma_f32_16x16x32_bf16 v[64:67], v[216:219], v[200:203], v[64:67]
	s_setprio 0
	s_barrier
	s_add_i32 s24, 0, 0x1c000
	s_add_i32 s4, s4, s27
	v_lshl_add_u64 v[158:159], v[158:159], 0, s[0:1]
	s_mov_b32 m0, s4
	global_load_lds_dwordx4 v[158:159], off
	v_lshl_add_u64 v[158:159], v[220:221], 0, s[0:1]
	s_add_i32 m0, s4, 0x2000
	s_nop 0
	global_load_lds_dwordx4 v[158:159], off
	s_mov_b32 m0, s38
	v_lshl_add_u64 v[158:159], v[222:223], 0, s[0:1]
	ds_read_b128 v[154:157], v163 offset:49152
	ds_read_b128 v[164:167], v163 offset:50176
	ds_read_b128 v[168:171], v163 offset:51200
	ds_read_b128 v[172:175], v163 offset:52224
	ds_read_b128 v[176:179], v163 offset:53248
	ds_read_b128 v[180:183], v163 offset:54272
	ds_read_b128 v[196:199], v163 offset:55296
	ds_read_b128 v[200:203], v163 offset:56320
	global_load_lds_dwordx4 v[158:159], off
	v_lshl_add_u64 v[158:159], v[224:225], 0, s[0:1]
	s_mov_b32 m0, s39
	s_nop 0
	global_load_lds_dwordx4 v[158:159], off
	s_add_u32 s20, s20, 0x80080
	s_addc_u32 s21, s21, 0
	s_add_i32 s4, s24, s27
	v_lshl_add_u64 v[158:159], s[20:21], 0, v[186:187]
	s_mov_b32 m0, s4
	s_nop 0
	global_load_lds_dwordx4 v[158:159], off
	v_lshl_add_u64 v[158:159], s[20:21], 0, v[144:145]
	s_add_i32 m0, s4, 0x2000
	s_nop 0
	global_load_lds_dwordx4 v[158:159], off
	s_waitcnt vmcnt(8)
	s_waitcnt lgkmcnt(0)
	s_barrier
	s_setprio 1
	v_mfma_f32_16x16x32_bf16 v[60:63], v[128:131], v[154:157], v[60:63]
	v_mfma_f32_16x16x32_bf16 v[56:59], v[136:139], v[154:157], v[56:59]
	v_mfma_f32_16x16x32_bf16 v[44:47], v[128:131], v[168:171], v[44:47]
	v_mfma_f32_16x16x32_bf16 v[40:43], v[136:139], v[168:171], v[40:43]
	v_mfma_f32_16x16x32_bf16 v[28:31], v[128:131], v[176:179], v[28:31]
	v_mfma_f32_16x16x32_bf16 v[24:27], v[136:139], v[176:179], v[24:27]
	v_mfma_f32_16x16x32_bf16 v[12:15], v[128:131], v[196:199], v[12:15]
	v_mfma_f32_16x16x32_bf16 v[8:11], v[136:139], v[196:199], v[8:11]
	v_mfma_f32_16x16x32_bf16 v[60:63], v[132:135], v[164:167], v[60:63]
	v_mfma_f32_16x16x32_bf16 v[56:59], v[140:143], v[164:167], v[56:59]
	v_mfma_f32_16x16x32_bf16 v[44:47], v[132:135], v[172:175], v[44:47]
	v_mfma_f32_16x16x32_bf16 v[40:43], v[140:143], v[172:175], v[40:43]
	v_mfma_f32_16x16x32_bf16 v[28:31], v[132:135], v[180:183], v[28:31]
	v_mfma_f32_16x16x32_bf16 v[24:27], v[140:143], v[180:183], v[24:27]
	v_mfma_f32_16x16x32_bf16 v[12:15], v[132:135], v[200:203], v[12:15]
	v_mfma_f32_16x16x32_bf16 v[8:11], v[140:143], v[200:203], v[8:11]
	v_mfma_f32_16x16x32_bf16 v[52:55], v[204:207], v[154:157], v[52:55]
	v_mfma_f32_16x16x32_bf16 v[48:51], v[212:215], v[154:157], v[48:51]
	v_mfma_f32_16x16x32_bf16 v[36:39], v[204:207], v[168:171], v[36:39]
	v_mfma_f32_16x16x32_bf16 v[32:35], v[212:215], v[168:171], v[32:35]
	v_mfma_f32_16x16x32_bf16 v[20:23], v[204:207], v[176:179], v[20:23]
	v_mfma_f32_16x16x32_bf16 v[16:19], v[212:215], v[176:179], v[16:19]
	v_mfma_f32_16x16x32_bf16 v[4:7], v[204:207], v[196:199], v[4:7]
	v_mfma_f32_16x16x32_bf16 v[0:3], v[212:215], v[196:199], v[0:3]
	v_mfma_f32_16x16x32_bf16 v[52:55], v[208:211], v[164:167], v[52:55]
	v_mfma_f32_16x16x32_bf16 v[48:51], v[216:219], v[164:167], v[48:51]
	v_mfma_f32_16x16x32_bf16 v[36:39], v[208:211], v[172:175], v[36:39]
	v_mfma_f32_16x16x32_bf16 v[32:35], v[216:219], v[172:175], v[32:35]
	v_mfma_f32_16x16x32_bf16 v[20:23], v[208:211], v[180:183], v[20:23]
	v_mfma_f32_16x16x32_bf16 v[16:19], v[216:219], v[180:183], v[16:19]
	v_mfma_f32_16x16x32_bf16 v[4:7], v[208:211], v[200:203], v[4:7]
	v_mfma_f32_16x16x32_bf16 v[0:3], v[216:219], v[200:203], v[0:3]
	s_setprio 0
	s_add_i32 s57, s57, 2
	s_add_u32 s12, s12, 0x100
	s_addc_u32 s13, s13, 0
	s_add_u32 s53, s53, 0x100
	s_addc_u32 s56, s56, 0
	s_cmp_gt_u32 s57, 29
	s_barrier
	s_cbranch_scc0 .LBB0_803
	s_lshl_b32 s3, s44, 8
	s_add_i32 s4, s3, s35
	v_add_u32_e32 v156, s3, v160
	s_min_i32 s3, s4, 0x4000
	v_add_u32_e32 v128, s35, v156
	s_ashr_i32 s12, s3, 11
	v_ashrrev_i32_e32 v129, 31, v128
	s_ashr_i32 s13, s12, 31
	v_lshl_add_u64 v[128:129], v[128:129], 2, s[48:49]
	s_lshl_b64 s[12:13], s[12:13], 15
	global_load_dword v167, v[128:129], off
	global_load_dword v170, v[128:129], off offset:64
	global_load_dword v171, v[128:129], off offset:128
	global_load_dword v172, v[128:129], off offset:192
	global_load_dword v173, v[128:129], off offset:512
	global_load_dword v166, v[128:129], off offset:576
	global_load_dword v165, v[128:129], off offset:640
	v_lshl_or_b32 v154, s41, 8, v162
	s_add_u32 s12, s37, s12
	s_addc_u32 s13, s6, s13
	v_ashrrev_i32_e32 v155, 31, v154
	global_load_dword v164, v[128:129], off offset:704
	v_lshl_add_u64 v[128:129], v[154:155], 2, s[12:13]
	global_load_dwordx4 v[140:143], v[128:129], off
	global_load_dwordx4 v[136:139], v[128:129], off offset:16
	global_load_dwordx4 v[132:135], v[128:129], off offset:512
	s_nop 0
	global_load_dwordx4 v[128:131], v[128:129], off offset:528
	v_ashrrev_i32_e32 v157, 31, v156
	v_lshlrev_b64 v[158:159], 1, v[154:155]
	v_lshlrev_b64 v[154:155], 14, v[156:157]
	v_lshl_add_u64 v[154:155], s[54:55], 0, v[154:155]
	v_lshl_add_u64 v[154:155], v[154:155], 0, v[158:159]
	v_or_b32_e32 v168, 16, v156
	v_ashrrev_i32_e32 v169, 31, v168
	s_mov_b32 s3, 0x200000
	s_mov_b64 s[12:13], 0x200000
	s_mov_b32 s41, s2
	s_mov_b32 s44, s14
	s_mov_b64 s[20:21], s[28:29]
	s_waitcnt vmcnt(0)
	s_nop 0
	v_fmamk_f32 v157, v167, 0x3a000000, v229
	v_mul_f32_e32 v167, 0x4b800000, v157
	v_cmp_gt_f32_e32 vcc, s5, v157
	s_nop 1
	v_cndmask_b32_e32 v157, v157, v167, vcc
	v_rsq_f32_e32 v157, v157
	v_fmamk_f32 v167, v170, 0x3a000000, v229
	v_mul_f32_e32 v170, 0x45800000, v157
	v_cndmask_b32_e32 v170, v157, v170, vcc
	v_pk_fma_f32 v[124:125], v[124:125], v[170:171], v[140:141] op_sel_hi:[1,0,1]
	v_pk_fma_f32 v[112:113], v[112:113], v[170:171], v[128:129] op_sel_hi:[1,0,1]
	v_pk_fma_f32 v[126:127], v[126:127], v[170:171], v[142:143] op_sel_hi:[1,0,1]
	v_pk_fma_f32 v[122:123], v[122:123], v[170:171], v[138:139] op_sel_hi:[1,0,1]
	v_pk_fma_f32 v[120:121], v[120:121], v[170:171], v[136:137] op_sel_hi:[1,0,1]
	v_pk_fma_f32 v[116:117], v[116:117], v[170:171], v[132:133] op_sel_hi:[1,0,1]
	v_pk_fma_f32 v[114:115], v[114:115], v[170:171], v[130:131] op_sel_hi:[1,0,1]
	v_max_f32_e32 v124, 0, v124
	v_max_f32_e32 v125, 0, v125
	v_max_f32_e32 v112, 0, v112
	v_pk_fma_f32 v[118:119], v[118:119], v[170:171], v[134:135] op_sel_hi:[1,0,1]
	v_max_f32_e32 v120, 0, v120
	v_max_f32_e32 v121, 0, v121
	v_max_f32_e32 v126, 0, v126
	v_max_f32_e32 v122, 0, v122
	v_max_f32_e32 v127, 0, v127
	v_max_f32_e32 v123, 0, v123
	v_max_f32_e32 v116, 0, v116
	v_max_f32_e32 v117, 0, v117
	v_max_f32_e32 v113, 0, v113
	v_max_f32_e32 v114, 0, v114
	v_max_f32_e32 v115, 0, v115
	v_mul_f32_e32 v124, v124, v124
	v_mul_f32_e32 v125, v125, v125
	v_mul_f32_e32 v157, v112, v112
	v_cvt_pk_bf16_f32 v112, v124, v125
	v_mul_f32_e32 v174, 0x4b800000, v167
	v_max_f32_e32 v118, 0, v118
	v_max_f32_e32 v119, 0, v119
	v_mul_f32_e32 v120, v120, v120
	v_mul_f32_e32 v121, v121, v121
	v_mul_f32_e32 v126, v126, v126
	v_mul_f32_e32 v122, v122, v122
	v_mul_f32_e32 v127, v127, v127
	v_mul_f32_e32 v123, v123, v123
	v_mul_f32_e32 v116, v116, v116
	v_mul_f32_e32 v117, v117, v117
	v_mul_f32_e32 v170, v113, v113
	v_mul_f32_e32 v175, v114, v114
	v_mul_f32_e32 v176, v115, v115
	v_cvt_pk_bf16_f32 v113, v126, v127
	v_cvt_pk_bf16_f32 v114, v120, v121
	v_cvt_pk_bf16_f32 v115, v122, v123
	global_store_dwordx4 v[154:155], v[112:115], off
	v_cmp_gt_f32_e32 vcc, s5, v167
	v_mul_f32_e32 v118, v118, v118
	v_cvt_pk_bf16_f32 v112, v116, v117
	v_mul_f32_e32 v119, v119, v119
	v_cvt_pk_bf16_f32 v113, v118, v119
	v_cvt_pk_bf16_f32 v114, v157, v170
	v_cvt_pk_bf16_f32 v115, v175, v176
	global_store_dwordx4 v[154:155], v[112:115], off offset:256
	s_nop 1
	v_cndmask_b32_e32 v112, v167, v174, vcc
	v_rsq_f32_e32 v114, v112
	v_lshlrev_b64 v[112:113], 14, v[168:169]
	v_lshl_add_u64 v[112:113], s[54:55], 0, v[112:113]
	v_lshl_add_u64 v[112:113], v[112:113], 0, v[158:159]
	v_mul_f32_e32 v115, 0x45800000, v114
	v_cndmask_b32_e32 v114, v114, v115, vcc
	v_pk_fma_f32 v[104:105], v[104:105], v[114:115], v[136:137] op_sel_hi:[1,0,1]
	v_pk_fma_f32 v[108:109], v[108:109], v[114:115], v[140:141] op_sel_hi:[1,0,1]
	v_pk_fma_f32 v[106:107], v[106:107], v[114:115], v[138:139] op_sel_hi:[1,0,1]
	v_max_f32_e32 v104, 0, v104
	v_pk_fma_f32 v[110:111], v[110:111], v[114:115], v[142:143] op_sel_hi:[1,0,1]
	v_mul_f32_e32 v115, v104, v104
	v_max_f32_e32 v104, 0, v109
	v_max_f32_e32 v105, 0, v105
	v_max_f32_e32 v106, 0, v106
	v_max_f32_e32 v108, 0, v108
	v_mul_f32_e32 v104, v104, v104
	v_mul_f32_e32 v109, v105, v105
	v_max_f32_e32 v105, 0, v110
	v_mul_f32_e32 v110, v106, v106
	v_max_f32_e32 v106, 0, v111
	v_max_f32_e32 v107, 0, v107
	v_pk_fma_f32 v[98:99], v[98:99], v[114:115], v[130:131] op_sel_hi:[1,0,1]
	v_pk_fma_f32 v[96:97], v[96:97], v[114:115], v[128:129] op_sel_hi:[1,0,1]
	v_mul_f32_e32 v108, v108, v108
	v_mul_f32_e32 v105, v105, v105
	v_mul_f32_e32 v106, v106, v106
	v_mul_f32_e32 v107, v107, v107
	v_cvt_pk_bf16_f32 v104, v108, v104
	v_pk_fma_f32 v[102:103], v[102:103], v[114:115], v[134:135] op_sel_hi:[1,0,1]
	v_pk_fma_f32 v[100:101], v[100:101], v[114:115], v[132:133] op_sel_hi:[1,0,1]
	v_max_f32_e32 v96, 0, v96
	v_max_f32_e32 v97, 0, v97
	v_max_f32_e32 v98, 0, v98
	v_cvt_pk_bf16_f32 v105, v105, v106
	v_cvt_pk_bf16_f32 v106, v115, v109
	v_cvt_pk_bf16_f32 v107, v110, v107
	global_store_dwordx4 v[112:113], v[104:107], off
	v_max_f32_e32 v100, 0, v100
	v_max_f32_e32 v99, 0, v99
	v_mul_f32_e32 v104, v96, v96
	v_max_f32_e32 v96, 0, v101
	v_mul_f32_e32 v101, v97, v97
	v_max_f32_e32 v97, 0, v102
	v_mul_f32_e32 v102, v98, v98
	v_max_f32_e32 v98, 0, v103
	v_mul_f32_e32 v96, v96, v96
	v_mul_f32_e32 v97, v97, v97
	v_mul_f32_e32 v98, v98, v98
	v_mul_f32_e32 v100, v100, v100
	v_mul_f32_e32 v99, v99, v99
	v_cvt_pk_bf16_f32 v96, v100, v96
	v_cvt_pk_bf16_f32 v97, v97, v98
	v_cvt_pk_bf16_f32 v98, v104, v101
	v_cvt_pk_bf16_f32 v99, v102, v99
	global_store_dwordx4 v[112:113], v[96:99], off offset:256
	s_nop 1
	v_fmamk_f32 v98, v171, 0x3a000000, v229
	v_mul_f32_e32 v99, 0x4b800000, v98
	v_cmp_gt_f32_e32 vcc, s5, v98
	v_or_b32_e32 v96, 32, v156
	v_ashrrev_i32_e32 v97, 31, v96
	v_cndmask_b32_e32 v98, v98, v99, vcc
	v_rsq_f32_e32 v98, v98
	v_lshlrev_b64 v[96:97], 14, v[96:97]
	v_lshl_add_u64 v[96:97], s[54:55], 0, v[96:97]
	v_lshl_add_u64 v[96:97], v[96:97], 0, v[158:159]
	v_mul_f32_e32 v99, 0x45800000, v98
	v_cndmask_b32_e32 v98, v98, v99, vcc
	v_pk_fma_f32 v[88:89], v[88:89], v[98:99], v[136:137] op_sel_hi:[1,0,1]
	v_pk_fma_f32 v[92:93], v[92:93], v[98:99], v[140:141] op_sel_hi:[1,0,1]
	v_pk_fma_f32 v[90:91], v[90:91], v[98:99], v[138:139] op_sel_hi:[1,0,1]
	v_max_f32_e32 v88, 0, v88
	v_pk_fma_f32 v[94:95], v[94:95], v[98:99], v[142:143] op_sel_hi:[1,0,1]
	v_mul_f32_e32 v99, v88, v88
	v_max_f32_e32 v88, 0, v93
	v_max_f32_e32 v89, 0, v89
	v_max_f32_e32 v90, 0, v90
	v_max_f32_e32 v92, 0, v92
	v_mul_f32_e32 v88, v88, v88
	v_mul_f32_e32 v93, v89, v89
	v_max_f32_e32 v89, 0, v94
	v_mul_f32_e32 v94, v90, v90
	v_max_f32_e32 v90, 0, v95
	v_max_f32_e32 v91, 0, v91
	v_pk_fma_f32 v[82:83], v[82:83], v[98:99], v[130:131] op_sel_hi:[1,0,1]
	v_pk_fma_f32 v[80:81], v[80:81], v[98:99], v[128:129] op_sel_hi:[1,0,1]
	v_mul_f32_e32 v92, v92, v92
	v_mul_f32_e32 v89, v89, v89
	v_mul_f32_e32 v90, v90, v90
	v_mul_f32_e32 v91, v91, v91
	v_cvt_pk_bf16_f32 v88, v92, v88
	v_pk_fma_f32 v[86:87], v[86:87], v[98:99], v[134:135] op_sel_hi:[1,0,1]
	v_pk_fma_f32 v[84:85], v[84:85], v[98:99], v[132:133] op_sel_hi:[1,0,1]
	v_max_f32_e32 v80, 0, v80
	v_max_f32_e32 v81, 0, v81
	v_max_f32_e32 v82, 0, v82
	v_cvt_pk_bf16_f32 v89, v89, v90
	v_cvt_pk_bf16_f32 v90, v99, v93
	v_cvt_pk_bf16_f32 v91, v94, v91
	global_store_dwordx4 v[96:97], v[88:91], off
	v_max_f32_e32 v84, 0, v84
	v_max_f32_e32 v83, 0, v83
	v_mul_f32_e32 v88, v80, v80
	v_max_f32_e32 v80, 0, v85
	v_mul_f32_e32 v85, v81, v81
	v_max_f32_e32 v81, 0, v86
	v_mul_f32_e32 v86, v82, v82
	v_max_f32_e32 v82, 0, v87
	v_mul_f32_e32 v80, v80, v80
	v_mul_f32_e32 v81, v81, v81
	v_mul_f32_e32 v82, v82, v82
	v_mul_f32_e32 v84, v84, v84
	v_mul_f32_e32 v83, v83, v83
	v_cvt_pk_bf16_f32 v80, v84, v80
	v_cvt_pk_bf16_f32 v81, v81, v82
	v_cvt_pk_bf16_f32 v82, v88, v85
	v_cvt_pk_bf16_f32 v83, v86, v83
	global_store_dwordx4 v[96:97], v[80:83], off offset:256
	s_nop 1
	v_fmamk_f32 v82, v172, 0x3a000000, v229
	v_mul_f32_e32 v83, 0x4b800000, v82
	v_cmp_gt_f32_e32 vcc, s5, v82
	v_or_b32_e32 v80, 48, v156
	v_ashrrev_i32_e32 v81, 31, v80
	v_cndmask_b32_e32 v82, v82, v83, vcc
	v_rsq_f32_e32 v82, v82
	v_lshlrev_b64 v[80:81], 14, v[80:81]
	v_lshl_add_u64 v[80:81], s[54:55], 0, v[80:81]
	v_lshl_add_u64 v[80:81], v[80:81], 0, v[158:159]
	v_mul_f32_e32 v83, 0x45800000, v82
	v_cndmask_b32_e32 v82, v82, v83, vcc
	v_pk_fma_f32 v[72:73], v[72:73], v[82:83], v[136:137] op_sel_hi:[1,0,1]
	v_pk_fma_f32 v[76:77], v[76:77], v[82:83], v[140:141] op_sel_hi:[1,0,1]
	v_pk_fma_f32 v[74:75], v[74:75], v[82:83], v[138:139] op_sel_hi:[1,0,1]
	v_max_f32_e32 v72, 0, v72
	v_pk_fma_f32 v[78:79], v[78:79], v[82:83], v[142:143] op_sel_hi:[1,0,1]
	v_mul_f32_e32 v83, v72, v72
	v_max_f32_e32 v72, 0, v77
	v_max_f32_e32 v73, 0, v73
	v_max_f32_e32 v74, 0, v74
	v_max_f32_e32 v76, 0, v76
	v_mul_f32_e32 v72, v72, v72
	v_mul_f32_e32 v77, v73, v73
	v_max_f32_e32 v73, 0, v78
	v_mul_f32_e32 v78, v74, v74
	v_max_f32_e32 v74, 0, v79
	v_max_f32_e32 v75, 0, v75
	v_pk_fma_f32 v[64:65], v[64:65], v[82:83], v[128:129] op_sel_hi:[1,0,1]
	v_mul_f32_e32 v76, v76, v76
	v_mul_f32_e32 v73, v73, v73
	v_mul_f32_e32 v74, v74, v74
	v_mul_f32_e32 v75, v75, v75
	v_cvt_pk_bf16_f32 v72, v76, v72
	v_pk_fma_f32 v[68:69], v[68:69], v[82:83], v[132:133] op_sel_hi:[1,0,1]
	v_pk_fma_f32 v[66:67], v[66:67], v[82:83], v[130:131] op_sel_hi:[1,0,1]
	v_max_f32_e32 v64, 0, v64
	v_cvt_pk_bf16_f32 v73, v73, v74
	v_cvt_pk_bf16_f32 v74, v83, v77
	v_cvt_pk_bf16_f32 v75, v78, v75
	global_store_dwordx4 v[80:81], v[72:75], off
	v_pk_fma_f32 v[70:71], v[70:71], v[82:83], v[134:135] op_sel_hi:[1,0,1]
	v_max_f32_e32 v68, 0, v68
	v_mul_f32_e32 v72, v64, v64
	v_max_f32_e32 v64, 0, v69
	v_max_f32_e32 v65, 0, v65
	v_max_f32_e32 v66, 0, v66
	v_mul_f32_e32 v68, v68, v68
	v_mul_f32_e32 v64, v64, v64
	v_mul_f32_e32 v69, v65, v65
	v_max_f32_e32 v65, 0, v70
	v_mul_f32_e32 v70, v66, v66
	v_max_f32_e32 v66, 0, v71
	v_mul_f32_e32 v65, v65, v65
	v_mul_f32_e32 v66, v66, v66
	v_cvt_pk_bf16_f32 v64, v68, v64
	v_fmamk_f32 v68, v173, 0x3a000000, v229
	v_cvt_pk_bf16_f32 v65, v65, v66
	v_cvt_pk_bf16_f32 v66, v72, v69
	v_mul_f32_e32 v69, 0x4b800000, v68
	v_cmp_gt_f32_e32 vcc, s5, v68
	v_max_f32_e32 v67, 0, v67
	v_mul_f32_e32 v67, v67, v67
	v_cndmask_b32_e32 v68, v68, v69, vcc
	v_rsq_f32_e32 v68, v68
	v_cvt_pk_bf16_f32 v67, v70, v67
	global_store_dwordx4 v[80:81], v[64:67], off offset:256
	s_nop 1
	v_mul_f32_e32 v66, 0x45800000, v68
	v_cndmask_b32_e32 v66, v68, v66, vcc
	v_pk_fma_f32 v[56:57], v[56:57], v[66:67], v[136:137] op_sel_hi:[1,0,1]
	v_pk_fma_f32 v[60:61], v[60:61], v[66:67], v[140:141] op_sel_hi:[1,0,1]
	v_pk_fma_f32 v[58:59], v[58:59], v[66:67], v[138:139] op_sel_hi:[1,0,1]
	v_max_f32_e32 v56, 0, v56
	v_pk_fma_f32 v[62:63], v[62:63], v[66:67], v[142:143] op_sel_hi:[1,0,1]
	v_max_f32_e32 v60, 0, v60
	v_mul_f32_e32 v67, v56, v56
	v_max_f32_e32 v56, 0, v61
	v_max_f32_e32 v57, 0, v57
	v_max_f32_e32 v58, 0, v58
	v_mul_f32_e32 v60, v60, v60
	v_mul_f32_e32 v56, v56, v56
	v_mul_f32_e32 v61, v57, v57
	v_max_f32_e32 v57, 0, v62
	v_mul_f32_e32 v62, v58, v58
	v_max_f32_e32 v58, 0, v63
	v_mul_f32_e32 v57, v57, v57
	v_max_f32_e32 v59, 0, v59
	v_mul_f32_e32 v58, v58, v58
	v_cvt_pk_bf16_f32 v56, v60, v56
	v_add_co_u32_e32 v60, vcc, s3, v154
	v_pk_fma_f32 v[48:49], v[48:49], v[66:67], v[128:129] op_sel_hi:[1,0,1]
	v_mul_f32_e32 v59, v59, v59
	v_cvt_pk_bf16_f32 v57, v57, v58
	v_cvt_pk_bf16_f32 v58, v67, v61
	v_addc_co_u32_e32 v61, vcc, 0, v155, vcc
	v_pk_fma_f32 v[52:53], v[52:53], v[66:67], v[132:133] op_sel_hi:[1,0,1]
	v_pk_fma_f32 v[50:51], v[50:51], v[66:67], v[130:131] op_sel_hi:[1,0,1]
	v_max_f32_e32 v48, 0, v48
	v_cvt_pk_bf16_f32 v59, v62, v59
	global_store_dwordx4 v[60:61], v[56:59], off
	v_pk_fma_f32 v[54:55], v[54:55], v[66:67], v[134:135] op_sel_hi:[1,0,1]
	v_max_f32_e32 v52, 0, v52
	v_mul_f32_e32 v56, v48, v48
	v_max_f32_e32 v48, 0, v53
	v_max_f32_e32 v49, 0, v49
	v_max_f32_e32 v50, 0, v50
	v_mul_f32_e32 v52, v52, v52
	v_mul_f32_e32 v48, v48, v48
	v_mul_f32_e32 v53, v49, v49
	v_max_f32_e32 v49, 0, v54
	v_mul_f32_e32 v54, v50, v50
	v_max_f32_e32 v50, 0, v55
	v_mul_f32_e32 v49, v49, v49
	v_mul_f32_e32 v50, v50, v50
	v_cvt_pk_bf16_f32 v48, v52, v48
	v_fmamk_f32 v52, v166, 0x3a000000, v229
	v_cvt_pk_bf16_f32 v49, v49, v50
	v_cvt_pk_bf16_f32 v50, v56, v53
	v_mul_f32_e32 v53, 0x4b800000, v52
	v_cmp_gt_f32_e32 vcc, s5, v52
	v_max_f32_e32 v51, 0, v51
	v_lshl_add_u64 v[64:65], v[154:155], 0, s[12:13]
	v_cndmask_b32_e32 v52, v52, v53, vcc
	v_rsq_f32_e32 v52, v52
	v_mul_f32_e32 v51, v51, v51
	v_cvt_pk_bf16_f32 v51, v54, v51
	global_store_dwordx4 v[64:65], v[48:51], off offset:256
	s_mov_b32 s3, 0x240000
	s_mov_b64 s[12:13], 0x240000
	v_mul_f32_e32 v50, 0x45800000, v52
	v_cndmask_b32_e32 v50, v52, v50, vcc
	v_pk_fma_f32 v[40:41], v[40:41], v[50:51], v[136:137] op_sel_hi:[1,0,1]
	v_pk_fma_f32 v[44:45], v[44:45], v[50:51], v[140:141] op_sel_hi:[1,0,1]
	v_pk_fma_f32 v[42:43], v[42:43], v[50:51], v[138:139] op_sel_hi:[1,0,1]
	v_max_f32_e32 v40, 0, v40
	v_pk_fma_f32 v[46:47], v[46:47], v[50:51], v[142:143] op_sel_hi:[1,0,1]
	v_max_f32_e32 v44, 0, v44
	v_mul_f32_e32 v51, v40, v40
	v_max_f32_e32 v40, 0, v45
	v_max_f32_e32 v41, 0, v41
	v_max_f32_e32 v42, 0, v42
	v_mul_f32_e32 v44, v44, v44
	v_mul_f32_e32 v40, v40, v40
	v_mul_f32_e32 v45, v41, v41
	v_max_f32_e32 v41, 0, v46
	v_mul_f32_e32 v46, v42, v42
	v_max_f32_e32 v42, 0, v47
	v_mul_f32_e32 v41, v41, v41
	v_max_f32_e32 v43, 0, v43
	v_mul_f32_e32 v42, v42, v42
	v_cvt_pk_bf16_f32 v40, v44, v40
	v_add_co_u32_e32 v44, vcc, s3, v154
	v_pk_fma_f32 v[32:33], v[32:33], v[50:51], v[128:129] op_sel_hi:[1,0,1]
	v_mul_f32_e32 v43, v43, v43
	v_cvt_pk_bf16_f32 v41, v41, v42
	v_cvt_pk_bf16_f32 v42, v51, v45
	v_addc_co_u32_e32 v45, vcc, 0, v155, vcc
	v_pk_fma_f32 v[36:37], v[36:37], v[50:51], v[132:133] op_sel_hi:[1,0,1]
	v_pk_fma_f32 v[34:35], v[34:35], v[50:51], v[130:131] op_sel_hi:[1,0,1]
	v_max_f32_e32 v32, 0, v32
	v_cvt_pk_bf16_f32 v43, v46, v43
	global_store_dwordx4 v[44:45], v[40:43], off
	v_pk_fma_f32 v[38:39], v[38:39], v[50:51], v[134:135] op_sel_hi:[1,0,1]
	v_max_f32_e32 v36, 0, v36
	v_mul_f32_e32 v40, v32, v32
	v_max_f32_e32 v32, 0, v37
	v_max_f32_e32 v33, 0, v33
	v_max_f32_e32 v34, 0, v34
	v_mul_f32_e32 v36, v36, v36
	v_mul_f32_e32 v32, v32, v32
	v_mul_f32_e32 v37, v33, v33
	v_max_f32_e32 v33, 0, v38
	v_mul_f32_e32 v38, v34, v34
	v_max_f32_e32 v34, 0, v39
	v_mul_f32_e32 v33, v33, v33
	v_mul_f32_e32 v34, v34, v34
	v_cvt_pk_bf16_f32 v32, v36, v32
	v_fmamk_f32 v36, v165, 0x3a000000, v229
	v_cvt_pk_bf16_f32 v33, v33, v34
	v_cvt_pk_bf16_f32 v34, v40, v37
	v_mul_f32_e32 v37, 0x4b800000, v36
	v_cmp_gt_f32_e32 vcc, s5, v36
	v_max_f32_e32 v35, 0, v35
	v_lshl_add_u64 v[48:49], v[154:155], 0, s[12:13]
	v_cndmask_b32_e32 v36, v36, v37, vcc
	v_rsq_f32_e32 v36, v36
	v_mul_f32_e32 v35, v35, v35
	v_cvt_pk_bf16_f32 v35, v38, v35
	global_store_dwordx4 v[48:49], v[32:35], off offset:256
	s_mov_b32 s3, 0x280000
	s_mov_b64 s[12:13], 0x280000
	v_mul_f32_e32 v34, 0x45800000, v36
	v_cndmask_b32_e32 v34, v36, v34, vcc
	v_pk_fma_f32 v[24:25], v[24:25], v[34:35], v[136:137] op_sel_hi:[1,0,1]
	v_pk_fma_f32 v[28:29], v[28:29], v[34:35], v[140:141] op_sel_hi:[1,0,1]
	v_pk_fma_f32 v[26:27], v[26:27], v[34:35], v[138:139] op_sel_hi:[1,0,1]
	v_max_f32_e32 v24, 0, v24
	v_pk_fma_f32 v[30:31], v[30:31], v[34:35], v[142:143] op_sel_hi:[1,0,1]
	v_max_f32_e32 v28, 0, v28
	v_mul_f32_e32 v35, v24, v24
	v_max_f32_e32 v24, 0, v29
	v_max_f32_e32 v25, 0, v25
	v_max_f32_e32 v26, 0, v26
	v_mul_f32_e32 v28, v28, v28
	v_mul_f32_e32 v24, v24, v24
	v_mul_f32_e32 v29, v25, v25
	v_max_f32_e32 v25, 0, v30
	v_mul_f32_e32 v30, v26, v26
	v_max_f32_e32 v26, 0, v31
	v_mul_f32_e32 v25, v25, v25
	v_max_f32_e32 v27, 0, v27
	v_mul_f32_e32 v26, v26, v26
	v_cvt_pk_bf16_f32 v24, v28, v24
	v_add_co_u32_e32 v28, vcc, s3, v154
	v_pk_fma_f32 v[16:17], v[16:17], v[34:35], v[128:129] op_sel_hi:[1,0,1]
	v_mul_f32_e32 v27, v27, v27
	v_cvt_pk_bf16_f32 v25, v25, v26
	v_cvt_pk_bf16_f32 v26, v35, v29
	v_addc_co_u32_e32 v29, vcc, 0, v155, vcc
	v_pk_fma_f32 v[20:21], v[20:21], v[34:35], v[132:133] op_sel_hi:[1,0,1]
	v_pk_fma_f32 v[18:19], v[18:19], v[34:35], v[130:131] op_sel_hi:[1,0,1]
	v_max_f32_e32 v16, 0, v16
	v_cvt_pk_bf16_f32 v27, v30, v27
	global_store_dwordx4 v[28:29], v[24:27], off
	v_pk_fma_f32 v[22:23], v[22:23], v[34:35], v[134:135] op_sel_hi:[1,0,1]
	v_max_f32_e32 v20, 0, v20
	v_mul_f32_e32 v24, v16, v16
	v_max_f32_e32 v16, 0, v21
	v_max_f32_e32 v17, 0, v17
	v_max_f32_e32 v18, 0, v18
	v_mul_f32_e32 v20, v20, v20
	v_mul_f32_e32 v16, v16, v16
	v_mul_f32_e32 v21, v17, v17
	v_max_f32_e32 v17, 0, v22
	v_mul_f32_e32 v22, v18, v18
	v_max_f32_e32 v18, 0, v23
	v_mul_f32_e32 v17, v17, v17
	v_mul_f32_e32 v18, v18, v18
	v_cvt_pk_bf16_f32 v16, v20, v16
	v_fmamk_f32 v20, v164, 0x3a000000, v229
	v_cvt_pk_bf16_f32 v17, v17, v18
	v_cvt_pk_bf16_f32 v18, v24, v21
	v_mul_f32_e32 v21, 0x4b800000, v20
	v_cmp_gt_f32_e32 vcc, s5, v20
	v_max_f32_e32 v19, 0, v19
	v_lshl_add_u64 v[32:33], v[154:155], 0, s[12:13]
	v_cndmask_b32_e32 v20, v20, v21, vcc
	v_rsq_f32_e32 v20, v20
	v_mul_f32_e32 v19, v19, v19
	v_cvt_pk_bf16_f32 v19, v22, v19
	global_store_dwordx4 v[32:33], v[16:19], off offset:256
	s_mov_b32 s3, 0x2c0000
	s_mov_b64 s[12:13], 0x2c0000
	v_mul_f32_e32 v18, 0x45800000, v20
	v_cndmask_b32_e32 v18, v20, v18, vcc
	v_pk_fma_f32 v[8:9], v[8:9], v[18:19], v[136:137] op_sel_hi:[1,0,1]
	v_pk_fma_f32 v[12:13], v[12:13], v[18:19], v[140:141] op_sel_hi:[1,0,1]
	v_pk_fma_f32 v[10:11], v[10:11], v[18:19], v[138:139] op_sel_hi:[1,0,1]
	v_max_f32_e32 v8, 0, v8
	v_pk_fma_f32 v[14:15], v[14:15], v[18:19], v[142:143] op_sel_hi:[1,0,1]
	v_max_f32_e32 v12, 0, v12
	v_mul_f32_e32 v19, v8, v8
	v_max_f32_e32 v8, 0, v13
	v_max_f32_e32 v9, 0, v9
	v_max_f32_e32 v10, 0, v10
	v_mul_f32_e32 v12, v12, v12
	v_mul_f32_e32 v8, v8, v8
	v_mul_f32_e32 v13, v9, v9
	v_max_f32_e32 v9, 0, v14
	v_mul_f32_e32 v14, v10, v10
	v_max_f32_e32 v10, 0, v15
	v_mul_f32_e32 v9, v9, v9
	v_max_f32_e32 v11, 0, v11
	v_mul_f32_e32 v10, v10, v10
	v_cvt_pk_bf16_f32 v8, v12, v8
	v_add_co_u32_e32 v12, vcc, s3, v154
	v_pk_fma_f32 v[2:3], v[2:3], v[18:19], v[130:131] op_sel_hi:[1,0,1]
	v_pk_fma_f32 v[0:1], v[0:1], v[18:19], v[128:129] op_sel_hi:[1,0,1]
	v_mul_f32_e32 v11, v11, v11
	v_cvt_pk_bf16_f32 v9, v9, v10
	v_cvt_pk_bf16_f32 v10, v19, v13
	v_addc_co_u32_e32 v13, vcc, 0, v155, vcc
	v_pk_fma_f32 v[6:7], v[6:7], v[18:19], v[134:135] op_sel_hi:[1,0,1]
	v_pk_fma_f32 v[4:5], v[4:5], v[18:19], v[132:133] op_sel_hi:[1,0,1]
	v_max_f32_e32 v0, 0, v0
	v_max_f32_e32 v1, 0, v1
	v_max_f32_e32 v2, 0, v2
	v_cvt_pk_bf16_f32 v11, v14, v11
	global_store_dwordx4 v[12:13], v[8:11], off
	v_max_f32_e32 v3, 0, v3
	v_lshl_add_u64 v[16:17], v[154:155], 0, s[12:13]
	v_mul_f32_e32 v8, v0, v0
	v_max_f32_e32 v0, 0, v5
	v_mul_f32_e32 v5, v1, v1
	v_max_f32_e32 v1, 0, v6
	v_mul_f32_e32 v6, v2, v2
	v_max_f32_e32 v2, 0, v7
	v_max_f32_e32 v4, 0, v4
	v_mul_f32_e32 v0, v0, v0
	v_mul_f32_e32 v1, v1, v1
	v_mul_f32_e32 v2, v2, v2
	v_mul_f32_e32 v3, v3, v3
	s_and_b64 vcc, exec, s[42:43]
	s_mov_b64 s[12:13], s[18:19]
	v_mul_f32_e32 v4, v4, v4
	v_cvt_pk_bf16_f32 v0, v4, v0
	v_cvt_pk_bf16_f32 v1, v1, v2
	v_cvt_pk_bf16_f32 v2, v8, v5
	v_cvt_pk_bf16_f32 v3, v6, v3
	global_store_dwordx4 v[16:17], v[0:3], off offset:256
	s_cbranch_vccz .LBB0_796
	s_waitcnt vmcnt(0)
	s_cmpk_gt_u32 s22, 0xff
	v_readlane_b32 s35, v252, 37
	s_cbranch_scc1 .LBB0_807
	s_barrier

.LBB0_880:
	v_bfe_u32 v16, v6, 4, 2
	v_readlane_b32 s20, v252, 29
	v_and_b32_e32 v7, 15, v6
	v_lshlrev_b32_e32 v17, 4, v16
	v_lshlrev_b32_e32 v6, 2, v6
	s_lshl_b32 s2, s2, 5
	v_mov_b32_e32 v147, v187
	v_readlane_b32 s21, v252, 30
	v_lshl_or_b32 v160, s3, 6, v7
	v_lshl_or_b32 v7, v7, 6, v17
	s_lshl_b32 s3, s3, 13
	v_and_b32_e32 v6, 32, v6
	s_and_b32 s2, s2, 0x60
	v_lshl_add_u64 v[8:9], s[20:21], 0, v[146:147]
	v_mov_b32_e32 v145, v187
	v_readlane_b32 s12, v252, 25
	v_bitop3_b32 v17, v7, s3, v6 bitop3:0xde
	s_lshl_b32 s3, s2, 7
	v_lshl_add_u64 v[10:11], s[20:21], 0, v[144:145]
	v_readlane_b32 s13, v252, 26
	v_bitop3_b32 v161, v7, s3, v6 bitop3:0xde
	s_add_i32 m0, s22, 0x18000
	v_lshl_add_u64 v[6:7], v[8:9], 0, s[0:1]
	v_lshl_add_u64 v[12:13], s[12:13], 0, v[146:147]
	s_waitcnt vmcnt(2)
	s_barrier
	global_load_lds_dwordx4 v[6:7], off
	v_lshl_add_u64 v[6:7], v[10:11], 0, s[0:1]
	s_add_i32 m0, s22, 0x1a000
	s_add_i32 s16, s22, 0x8000
	v_lshl_add_u64 v[14:15], s[12:13], 0, v[144:145]
	global_load_lds_dwordx4 v[6:7], off
	v_lshl_add_u64 v[6:7], v[12:13], 0, s[0:1]
	s_mov_b32 m0, s16
	s_add_i32 s17, s22, 0xa000
	v_readlane_b32 s18, v252, 31
	global_load_lds_dwordx4 v[6:7], off
	v_lshl_add_u64 v[6:7], v[14:15], 0, s[0:1]
	s_mov_b32 m0, s17
	v_readlane_b32 s19, v252, 32
	global_load_lds_dwordx4 v[6:7], off
	s_add_i32 m0, s22, 0x1c000
	v_lshl_add_u64 v[6:7], s[18:19], 0, v[146:147]
	global_load_lds_dwordx4 v[6:7], off
	v_lshl_add_u64 v[6:7], s[18:19], 0, v[144:145]
	s_add_i32 m0, s22, 0x1e000
	v_lshl_or_b32 v162, v16, 2, s2
	global_load_lds_dwordx4 v[6:7], off
	v_lshlrev_b32_e32 v6, 17, v3
	v_and_b32_e32 v6, 0xfffc0000, v6
	v_lshl_add_u32 v4, v4, 14, v6
	v_and_b32_e32 v3, 1, v3
	v_lshl_or_b32 v3, v3, 6, v4
	v_lshl_add_u32 v148, v5, 1, v3
	v_lshlrev_b32_e32 v3, 17, v0
	v_and_b32_e32 v3, 0xfffc0000, v3
	s_waitcnt vmcnt(6)
	v_lshl_add_u32 v1, v1, 14, v3
	v_and_b32_e32 v0, 1, v0
	v_lshl_or_b32 v0, v0, 6, v1
	v_readlane_b32 s2, v252, 21
	v_mov_b32_e32 v149, v187
	v_lshl_add_u32 v150, v2, 1, v0
	v_mov_b32_e32 v151, v187
	s_mov_b32 s52, 0
	v_add_u32_e32 v163, 0, v17
	v_readlane_b32 s53, v252, 20
	s_mov_b32 s56, s2
	s_barrier
	v_readlane_b32 s3, v252, 22
	s_branch .LBB0_882

.LBB0_889:
	s_add_u32 s4, s12, 0xffe00080
	s_addc_u32 s20, s13, -1
	s_add_i32 s58, 0, 0x10000
	v_add_u32_e32 v124, s58, v161
	ds_read_b128 v[104:107], v124
	ds_read_b128 v[108:111], v124 offset:1024
	ds_read_b128 v[116:119], v124 offset:2048
	ds_read_b128 v[124:127], v124 offset:3072
	s_cmpk_eq_i32 vcc_hi, 0x7c
	s_cselect_b32 s25, s29, s20
	s_cselect_b32 s24, s57, s4
	s_cselect_b32 s21, s19, vcc_lo
	s_cselect_b32 s20, s68, s69
	v_lshl_add_u64 v[200:201], s[12:13], 0, v[148:149]
	s_add_i32 m0, s22, 0xc000
	ds_read_b128 v[152:155], v163
	ds_read_b128 v[156:159], v163 offset:1024
	ds_read_b128 v[164:167], v163 offset:2048
	ds_read_b128 v[168:171], v163 offset:3072
	ds_read_b128 v[172:175], v163 offset:4096
	ds_read_b128 v[176:179], v163 offset:5120
	ds_read_b128 v[180:183], v163 offset:6144
	ds_read_b128 v[196:199], v163 offset:7168
	global_load_lds_dwordx4 v[200:201], off
	v_lshl_add_u64 v[200:201], s[12:13], 0, v[150:151]
	s_add_i32 m0, s22, 0xe000
	s_nop 0
	global_load_lds_dwordx4 v[200:201], off
	v_add_u32_e32 v212, 0x14000, v161
	ds_read_b128 v[200:203], v212
	ds_read_b128 v[204:207], v212 offset:1024
	ds_read_b128 v[208:211], v212 offset:2048
	ds_read_b128 v[212:215], v212 offset:3072
	s_waitcnt vmcnt(8)
	s_waitcnt lgkmcnt(0)
	s_barrier
	s_setprio 1
	v_mfma_f32_16x16x32_bf16 v[140:143], v[104:107], v[152:155], v[140:143]
	v_mfma_f32_16x16x32_bf16 v[136:139], v[116:119], v[152:155], v[136:139]
	v_mfma_f32_16x16x32_bf16 v[120:123], v[104:107], v[164:167], v[120:123]
	v_mfma_f32_16x16x32_bf16 v[112:115], v[116:119], v[164:167], v[112:115]
	v_mfma_f32_16x16x32_bf16 v[92:95], v[104:107], v[172:175], v[92:95]
	v_mfma_f32_16x16x32_bf16 v[88:91], v[116:119], v[172:175], v[88:91]
	v_mfma_f32_16x16x32_bf16 v[76:79], v[104:107], v[180:183], v[76:79]
	v_mfma_f32_16x16x32_bf16 v[72:75], v[116:119], v[180:183], v[72:75]
	v_mfma_f32_16x16x32_bf16 v[140:143], v[108:111], v[156:159], v[140:143]
	v_mfma_f32_16x16x32_bf16 v[136:139], v[124:127], v[156:159], v[136:139]
	v_mfma_f32_16x16x32_bf16 v[120:123], v[108:111], v[168:171], v[120:123]
	v_mfma_f32_16x16x32_bf16 v[112:115], v[124:127], v[168:171], v[112:115]
	v_mfma_f32_16x16x32_bf16 v[92:95], v[108:111], v[176:179], v[92:95]
	v_mfma_f32_16x16x32_bf16 v[88:91], v[124:127], v[176:179], v[88:91]
	v_mfma_f32_16x16x32_bf16 v[76:79], v[108:111], v[196:199], v[76:79]
	v_mfma_f32_16x16x32_bf16 v[72:75], v[124:127], v[196:199], v[72:75]
	v_mfma_f32_16x16x32_bf16 v[132:135], v[200:203], v[152:155], v[132:135]
	v_mfma_f32_16x16x32_bf16 v[128:131], v[208:211], v[152:155], v[128:131]
	v_mfma_f32_16x16x32_bf16 v[100:103], v[200:203], v[164:167], v[100:103]
	v_mfma_f32_16x16x32_bf16 v[96:99], v[208:211], v[164:167], v[96:99]
	v_mfma_f32_16x16x32_bf16 v[84:87], v[200:203], v[172:175], v[84:87]
	v_mfma_f32_16x16x32_bf16 v[80:83], v[208:211], v[172:175], v[80:83]
	v_mfma_f32_16x16x32_bf16 v[68:71], v[200:203], v[180:183], v[68:71]
	v_mfma_f32_16x16x32_bf16 v[64:67], v[208:211], v[180:183], v[64:67]
	v_mfma_f32_16x16x32_bf16 v[132:135], v[204:207], v[156:159], v[132:135]
	v_mfma_f32_16x16x32_bf16 v[128:131], v[212:215], v[156:159], v[128:131]
	v_mfma_f32_16x16x32_bf16 v[100:103], v[204:207], v[168:171], v[100:103]
	v_mfma_f32_16x16x32_bf16 v[96:99], v[212:215], v[168:171], v[96:99]
	v_mfma_f32_16x16x32_bf16 v[84:87], v[204:207], v[176:179], v[84:87]
	v_mfma_f32_16x16x32_bf16 v[80:83], v[212:215], v[176:179], v[80:83]
	v_mfma_f32_16x16x32_bf16 v[68:71], v[204:207], v[196:199], v[68:71]
	v_mfma_f32_16x16x32_bf16 v[64:67], v[212:215], v[196:199], v[64:67]
	s_setprio 0
	s_barrier
	s_add_i32 s4, 0, 0x14000
	s_add_i32 s58, s58, s27
	v_lshl_add_u64 v[216:217], s[20:21], 0, v[146:147]
	s_mov_b32 m0, s58
	global_load_lds_dwordx4 v[216:217], off
	v_lshl_add_u64 v[218:219], s[20:21], 0, v[144:145]
	s_add_i32 m0, s58, 0x2000
	s_nop 0
	global_load_lds_dwordx4 v[218:219], off
	s_mov_b32 m0, s22
	v_lshl_add_u64 v[220:221], s[24:25], 0, v[146:147]
	ds_read_b128 v[152:155], v163 offset:16384
	ds_read_b128 v[156:159], v163 offset:17408
	ds_read_b128 v[164:167], v163 offset:18432
	ds_read_b128 v[168:171], v163 offset:19456
	ds_read_b128 v[172:175], v163 offset:20480
	ds_read_b128 v[176:179], v163 offset:21504
	ds_read_b128 v[180:183], v163 offset:22528
	ds_read_b128 v[196:199], v163 offset:23552
	global_load_lds_dwordx4 v[220:221], off
	v_lshl_add_u64 v[222:223], s[24:25], 0, v[144:145]
	s_mov_b32 m0, s23
	s_nop 0
	global_load_lds_dwordx4 v[222:223], off
	s_waitcnt vmcnt(6)
	s_waitcnt lgkmcnt(0)
	s_barrier
	s_setprio 1
	v_mfma_f32_16x16x32_bf16 v[60:63], v[104:107], v[152:155], v[60:63]
	v_mfma_f32_16x16x32_bf16 v[56:59], v[116:119], v[152:155], v[56:59]
	v_mfma_f32_16x16x32_bf16 v[44:47], v[104:107], v[164:167], v[44:47]
	v_mfma_f32_16x16x32_bf16 v[40:43], v[116:119], v[164:167], v[40:43]
	v_mfma_f32_16x16x32_bf16 v[28:31], v[104:107], v[172:175], v[28:31]
	v_mfma_f32_16x16x32_bf16 v[24:27], v[116:119], v[172:175], v[24:27]
	v_mfma_f32_16x16x32_bf16 v[12:15], v[104:107], v[180:183], v[12:15]
	v_mfma_f32_16x16x32_bf16 v[8:11], v[116:119], v[180:183], v[8:11]
	v_mfma_f32_16x16x32_bf16 v[60:63], v[108:111], v[156:159], v[60:63]
	v_mfma_f32_16x16x32_bf16 v[56:59], v[124:127], v[156:159], v[56:59]
	v_mfma_f32_16x16x32_bf16 v[44:47], v[108:111], v[168:171], v[44:47]
	v_mfma_f32_16x16x32_bf16 v[40:43], v[124:127], v[168:171], v[40:43]
	v_mfma_f32_16x16x32_bf16 v[28:31], v[108:111], v[176:179], v[28:31]
	v_mfma_f32_16x16x32_bf16 v[24:27], v[124:127], v[176:179], v[24:27]
	v_mfma_f32_16x16x32_bf16 v[12:15], v[108:111], v[196:199], v[12:15]
	v_mfma_f32_16x16x32_bf16 v[8:11], v[124:127], v[196:199], v[8:11]
	v_mfma_f32_16x16x32_bf16 v[52:55], v[200:203], v[152:155], v[52:55]
	v_mfma_f32_16x16x32_bf16 v[48:51], v[208:211], v[152:155], v[48:51]
	v_mfma_f32_16x16x32_bf16 v[36:39], v[200:203], v[164:167], v[36:39]
	v_mfma_f32_16x16x32_bf16 v[32:35], v[208:211], v[164:167], v[32:35]
	v_mfma_f32_16x16x32_bf16 v[20:23], v[200:203], v[172:175], v[20:23]
	v_mfma_f32_16x16x32_bf16 v[16:19], v[208:211], v[172:175], v[16:19]
	v_mfma_f32_16x16x32_bf16 v[4:7], v[200:203], v[180:183], v[4:7]
	v_mfma_f32_16x16x32_bf16 v[0:3], v[208:211], v[180:183], v[0:3]
	v_mfma_f32_16x16x32_bf16 v[52:55], v[204:207], v[156:159], v[52:55]
	v_mfma_f32_16x16x32_bf16 v[48:51], v[212:215], v[156:159], v[48:51]
	v_mfma_f32_16x16x32_bf16 v[36:39], v[204:207], v[168:171], v[36:39]
	v_mfma_f32_16x16x32_bf16 v[32:35], v[212:215], v[168:171], v[32:35]
	v_mfma_f32_16x16x32_bf16 v[20:23], v[204:207], v[176:179], v[20:23]
	v_mfma_f32_16x16x32_bf16 v[16:19], v[212:215], v[176:179], v[16:19]
	v_mfma_f32_16x16x32_bf16 v[4:7], v[204:207], v[196:199], v[4:7]
	v_mfma_f32_16x16x32_bf16 v[0:3], v[212:215], v[196:199], v[0:3]
	s_setprio 0
	s_barrier
	s_add_u32 s58, s20, 0x200000
	s_addc_u32 s59, s21, 0
	s_add_i32 s4, s4, s27
	v_lshl_add_u64 v[104:105], s[58:59], 0, v[146:147]
	s_mov_b32 m0, s4
	s_nop 0
	global_load_lds_dwordx4 v[104:105], off
	v_lshl_add_u64 v[104:105], s[58:59], 0, v[144:145]
	s_add_i32 m0, s4, 0x2000
	s_nop 0
	global_load_lds_dwordx4 v[104:105], off
	s_add_i32 s4, 0, 0x18000
	v_add_u32_e32 v124, s4, v161
	ds_read_b128 v[104:107], v124
	ds_read_b128 v[108:111], v124 offset:1024
	ds_read_b128 v[116:119], v124 offset:2048
	ds_read_b128 v[124:127], v124 offset:3072
	s_add_u32 s24, s24, 0x200000
	s_addc_u32 s25, s25, 0
	s_mov_b32 m0, s30
	v_lshl_add_u64 v[200:201], s[24:25], 0, v[146:147]
	ds_read_b128 v[152:155], v163 offset:32768
	ds_read_b128 v[156:159], v163 offset:33792
	ds_read_b128 v[164:167], v163 offset:34816
	ds_read_b128 v[168:171], v163 offset:35840
	ds_read_b128 v[172:175], v163 offset:36864
	ds_read_b128 v[176:179], v163 offset:37888
	ds_read_b128 v[180:183], v163 offset:38912
	ds_read_b128 v[196:199], v163 offset:39936
	global_load_lds_dwordx4 v[200:201], off
	v_lshl_add_u64 v[200:201], s[24:25], 0, v[144:145]
	s_mov_b32 m0, s31
	s_nop 0
	global_load_lds_dwordx4 v[200:201], off
	v_add_u32_e32 v212, 0x1c000, v161
	ds_read_b128 v[200:203], v212
	ds_read_b128 v[204:207], v212 offset:1024
	ds_read_b128 v[208:211], v212 offset:2048
	ds_read_b128 v[212:215], v212 offset:3072
	s_waitcnt vmcnt(8)
	s_waitcnt lgkmcnt(0)
	s_barrier
	s_setprio 1
	v_mfma_f32_16x16x32_bf16 v[140:143], v[104:107], v[152:155], v[140:143]
	v_mfma_f32_16x16x32_bf16 v[136:139], v[116:119], v[152:155], v[136:139]
	v_mfma_f32_16x16x32_bf16 v[120:123], v[104:107], v[164:167], v[120:123]
	v_mfma_f32_16x16x32_bf16 v[112:115], v[116:119], v[164:167], v[112:115]
	v_mfma_f32_16x16x32_bf16 v[92:95], v[104:107], v[172:175], v[92:95]
	v_mfma_f32_16x16x32_bf16 v[88:91], v[116:119], v[172:175], v[88:91]
	v_mfma_f32_16x16x32_bf16 v[76:79], v[104:107], v[180:183], v[76:79]
	v_mfma_f32_16x16x32_bf16 v[72:75], v[116:119], v[180:183], v[72:75]
	v_mfma_f32_16x16x32_bf16 v[140:143], v[108:111], v[156:159], v[140:143]
	v_mfma_f32_16x16x32_bf16 v[136:139], v[124:127], v[156:159], v[136:139]
	v_mfma_f32_16x16x32_bf16 v[120:123], v[108:111], v[168:171], v[120:123]
	v_mfma_f32_16x16x32_bf16 v[112:115], v[124:127], v[168:171], v[112:115]
	v_mfma_f32_16x16x32_bf16 v[92:95], v[108:111], v[176:179], v[92:95]
	v_mfma_f32_16x16x32_bf16 v[88:91], v[124:127], v[176:179], v[88:91]
	v_mfma_f32_16x16x32_bf16 v[76:79], v[108:111], v[196:199], v[76:79]
	v_mfma_f32_16x16x32_bf16 v[72:75], v[124:127], v[196:199], v[72:75]
	v_mfma_f32_16x16x32_bf16 v[132:135], v[200:203], v[152:155], v[132:135]
	v_mfma_f32_16x16x32_bf16 v[128:131], v[208:211], v[152:155], v[128:131]
	v_mfma_f32_16x16x32_bf16 v[100:103], v[200:203], v[164:167], v[100:103]
	v_mfma_f32_16x16x32_bf16 v[96:99], v[208:211], v[164:167], v[96:99]
	v_mfma_f32_16x16x32_bf16 v[84:87], v[200:203], v[172:175], v[84:87]
	v_mfma_f32_16x16x32_bf16 v[80:83], v[208:211], v[172:175], v[80:83]
	v_mfma_f32_16x16x32_bf16 v[68:71], v[200:203], v[180:183], v[68:71]
	v_mfma_f32_16x16x32_bf16 v[64:67], v[208:211], v[180:183], v[64:67]
	v_mfma_f32_16x16x32_bf16 v[132:135], v[204:207], v[156:159], v[132:135]
	v_mfma_f32_16x16x32_bf16 v[128:131], v[212:215], v[156:159], v[128:131]
	v_mfma_f32_16x16x32_bf16 v[100:103], v[204:207], v[168:171], v[100:103]
	v_mfma_f32_16x16x32_bf16 v[96:99], v[212:215], v[168:171], v[96:99]
	v_mfma_f32_16x16x32_bf16 v[84:87], v[204:207], v[176:179], v[84:87]
	v_mfma_f32_16x16x32_bf16 v[80:83], v[212:215], v[176:179], v[80:83]
	v_mfma_f32_16x16x32_bf16 v[68:71], v[204:207], v[196:199], v[68:71]
	v_mfma_f32_16x16x32_bf16 v[64:67], v[212:215], v[196:199], v[64:67]
	s_setprio 0
	s_barrier
	s_add_i32 s24, 0, 0x1c000
	s_add_i32 s4, s4, s27
	v_lshl_add_u64 v[216:217], v[216:217], 0, s[0:1]
	s_mov_b32 m0, s4
	global_load_lds_dwordx4 v[216:217], off
	v_lshl_add_u64 v[216:217], v[218:219], 0, s[0:1]
	s_add_i32 m0, s4, 0x2000
	s_nop 0
	global_load_lds_dwordx4 v[216:217], off
	s_mov_b32 m0, s16
	v_lshl_add_u64 v[216:217], v[220:221], 0, s[0:1]
	ds_read_b128 v[152:155], v163 offset:49152
	ds_read_b128 v[156:159], v163 offset:50176
	ds_read_b128 v[164:167], v163 offset:51200
	ds_read_b128 v[168:171], v163 offset:52224
	ds_read_b128 v[172:175], v163 offset:53248
	ds_read_b128 v[176:179], v163 offset:54272
	ds_read_b128 v[180:183], v163 offset:55296
	ds_read_b128 v[196:199], v163 offset:56320
	global_load_lds_dwordx4 v[216:217], off
	v_lshl_add_u64 v[216:217], v[222:223], 0, s[0:1]
	s_mov_b32 m0, s17
	s_nop 0
	global_load_lds_dwordx4 v[216:217], off
	s_add_u32 s20, s20, 0x200080
	s_addc_u32 s21, s21, 0
	s_add_i32 s4, s24, s27
	v_lshl_add_u64 v[216:217], s[20:21], 0, v[146:147]
	s_mov_b32 m0, s4
	s_nop 0
	global_load_lds_dwordx4 v[216:217], off
	v_lshl_add_u64 v[216:217], s[20:21], 0, v[144:145]
	s_add_i32 m0, s4, 0x2000
	s_nop 0
	global_load_lds_dwordx4 v[216:217], off
	s_waitcnt vmcnt(8)
	s_waitcnt lgkmcnt(0)
	s_barrier
	s_setprio 1
	v_mfma_f32_16x16x32_bf16 v[60:63], v[104:107], v[152:155], v[60:63]
	v_mfma_f32_16x16x32_bf16 v[56:59], v[116:119], v[152:155], v[56:59]
	v_mfma_f32_16x16x32_bf16 v[44:47], v[104:107], v[164:167], v[44:47]
	v_mfma_f32_16x16x32_bf16 v[40:43], v[116:119], v[164:167], v[40:43]
	v_mfma_f32_16x16x32_bf16 v[28:31], v[104:107], v[172:175], v[28:31]
	v_mfma_f32_16x16x32_bf16 v[24:27], v[116:119], v[172:175], v[24:27]
	v_mfma_f32_16x16x32_bf16 v[12:15], v[104:107], v[180:183], v[12:15]
	v_mfma_f32_16x16x32_bf16 v[8:11], v[116:119], v[180:183], v[8:11]
	v_mfma_f32_16x16x32_bf16 v[60:63], v[108:111], v[156:159], v[60:63]
	v_mfma_f32_16x16x32_bf16 v[56:59], v[124:127], v[156:159], v[56:59]
	v_mfma_f32_16x16x32_bf16 v[44:47], v[108:111], v[168:171], v[44:47]
	v_mfma_f32_16x16x32_bf16 v[40:43], v[124:127], v[168:171], v[40:43]
	v_mfma_f32_16x16x32_bf16 v[28:31], v[108:111], v[176:179], v[28:31]
	v_mfma_f32_16x16x32_bf16 v[24:27], v[124:127], v[176:179], v[24:27]
	v_mfma_f32_16x16x32_bf16 v[12:15], v[108:111], v[196:199], v[12:15]
	v_mfma_f32_16x16x32_bf16 v[8:11], v[124:127], v[196:199], v[8:11]
	v_mfma_f32_16x16x32_bf16 v[52:55], v[200:203], v[152:155], v[52:55]
	v_mfma_f32_16x16x32_bf16 v[48:51], v[208:211], v[152:155], v[48:51]
	v_mfma_f32_16x16x32_bf16 v[36:39], v[200:203], v[164:167], v[36:39]
	v_mfma_f32_16x16x32_bf16 v[32:35], v[208:211], v[164:167], v[32:35]
	v_mfma_f32_16x16x32_bf16 v[20:23], v[200:203], v[172:175], v[20:23]
	v_mfma_f32_16x16x32_bf16 v[16:19], v[208:211], v[172:175], v[16:19]
	v_mfma_f32_16x16x32_bf16 v[4:7], v[200:203], v[180:183], v[4:7]
	v_mfma_f32_16x16x32_bf16 v[0:3], v[208:211], v[180:183], v[0:3]
	v_mfma_f32_16x16x32_bf16 v[52:55], v[204:207], v[156:159], v[52:55]
	v_mfma_f32_16x16x32_bf16 v[48:51], v[212:215], v[156:159], v[48:51]
	v_mfma_f32_16x16x32_bf16 v[36:39], v[204:207], v[168:171], v[36:39]
	v_mfma_f32_16x16x32_bf16 v[32:35], v[212:215], v[168:171], v[32:35]
	v_mfma_f32_16x16x32_bf16 v[20:23], v[204:207], v[176:179], v[20:23]
	v_mfma_f32_16x16x32_bf16 v[16:19], v[212:215], v[176:179], v[16:19]
	v_mfma_f32_16x16x32_bf16 v[4:7], v[204:207], v[196:199], v[4:7]
	v_mfma_f32_16x16x32_bf16 v[0:3], v[212:215], v[196:199], v[0:3]
	s_setprio 0
	s_add_i32 vcc_hi, vcc_hi, 2
	s_add_u32 s12, s12, 0x100
	s_addc_u32 s13, s13, 0
	s_add_u32 s69, s69, 0x100
	s_addc_u32 vcc_lo, vcc_lo, 0
	s_cmpk_gt_u32 vcc_hi, 0x7d
	s_barrier
	s_cbranch_scc0 .LBB0_889
	s_lshl_b32 s4, s56, 8
	s_add_i32 s4, s4, s35
	s_min_i32 s12, s4, 0x4000
	s_ashr_i32 s12, s12, 11
	s_mul_hi_i32 s13, s12, 0xc000
	s_mul_i32 s12, s12, 0xc000
	v_lshl_or_b32 v154, s53, 8, v162
	s_add_u32 s12, s8, s12
	s_addc_u32 s13, s9, s13
	v_ashrrev_i32_e32 v155, 31, v154
	v_lshl_add_u64 v[104:105], v[154:155], 2, s[12:13]
	global_load_dwordx4 v[124:127], v[104:105], off
	global_load_dwordx4 v[116:119], v[104:105], off offset:64
	global_load_dwordx4 v[108:111], v[104:105], off offset:512
	s_nop 0
	global_load_dwordx4 v[104:107], v[104:105], off offset:576
	v_add_u32_e32 v152, s4, v160
	s_movk_i32 s4, 0x3fff
	v_cmp_lt_i32_e32 vcc, s4, v152
	s_and_saveexec_b64 s[12:13], vcc
	s_xor_b64 s[12:13], exec, s[12:13]
	v_add_u32_e32 v186, 0xffffc000, v152
	v_lshlrev_b64 v[156:157], 13, v[186:187]
	v_mov_b32_e32 v153, v187
	v_lshl_add_u64 v[158:159], s[10:11], 0, v[156:157]
	v_lshlrev_b64 v[156:157], 13, v[152:153]
	s_andn2_saveexec_b64 s[12:13], s[12:13]
	v_ashrrev_i32_e32 v153, 31, v152
	v_lshlrev_b64 v[156:157], 13, v[152:153]
	v_lshl_add_u64 v[158:159], s[66:67], 0, v[156:157]
	s_or_b64 exec, exec, s[12:13]
	v_lshlrev_b64 v[154:155], 2, v[154:155]
	v_lshl_add_u64 v[158:159], v[158:159], 0, v[154:155]
	global_load_dwordx4 v[164:167], v[158:159], off
	v_lshl_add_u64 v[156:157], s[66:67], 0, v[156:157]
	v_lshl_add_u64 v[156:157], v[156:157], 0, v[154:155]
	s_movk_i32 s4, 0x3fef
	v_cmp_lt_i32_e32 vcc, s4, v152
	s_waitcnt vmcnt(0)
	v_pk_fma_f32 v[142:143], v[142:143], v[126:127], v[166:167]
	v_pk_fma_f32 v[140:141], v[140:141], v[124:125], v[164:165]
	global_store_dwordx4 v[156:157], v[140:143], off
	global_load_dwordx4 v[140:143], v[158:159], off offset:64
	s_waitcnt vmcnt(0)
	v_pk_fma_f32 v[138:139], v[138:139], v[118:119], v[142:143]
	v_pk_fma_f32 v[136:137], v[136:137], v[116:117], v[140:141]
	global_store_dwordx4 v[156:157], v[136:139], off offset:64
	global_load_dwordx4 v[136:139], v[158:159], off offset:512
	s_waitcnt vmcnt(0)
	v_pk_fma_f32 v[134:135], v[134:135], v[110:111], v[138:139]
	v_pk_fma_f32 v[132:133], v[132:133], v[108:109], v[136:137]
	global_store_dwordx4 v[156:157], v[132:135], off offset:512
	global_load_dwordx4 v[134:137], v[158:159], off offset:576
	s_waitcnt vmcnt(0)
	v_pk_fma_f32 v[130:131], v[130:131], v[106:107], v[136:137]
	v_or_b32_e32 v132, 16, v152
	v_pk_fma_f32 v[128:129], v[128:129], v[104:105], v[134:135]
	global_store_dwordx4 v[156:157], v[128:131], off offset:576
	s_and_saveexec_b64 s[12:13], vcc
	s_xor_b64 s[12:13], exec, s[12:13]
	v_add_u32_e32 v186, 0xffffc010, v152
	v_lshlrev_b64 v[128:129], 13, v[186:187]
	v_mov_b32_e32 v133, v187
	v_lshl_add_u64 v[130:131], s[10:11], 0, v[128:129]
	v_lshlrev_b64 v[128:129], 13, v[132:133]
	s_andn2_saveexec_b64 s[12:13], s[12:13]
	v_ashrrev_i32_e32 v133, 31, v132
	v_lshlrev_b64 v[128:129], 13, v[132:133]
	v_lshl_add_u64 v[130:131], s[66:67], 0, v[128:129]
	s_or_b64 exec, exec, s[12:13]
	v_lshl_add_u64 v[134:135], v[130:131], 0, v[154:155]
	global_load_dwordx4 v[130:133], v[134:135], off
	v_lshl_add_u64 v[128:129], s[66:67], 0, v[128:129]
	v_lshl_add_u64 v[128:129], v[128:129], 0, v[154:155]
	s_movk_i32 s4, 0x3fdf
	v_cmp_lt_i32_e32 vcc, s4, v152
	s_waitcnt vmcnt(0)
	v_pk_fma_f32 v[122:123], v[122:123], v[126:127], v[132:133]
	v_pk_fma_f32 v[120:121], v[120:121], v[124:125], v[130:131]
	global_store_dwordx4 v[128:129], v[120:123], off
	global_load_dwordx4 v[120:123], v[134:135], off offset:64
	s_waitcnt vmcnt(0)
	v_pk_fma_f32 v[114:115], v[114:115], v[118:119], v[122:123]
	v_pk_fma_f32 v[112:113], v[112:113], v[116:117], v[120:121]
	global_store_dwordx4 v[128:129], v[112:115], off offset:64
	global_load_dwordx4 v[112:115], v[134:135], off offset:512
	s_waitcnt vmcnt(0)
	v_pk_fma_f32 v[102:103], v[102:103], v[110:111], v[114:115]
	v_pk_fma_f32 v[100:101], v[100:101], v[108:109], v[112:113]
	global_store_dwordx4 v[128:129], v[100:103], off offset:512
	global_load_dwordx4 v[112:115], v[134:135], off offset:576
	s_waitcnt vmcnt(0)
	v_pk_fma_f32 v[98:99], v[98:99], v[106:107], v[114:115]
	v_or_b32_e32 v100, 32, v152
	v_pk_fma_f32 v[96:97], v[96:97], v[104:105], v[112:113]
	global_store_dwordx4 v[128:129], v[96:99], off offset:576
	s_and_saveexec_b64 s[12:13], vcc
	s_xor_b64 s[12:13], exec, s[12:13]
	v_add_u32_e32 v186, 0xffffc020, v152
	v_lshlrev_b64 v[96:97], 13, v[186:187]
	v_mov_b32_e32 v101, v187
	v_lshl_add_u64 v[98:99], s[10:11], 0, v[96:97]
	v_lshlrev_b64 v[96:97], 13, v[100:101]
	s_andn2_saveexec_b64 s[12:13], s[12:13]
	v_ashrrev_i32_e32 v101, 31, v100
	v_lshlrev_b64 v[96:97], 13, v[100:101]
	v_lshl_add_u64 v[98:99], s[66:67], 0, v[96:97]
	s_or_b64 exec, exec, s[12:13]
	v_lshl_add_u64 v[102:103], v[98:99], 0, v[154:155]
	global_load_dwordx4 v[98:101], v[102:103], off
	v_lshl_add_u64 v[96:97], s[66:67], 0, v[96:97]
	v_lshl_add_u64 v[96:97], v[96:97], 0, v[154:155]
	s_movk_i32 s4, 0x3fcf
	v_cmp_lt_i32_e32 vcc, s4, v152
	s_waitcnt vmcnt(0)
	v_pk_fma_f32 v[94:95], v[94:95], v[126:127], v[100:101]
	v_pk_fma_f32 v[92:93], v[92:93], v[124:125], v[98:99]
	global_store_dwordx4 v[96:97], v[92:95], off
	global_load_dwordx4 v[92:95], v[102:103], off offset:64
	s_waitcnt vmcnt(0)
	v_pk_fma_f32 v[90:91], v[90:91], v[118:119], v[94:95]
	v_pk_fma_f32 v[88:89], v[88:89], v[116:117], v[92:93]
	global_store_dwordx4 v[96:97], v[88:91], off offset:64
	global_load_dwordx4 v[88:91], v[102:103], off offset:512
	s_waitcnt vmcnt(0)
	v_pk_fma_f32 v[86:87], v[86:87], v[110:111], v[90:91]
	v_pk_fma_f32 v[84:85], v[84:85], v[108:109], v[88:89]
	global_store_dwordx4 v[96:97], v[84:87], off offset:512
	global_load_dwordx4 v[86:89], v[102:103], off offset:576
	s_waitcnt vmcnt(0)
	v_pk_fma_f32 v[82:83], v[82:83], v[106:107], v[88:89]
	v_or_b32_e32 v84, 48, v152
	v_pk_fma_f32 v[80:81], v[80:81], v[104:105], v[86:87]
	global_store_dwordx4 v[96:97], v[80:83], off offset:576
	s_and_saveexec_b64 s[12:13], vcc
	s_xor_b64 s[12:13], exec, s[12:13]
	v_add_u32_e32 v186, 0xffffc030, v152
	v_lshlrev_b64 v[80:81], 13, v[186:187]
	v_mov_b32_e32 v85, v187
	v_lshl_add_u64 v[82:83], s[10:11], 0, v[80:81]
	v_lshlrev_b64 v[80:81], 13, v[84:85]
	s_andn2_saveexec_b64 s[12:13], s[12:13]
	v_ashrrev_i32_e32 v85, 31, v84
	v_lshlrev_b64 v[80:81], 13, v[84:85]
	v_lshl_add_u64 v[82:83], s[66:67], 0, v[80:81]
	s_or_b64 exec, exec, s[12:13]
	v_lshl_add_u64 v[86:87], v[82:83], 0, v[154:155]
	global_load_dwordx4 v[82:85], v[86:87], off
	v_lshl_add_u64 v[80:81], s[66:67], 0, v[80:81]
	v_lshl_add_u64 v[80:81], v[80:81], 0, v[154:155]
	s_movk_i32 s4, 0x3f7f
	v_cmp_lt_i32_e32 vcc, s4, v152
	s_waitcnt vmcnt(0)
	v_pk_fma_f32 v[78:79], v[78:79], v[126:127], v[84:85]
	v_pk_fma_f32 v[76:77], v[76:77], v[124:125], v[82:83]
	global_store_dwordx4 v[80:81], v[76:79], off
	global_load_dwordx4 v[76:79], v[86:87], off offset:64
	s_waitcnt vmcnt(0)
	v_pk_fma_f32 v[74:75], v[74:75], v[118:119], v[78:79]
	v_pk_fma_f32 v[72:73], v[72:73], v[116:117], v[76:77]
	global_store_dwordx4 v[80:81], v[72:75], off offset:64
	global_load_dwordx4 v[72:75], v[86:87], off offset:512
	s_waitcnt vmcnt(0)
	v_pk_fma_f32 v[70:71], v[70:71], v[110:111], v[74:75]
	v_pk_fma_f32 v[68:69], v[68:69], v[108:109], v[72:73]
	global_store_dwordx4 v[80:81], v[68:71], off offset:512
	global_load_dwordx4 v[70:73], v[86:87], off offset:576
	s_waitcnt vmcnt(0)
	v_pk_fma_f32 v[66:67], v[66:67], v[106:107], v[72:73]
	v_add_u32_e32 v68, 0x80, v152
	v_pk_fma_f32 v[64:65], v[64:65], v[104:105], v[70:71]
	global_store_dwordx4 v[80:81], v[64:67], off offset:576
	s_and_saveexec_b64 s[12:13], vcc
	s_xor_b64 s[12:13], exec, s[12:13]
	v_add_u32_e32 v186, 0xffffc080, v152
	v_lshlrev_b64 v[64:65], 13, v[186:187]
	v_mov_b32_e32 v69, v187
	v_lshl_add_u64 v[66:67], s[10:11], 0, v[64:65]
	v_lshlrev_b64 v[64:65], 13, v[68:69]
	s_andn2_saveexec_b64 s[12:13], s[12:13]
	v_ashrrev_i32_e32 v69, 31, v68
	v_lshlrev_b64 v[64:65], 13, v[68:69]
	v_lshl_add_u64 v[66:67], s[66:67], 0, v[64:65]
	s_or_b64 exec, exec, s[12:13]
	v_lshl_add_u64 v[70:71], v[66:67], 0, v[154:155]
	global_load_dwordx4 v[66:69], v[70:71], off
	v_lshl_add_u64 v[64:65], s[66:67], 0, v[64:65]
	v_lshl_add_u64 v[64:65], v[64:65], 0, v[154:155]
	s_movk_i32 s4, 0x3f6f
	v_cmp_lt_i32_e32 vcc, s4, v152
	s_waitcnt vmcnt(0)
	v_pk_fma_f32 v[62:63], v[62:63], v[126:127], v[68:69]
	v_pk_fma_f32 v[60:61], v[60:61], v[124:125], v[66:67]
	global_store_dwordx4 v[64:65], v[60:63], off
	global_load_dwordx4 v[60:63], v[70:71], off offset:64
	s_waitcnt vmcnt(0)
	v_pk_fma_f32 v[58:59], v[58:59], v[118:119], v[62:63]
	v_pk_fma_f32 v[56:57], v[56:57], v[116:117], v[60:61]
	global_store_dwordx4 v[64:65], v[56:59], off offset:64
	global_load_dwordx4 v[56:59], v[70:71], off offset:512
	s_waitcnt vmcnt(0)
	v_pk_fma_f32 v[54:55], v[54:55], v[110:111], v[58:59]
	v_pk_fma_f32 v[52:53], v[52:53], v[108:109], v[56:57]
	global_store_dwordx4 v[64:65], v[52:55], off offset:512
	global_load_dwordx4 v[54:57], v[70:71], off offset:576
	s_waitcnt vmcnt(0)
	v_pk_fma_f32 v[50:51], v[50:51], v[106:107], v[56:57]
	v_add_u32_e32 v52, 0x90, v152
	v_pk_fma_f32 v[48:49], v[48:49], v[104:105], v[54:55]
	global_store_dwordx4 v[64:65], v[48:51], off offset:576
	s_and_saveexec_b64 s[12:13], vcc
	s_xor_b64 s[12:13], exec, s[12:13]
	v_add_u32_e32 v186, 0xffffc090, v152
	v_lshlrev_b64 v[48:49], 13, v[186:187]
	v_mov_b32_e32 v53, v187
	v_lshl_add_u64 v[50:51], s[10:11], 0, v[48:49]
	v_lshlrev_b64 v[48:49], 13, v[52:53]
	s_andn2_saveexec_b64 s[12:13], s[12:13]
	v_ashrrev_i32_e32 v53, 31, v52
	v_lshlrev_b64 v[48:49], 13, v[52:53]
	v_lshl_add_u64 v[50:51], s[66:67], 0, v[48:49]
	s_or_b64 exec, exec, s[12:13]
	v_lshl_add_u64 v[54:55], v[50:51], 0, v[154:155]
	global_load_dwordx4 v[50:53], v[54:55], off
	v_lshl_add_u64 v[48:49], s[66:67], 0, v[48:49]
	v_lshl_add_u64 v[48:49], v[48:49], 0, v[154:155]
	s_movk_i32 s4, 0x3f5f
	v_cmp_lt_i32_e32 vcc, s4, v152
	s_waitcnt vmcnt(0)
	v_pk_fma_f32 v[46:47], v[46:47], v[126:127], v[52:53]
	v_pk_fma_f32 v[44:45], v[44:45], v[124:125], v[50:51]
	global_store_dwordx4 v[48:49], v[44:47], off
	global_load_dwordx4 v[44:47], v[54:55], off offset:64
	s_waitcnt vmcnt(0)
	v_pk_fma_f32 v[42:43], v[42:43], v[118:119], v[46:47]
	v_pk_fma_f32 v[40:41], v[40:41], v[116:117], v[44:45]
	global_store_dwordx4 v[48:49], v[40:43], off offset:64
	global_load_dwordx4 v[40:43], v[54:55], off offset:512
	s_waitcnt vmcnt(0)
	v_pk_fma_f32 v[38:39], v[38:39], v[110:111], v[42:43]
	v_pk_fma_f32 v[36:37], v[36:37], v[108:109], v[40:41]
	global_store_dwordx4 v[48:49], v[36:39], off offset:512
	global_load_dwordx4 v[38:41], v[54:55], off offset:576
	s_waitcnt vmcnt(0)
	v_pk_fma_f32 v[34:35], v[34:35], v[106:107], v[40:41]
	v_add_u32_e32 v36, 0xa0, v152
	v_pk_fma_f32 v[32:33], v[32:33], v[104:105], v[38:39]
	global_store_dwordx4 v[48:49], v[32:35], off offset:576
	s_and_saveexec_b64 s[12:13], vcc
	s_xor_b64 s[12:13], exec, s[12:13]
	v_add_u32_e32 v186, 0xffffc0a0, v152
	v_lshlrev_b64 v[32:33], 13, v[186:187]
	v_mov_b32_e32 v37, v187
	v_lshl_add_u64 v[34:35], s[10:11], 0, v[32:33]
	v_lshlrev_b64 v[32:33], 13, v[36:37]
	s_andn2_saveexec_b64 s[12:13], s[12:13]
	v_ashrrev_i32_e32 v37, 31, v36
	v_lshlrev_b64 v[32:33], 13, v[36:37]
	v_lshl_add_u64 v[34:35], s[66:67], 0, v[32:33]
	s_or_b64 exec, exec, s[12:13]
	v_lshl_add_u64 v[38:39], v[34:35], 0, v[154:155]
	global_load_dwordx4 v[34:37], v[38:39], off
	v_lshl_add_u64 v[32:33], s[66:67], 0, v[32:33]
	v_lshl_add_u64 v[32:33], v[32:33], 0, v[154:155]
	s_movk_i32 s4, 0x3f4f
	v_cmp_lt_i32_e32 vcc, s4, v152
	s_waitcnt vmcnt(0)
	v_pk_fma_f32 v[30:31], v[30:31], v[126:127], v[36:37]
	v_pk_fma_f32 v[28:29], v[28:29], v[124:125], v[34:35]
	global_store_dwordx4 v[32:33], v[28:31], off
	global_load_dwordx4 v[28:31], v[38:39], off offset:64
	s_waitcnt vmcnt(0)
	v_pk_fma_f32 v[26:27], v[26:27], v[118:119], v[30:31]
	v_pk_fma_f32 v[24:25], v[24:25], v[116:117], v[28:29]
	global_store_dwordx4 v[32:33], v[24:27], off offset:64
	global_load_dwordx4 v[24:27], v[38:39], off offset:512
	s_waitcnt vmcnt(0)
	v_pk_fma_f32 v[22:23], v[22:23], v[110:111], v[26:27]
	v_pk_fma_f32 v[20:21], v[20:21], v[108:109], v[24:25]
	global_store_dwordx4 v[32:33], v[20:23], off offset:512
	global_load_dwordx4 v[22:25], v[38:39], off offset:576
	s_waitcnt vmcnt(0)
	v_pk_fma_f32 v[18:19], v[18:19], v[106:107], v[24:25]
	v_add_u32_e32 v20, 0xb0, v152
	v_pk_fma_f32 v[16:17], v[16:17], v[104:105], v[22:23]
	global_store_dwordx4 v[32:33], v[16:19], off offset:576
	s_and_saveexec_b64 s[12:13], vcc
	s_xor_b64 s[12:13], exec, s[12:13]
	v_add_u32_e32 v186, 0xffffc0b0, v152
	v_lshlrev_b64 v[16:17], 13, v[186:187]
	v_mov_b32_e32 v21, v187
	v_lshl_add_u64 v[16:17], s[10:11], 0, v[16:17]
	v_lshlrev_b64 v[18:19], 13, v[20:21]
	s_andn2_saveexec_b64 s[12:13], s[12:13]
	s_cbranch_execz .LBB0_881
	v_ashrrev_i32_e32 v21, 31, v20
	v_lshlrev_b64 v[18:19], 13, v[20:21]
	v_lshl_add_u64 v[16:17], s[66:67], 0, v[18:19]
	s_branch .LBB0_881

.LBB0_930:
	v_readlane_b32 s24, v252, 29
	v_readlane_b32 s25, v252, 30
	v_mov_b32_e32 v129, v187
	v_readlane_b32 s12, v252, 25
	v_lshl_add_u64 v[8:9], s[24:25], 0, v[186:187]
	v_lshl_add_u64 v[10:11], s[24:25], 0, v[128:129]
	v_readlane_b32 s13, v252, 26
	s_add_i32 m0, s23, 0x18000
	v_lshl_add_u64 v[8:9], v[8:9], 0, s[0:1]
	v_lshl_add_u64 v[12:13], s[12:13], 0, v[186:187]
	s_waitcnt vmcnt(2)
	s_barrier
	global_load_lds_dwordx4 v[8:9], off
	v_lshl_add_u64 v[8:9], v[10:11], 0, s[0:1]
	s_add_i32 m0, s23, 0x1a000
	s_add_i32 s53, s23, 0x8000
	v_lshl_add_u64 v[14:15], s[12:13], 0, v[128:129]
	global_load_lds_dwordx4 v[8:9], off
	v_lshl_add_u64 v[8:9], v[12:13], 0, s[0:1]
	s_mov_b32 m0, s53
	s_add_i32 s68, s23, 0xa000
	v_readlane_b32 s18, v252, 31
	global_load_lds_dwordx4 v[8:9], off
	v_lshl_add_u64 v[8:9], v[14:15], 0, s[0:1]
	s_mov_b32 m0, s68
	v_readlane_b32 s19, v252, 32
	global_load_lds_dwordx4 v[8:9], off
	s_add_i32 m0, s23, 0x1c000
	v_lshl_add_u64 v[8:9], s[18:19], 0, v[186:187]
	global_load_lds_dwordx4 v[8:9], off
	v_lshl_add_u64 v[8:9], s[18:19], 0, v[128:129]
	s_add_i32 m0, s23, 0x1e000
	v_bfe_u32 v160, v1, 4, 2
	global_load_lds_dwordx4 v[8:9], off
	s_and_b32 s22, s2, 3
	v_and_b32_e32 v234, 15, v1
	s_lshl_b32 s2, s3, 6
	v_lshlrev_b32_e32 v7, 4, v160
	v_lshlrev_b32_e32 v1, 2, v1
	v_writelane_b32 v252, s2, 38
	v_or_b32_e32 v233, s2, v234
	v_lshl_or_b32 v7, v234, 6, v7
	s_lshl_b32 s2, s3, 13
	v_and_b32_e32 v1, 32, v1
	v_bitop3_b32 v8, v7, s2, v1 bitop3:0xde
	s_lshl_b32 s2, s22, 12
	v_bitop3_b32 v138, v7, s2, v1 bitop3:0xde
	v_lshlrev_b32_e32 v1, 17, v4
	v_and_b32_e32 v1, 0xfffc0000, v1
	v_lshl_add_u32 v1, v5, 14, v1
	v_and_b32_e32 v4, 1, v4
	v_lshl_or_b32 v1, v4, 6, v1
	v_lshl_add_u32 v130, v6, 1, v1
	v_lshlrev_b32_e32 v1, 17, v0
	v_and_b32_e32 v1, 0xfffc0000, v1
	v_lshl_add_u32 v1, v2, 14, v1
	v_and_b32_e32 v0, 1, v0
	v_lshl_or_b32 v0, v0, 6, v1
	v_readlane_b32 s2, v252, 20
	s_waitcnt vmcnt(6)
	v_lshl_add_u32 v132, v3, 1, v0
	v_mov_b32_e32 v2, v187
	v_mov_b32_e32 v3, v187
	s_mov_b32 s18, s2
	v_readlane_b32 s2, v252, 21
	v_mov_b32_e32 v0, v187
	v_mov_b32_e32 v1, v187
	v_add_u32_e32 v139, 0, v8
	v_mov_b64_e32 v[6:7], v[2:3]
	v_mov_b64_e32 v[14:15], v[2:3]
	v_mov_b64_e32 v[22:23], v[2:3]
	v_mov_b64_e32 v[30:31], v[2:3]
	v_mov_b64_e32 v[38:39], v[2:3]
	v_mov_b64_e32 v[50:51], v[2:3]
	v_mov_b64_e32 v[54:55], v[2:3]
	v_mov_b64_e32 v[10:11], v[2:3]
	v_mov_b64_e32 v[18:19], v[2:3]
	v_mov_b64_e32 v[26:27], v[2:3]
	v_mov_b64_e32 v[34:35], v[2:3]
	v_mov_b64_e32 v[42:43], v[2:3]
	v_mov_b64_e32 v[46:47], v[2:3]
	v_mov_b64_e32 v[58:59], v[2:3]
	v_mov_b64_e32 v[62:63], v[2:3]
	v_mov_b64_e32 v[66:67], v[2:3]
	v_mov_b64_e32 v[70:71], v[2:3]
	v_mov_b64_e32 v[82:83], v[2:3]
	v_mov_b64_e32 v[86:87], v[2:3]
	v_mov_b64_e32 v[98:99], v[2:3]
	v_mov_b64_e32 v[102:103], v[2:3]
	v_mov_b64_e32 v[114:115], v[2:3]
	v_mov_b64_e32 v[118:119], v[2:3]
	v_mov_b64_e32 v[74:75], v[2:3]
	v_mov_b64_e32 v[78:79], v[2:3]
	v_mov_b64_e32 v[90:91], v[2:3]
	v_mov_b64_e32 v[94:95], v[2:3]
	v_mov_b64_e32 v[106:107], v[2:3]
	v_mov_b64_e32 v[110:111], v[2:3]
	v_mov_b64_e32 v[122:123], v[2:3]
	v_mov_b64_e32 v[126:127], v[2:3]
	v_readlane_b32 s3, v252, 22
	v_mov_b32_e32 v131, v187
	v_mov_b32_e32 v133, v187
	s_mov_b32 s69, 0
	v_mov_b64_e32 v[4:5], v[0:1]
	v_mov_b64_e32 v[12:13], v[0:1]
	v_mov_b64_e32 v[20:21], v[0:1]
	v_mov_b64_e32 v[28:29], v[0:1]
	v_mov_b64_e32 v[36:37], v[0:1]
	v_mov_b64_e32 v[48:49], v[0:1]
	v_mov_b64_e32 v[52:53], v[0:1]
	v_mov_b64_e32 v[8:9], v[0:1]
	v_mov_b64_e32 v[16:17], v[0:1]
	v_mov_b64_e32 v[24:25], v[0:1]
	v_mov_b64_e32 v[32:33], v[0:1]
	v_mov_b64_e32 v[40:41], v[0:1]
	v_mov_b64_e32 v[44:45], v[0:1]
	v_mov_b64_e32 v[56:57], v[0:1]
	v_mov_b64_e32 v[60:61], v[0:1]
	v_mov_b64_e32 v[64:65], v[0:1]
	v_mov_b64_e32 v[68:69], v[0:1]
	v_mov_b64_e32 v[80:81], v[0:1]
	v_mov_b64_e32 v[84:85], v[0:1]
	v_mov_b64_e32 v[96:97], v[0:1]
	v_mov_b64_e32 v[100:101], v[0:1]
	v_mov_b64_e32 v[112:113], v[0:1]
	v_mov_b64_e32 v[116:117], v[0:1]
	v_mov_b64_e32 v[72:73], v[0:1]
	v_mov_b64_e32 v[76:77], v[0:1]
	v_mov_b64_e32 v[88:89], v[0:1]
	v_mov_b64_e32 v[92:93], v[0:1]
	v_mov_b64_e32 v[104:105], v[0:1]
	v_mov_b64_e32 v[108:109], v[0:1]
	v_mov_b64_e32 v[120:121], v[0:1]
	v_mov_b64_e32 v[124:125], v[0:1]
	s_mov_b32 s56, s2
	s_mov_b64 s[2:3], s[12:13]
	s_barrier
	s_branch .LBB0_933

.LBB0_940:
	s_add_u32 s24, s2, vcc_lo
	s_addc_u32 s25, s3, vcc_hi
	s_add_u32 s24, s24, 0x100
	s_addc_u32 s25, s25, 0
	s_add_u32 s61, s19, vcc_lo
	s_addc_u32 s62, s4, vcc_hi
	s_add_i32 s63, 0, 0x10000
	v_add_u32_e32 v152, s63, v138
	ds_read_b128 v[140:143], v152
	ds_read_b128 v[144:147], v152 offset:1024
	ds_read_b128 v[148:151], v152 offset:2048
	ds_read_b128 v[152:155], v152 offset:3072
	s_cmpk_eq_i32 vcc_lo, 0x3f00
	s_cselect_b32 s27, s39, s25
	s_cselect_b32 s26, s58, s24
	s_cselect_b32 s25, s29, s62
	s_cselect_b32 s24, s59, s61
	v_lshl_add_u64 v[182:183], v[134:135], 0, vcc
	s_add_i32 m0, s23, 0xc000
	ds_read_b128 v[156:159], v139
	ds_read_b128 v[162:165], v139 offset:1024
	ds_read_b128 v[166:169], v139 offset:2048
	ds_read_b128 v[170:173], v139 offset:3072
	ds_read_b128 v[174:177], v139 offset:4096
	ds_read_b128 v[178:181], v139 offset:5120
	ds_read_b128 v[196:199], v139 offset:6144
	ds_read_b128 v[200:203], v139 offset:7168
	global_load_lds_dwordx4 v[182:183], off
	v_lshl_add_u64 v[182:183], v[136:137], 0, vcc
	s_add_i32 m0, s23, 0xe000
	s_nop 0
	global_load_lds_dwordx4 v[182:183], off
	v_add_u32_e32 v216, 0x14000, v138
	ds_read_b128 v[204:207], v216
	ds_read_b128 v[208:211], v216 offset:1024
	ds_read_b128 v[212:215], v216 offset:2048
	ds_read_b128 v[216:219], v216 offset:3072
	s_waitcnt vmcnt(8)
	s_waitcnt lgkmcnt(0)
	s_barrier
	s_setprio 1
	v_mfma_f32_16x16x32_bf16 v[124:127], v[140:143], v[156:159], v[124:127]
	v_mfma_f32_16x16x32_bf16 v[120:123], v[148:151], v[156:159], v[120:123]
	v_mfma_f32_16x16x32_bf16 v[108:111], v[140:143], v[166:169], v[108:111]
	v_mfma_f32_16x16x32_bf16 v[104:107], v[148:151], v[166:169], v[104:107]
	v_mfma_f32_16x16x32_bf16 v[92:95], v[140:143], v[174:177], v[92:95]
	v_mfma_f32_16x16x32_bf16 v[88:91], v[148:151], v[174:177], v[88:91]
	v_mfma_f32_16x16x32_bf16 v[76:79], v[140:143], v[196:199], v[76:79]
	v_mfma_f32_16x16x32_bf16 v[72:75], v[148:151], v[196:199], v[72:75]
	v_mfma_f32_16x16x32_bf16 v[124:127], v[144:147], v[162:165], v[124:127]
	v_mfma_f32_16x16x32_bf16 v[120:123], v[152:155], v[162:165], v[120:123]
	v_mfma_f32_16x16x32_bf16 v[108:111], v[144:147], v[170:173], v[108:111]
	v_mfma_f32_16x16x32_bf16 v[104:107], v[152:155], v[170:173], v[104:107]
	v_mfma_f32_16x16x32_bf16 v[92:95], v[144:147], v[178:181], v[92:95]
	v_mfma_f32_16x16x32_bf16 v[88:91], v[152:155], v[178:181], v[88:91]
	v_mfma_f32_16x16x32_bf16 v[76:79], v[144:147], v[200:203], v[76:79]
	v_mfma_f32_16x16x32_bf16 v[72:75], v[152:155], v[200:203], v[72:75]
	v_mfma_f32_16x16x32_bf16 v[116:119], v[204:207], v[156:159], v[116:119]
	v_mfma_f32_16x16x32_bf16 v[112:115], v[212:215], v[156:159], v[112:115]
	v_mfma_f32_16x16x32_bf16 v[100:103], v[204:207], v[166:169], v[100:103]
	v_mfma_f32_16x16x32_bf16 v[96:99], v[212:215], v[166:169], v[96:99]
	v_mfma_f32_16x16x32_bf16 v[84:87], v[204:207], v[174:177], v[84:87]
	v_mfma_f32_16x16x32_bf16 v[80:83], v[212:215], v[174:177], v[80:83]
	v_mfma_f32_16x16x32_bf16 v[68:71], v[204:207], v[196:199], v[68:71]
	v_mfma_f32_16x16x32_bf16 v[64:67], v[212:215], v[196:199], v[64:67]
	v_mfma_f32_16x16x32_bf16 v[116:119], v[208:211], v[162:165], v[116:119]
	v_mfma_f32_16x16x32_bf16 v[112:115], v[216:219], v[162:165], v[112:115]
	v_mfma_f32_16x16x32_bf16 v[100:103], v[208:211], v[170:173], v[100:103]
	v_mfma_f32_16x16x32_bf16 v[96:99], v[216:219], v[170:173], v[96:99]
	v_mfma_f32_16x16x32_bf16 v[84:87], v[208:211], v[178:181], v[84:87]
	v_mfma_f32_16x16x32_bf16 v[80:83], v[216:219], v[178:181], v[80:83]
	v_mfma_f32_16x16x32_bf16 v[68:71], v[208:211], v[200:203], v[68:71]
	v_mfma_f32_16x16x32_bf16 v[64:67], v[216:219], v[200:203], v[64:67]
	s_setprio 0
	s_barrier
	s_add_i32 s61, 0, 0x14000
	s_add_i32 s62, s63, s17
	v_lshl_add_u64 v[182:183], s[24:25], 0, v[186:187]
	s_mov_b32 m0, s62
	global_load_lds_dwordx4 v[182:183], off
	v_lshl_add_u64 v[220:221], s[24:25], 0, v[128:129]
	s_add_i32 m0, s62, 0x2000
	s_nop 0
	global_load_lds_dwordx4 v[220:221], off
	s_mov_b32 m0, s23
	v_lshl_add_u64 v[222:223], s[26:27], 0, v[186:187]
	ds_read_b128 v[156:159], v139 offset:16384
	ds_read_b128 v[162:165], v139 offset:17408
	ds_read_b128 v[166:169], v139 offset:18432
	ds_read_b128 v[170:173], v139 offset:19456
	ds_read_b128 v[174:177], v139 offset:20480
	ds_read_b128 v[178:181], v139 offset:21504
	ds_read_b128 v[196:199], v139 offset:22528
	ds_read_b128 v[200:203], v139 offset:23552
	global_load_lds_dwordx4 v[222:223], off
	v_lshl_add_u64 v[224:225], s[26:27], 0, v[128:129]
	s_mov_b32 m0, s30
	s_nop 0
	global_load_lds_dwordx4 v[224:225], off
	s_waitcnt vmcnt(6)
	s_waitcnt lgkmcnt(0)
	s_barrier
	s_setprio 1
	v_mfma_f32_16x16x32_bf16 v[60:63], v[140:143], v[156:159], v[60:63]
	v_mfma_f32_16x16x32_bf16 v[56:59], v[148:151], v[156:159], v[56:59]
	v_mfma_f32_16x16x32_bf16 v[44:47], v[140:143], v[166:169], v[44:47]
	v_mfma_f32_16x16x32_bf16 v[40:43], v[148:151], v[166:169], v[40:43]
	v_mfma_f32_16x16x32_bf16 v[32:35], v[140:143], v[174:177], v[32:35]
	v_mfma_f32_16x16x32_bf16 v[24:27], v[148:151], v[174:177], v[24:27]
	v_mfma_f32_16x16x32_bf16 v[16:19], v[140:143], v[196:199], v[16:19]
	v_mfma_f32_16x16x32_bf16 v[8:11], v[148:151], v[196:199], v[8:11]
	v_mfma_f32_16x16x32_bf16 v[60:63], v[144:147], v[162:165], v[60:63]
	v_mfma_f32_16x16x32_bf16 v[56:59], v[152:155], v[162:165], v[56:59]
	v_mfma_f32_16x16x32_bf16 v[44:47], v[144:147], v[170:173], v[44:47]
	v_mfma_f32_16x16x32_bf16 v[40:43], v[152:155], v[170:173], v[40:43]
	v_mfma_f32_16x16x32_bf16 v[32:35], v[144:147], v[178:181], v[32:35]
	v_mfma_f32_16x16x32_bf16 v[24:27], v[152:155], v[178:181], v[24:27]
	v_mfma_f32_16x16x32_bf16 v[16:19], v[144:147], v[200:203], v[16:19]
	v_mfma_f32_16x16x32_bf16 v[8:11], v[152:155], v[200:203], v[8:11]
	v_mfma_f32_16x16x32_bf16 v[52:55], v[204:207], v[156:159], v[52:55]
	v_mfma_f32_16x16x32_bf16 v[48:51], v[212:215], v[156:159], v[48:51]
	v_mfma_f32_16x16x32_bf16 v[36:39], v[204:207], v[166:169], v[36:39]
	v_mfma_f32_16x16x32_bf16 v[28:31], v[212:215], v[166:169], v[28:31]
	v_mfma_f32_16x16x32_bf16 v[20:23], v[204:207], v[174:177], v[20:23]
	v_mfma_f32_16x16x32_bf16 v[12:15], v[212:215], v[174:177], v[12:15]
	v_mfma_f32_16x16x32_bf16 v[4:7], v[204:207], v[196:199], v[4:7]
	v_mfma_f32_16x16x32_bf16 v[0:3], v[212:215], v[196:199], v[0:3]
	v_mfma_f32_16x16x32_bf16 v[52:55], v[208:211], v[162:165], v[52:55]
	v_mfma_f32_16x16x32_bf16 v[48:51], v[216:219], v[162:165], v[48:51]
	v_mfma_f32_16x16x32_bf16 v[36:39], v[208:211], v[170:173], v[36:39]
	v_mfma_f32_16x16x32_bf16 v[28:31], v[216:219], v[170:173], v[28:31]
	v_mfma_f32_16x16x32_bf16 v[20:23], v[208:211], v[178:181], v[20:23]
	v_mfma_f32_16x16x32_bf16 v[12:15], v[216:219], v[178:181], v[12:15]
	v_mfma_f32_16x16x32_bf16 v[4:7], v[208:211], v[200:203], v[4:7]
	v_mfma_f32_16x16x32_bf16 v[0:3], v[216:219], v[200:203], v[0:3]
	s_setprio 0
	s_barrier
	s_add_u32 s62, s24, 0x200000
	s_addc_u32 s63, s25, 0
	s_add_i32 s61, s61, s17
	v_lshl_add_u64 v[140:141], s[62:63], 0, v[186:187]
	s_mov_b32 m0, s61
	s_nop 0
	global_load_lds_dwordx4 v[140:141], off
	v_lshl_add_u64 v[140:141], s[62:63], 0, v[128:129]
	s_add_i32 m0, s61, 0x2000
	s_nop 0
	global_load_lds_dwordx4 v[140:141], off
	s_add_i32 s61, 0, 0x18000
	v_add_u32_e32 v152, s61, v138
	ds_read_b128 v[140:143], v152
	ds_read_b128 v[144:147], v152 offset:1024
	ds_read_b128 v[148:151], v152 offset:2048
	ds_read_b128 v[152:155], v152 offset:3072
	s_add_u32 s26, s26, 0x200000
	s_addc_u32 s27, s27, 0
	s_mov_b32 m0, s31
	v_lshl_add_u64 v[204:205], s[26:27], 0, v[186:187]
	ds_read_b128 v[156:159], v139 offset:32768
	ds_read_b128 v[162:165], v139 offset:33792
	ds_read_b128 v[166:169], v139 offset:34816
	ds_read_b128 v[170:173], v139 offset:35840
	ds_read_b128 v[174:177], v139 offset:36864
	ds_read_b128 v[178:181], v139 offset:37888
	ds_read_b128 v[196:199], v139 offset:38912
	ds_read_b128 v[200:203], v139 offset:39936
	global_load_lds_dwordx4 v[204:205], off
	v_lshl_add_u64 v[204:205], s[26:27], 0, v[128:129]
	s_mov_b32 m0, s52
	s_nop 0
	global_load_lds_dwordx4 v[204:205], off
	v_add_u32_e32 v216, 0x1c000, v138
	ds_read_b128 v[204:207], v216
	ds_read_b128 v[208:211], v216 offset:1024
	ds_read_b128 v[212:215], v216 offset:2048
	ds_read_b128 v[216:219], v216 offset:3072
	s_waitcnt vmcnt(8)
	s_waitcnt lgkmcnt(0)
	s_barrier
	s_setprio 1
	v_mfma_f32_16x16x32_bf16 v[124:127], v[140:143], v[156:159], v[124:127]
	v_mfma_f32_16x16x32_bf16 v[120:123], v[148:151], v[156:159], v[120:123]
	v_mfma_f32_16x16x32_bf16 v[108:111], v[140:143], v[166:169], v[108:111]
	v_mfma_f32_16x16x32_bf16 v[104:107], v[148:151], v[166:169], v[104:107]
	v_mfma_f32_16x16x32_bf16 v[92:95], v[140:143], v[174:177], v[92:95]
	v_mfma_f32_16x16x32_bf16 v[88:91], v[148:151], v[174:177], v[88:91]
	v_mfma_f32_16x16x32_bf16 v[76:79], v[140:143], v[196:199], v[76:79]
	v_mfma_f32_16x16x32_bf16 v[72:75], v[148:151], v[196:199], v[72:75]
	v_mfma_f32_16x16x32_bf16 v[124:127], v[144:147], v[162:165], v[124:127]
	v_mfma_f32_16x16x32_bf16 v[120:123], v[152:155], v[162:165], v[120:123]
	v_mfma_f32_16x16x32_bf16 v[108:111], v[144:147], v[170:173], v[108:111]
	v_mfma_f32_16x16x32_bf16 v[104:107], v[152:155], v[170:173], v[104:107]
	v_mfma_f32_16x16x32_bf16 v[92:95], v[144:147], v[178:181], v[92:95]
	v_mfma_f32_16x16x32_bf16 v[88:91], v[152:155], v[178:181], v[88:91]
	v_mfma_f32_16x16x32_bf16 v[76:79], v[144:147], v[200:203], v[76:79]
	v_mfma_f32_16x16x32_bf16 v[72:75], v[152:155], v[200:203], v[72:75]
	v_mfma_f32_16x16x32_bf16 v[116:119], v[204:207], v[156:159], v[116:119]
	v_mfma_f32_16x16x32_bf16 v[112:115], v[212:215], v[156:159], v[112:115]
	v_mfma_f32_16x16x32_bf16 v[100:103], v[204:207], v[166:169], v[100:103]
	v_mfma_f32_16x16x32_bf16 v[96:99], v[212:215], v[166:169], v[96:99]
	v_mfma_f32_16x16x32_bf16 v[84:87], v[204:207], v[174:177], v[84:87]
	v_mfma_f32_16x16x32_bf16 v[80:83], v[212:215], v[174:177], v[80:83]
	v_mfma_f32_16x16x32_bf16 v[68:71], v[204:207], v[196:199], v[68:71]
	v_mfma_f32_16x16x32_bf16 v[64:67], v[212:215], v[196:199], v[64:67]
	v_mfma_f32_16x16x32_bf16 v[116:119], v[208:211], v[162:165], v[116:119]
	v_mfma_f32_16x16x32_bf16 v[112:115], v[216:219], v[162:165], v[112:115]
	v_mfma_f32_16x16x32_bf16 v[100:103], v[208:211], v[170:173], v[100:103]
	v_mfma_f32_16x16x32_bf16 v[96:99], v[216:219], v[170:173], v[96:99]
	v_mfma_f32_16x16x32_bf16 v[84:87], v[208:211], v[178:181], v[84:87]
	v_mfma_f32_16x16x32_bf16 v[80:83], v[216:219], v[178:181], v[80:83]
	v_mfma_f32_16x16x32_bf16 v[68:71], v[208:211], v[200:203], v[68:71]
	v_mfma_f32_16x16x32_bf16 v[64:67], v[216:219], v[200:203], v[64:67]
	s_setprio 0
	s_barrier
	s_add_i32 s26, 0, 0x1c000
	s_add_i32 s27, s61, s17
	v_lshl_add_u64 v[182:183], v[182:183], 0, s[0:1]
	s_mov_b32 m0, s27
	global_load_lds_dwordx4 v[182:183], off
	v_lshl_add_u64 v[182:183], v[220:221], 0, s[0:1]
	s_add_i32 m0, s27, 0x2000
	s_nop 0
	global_load_lds_dwordx4 v[182:183], off
	s_mov_b32 m0, s53
	v_lshl_add_u64 v[182:183], v[222:223], 0, s[0:1]
	ds_read_b128 v[156:159], v139 offset:49152
	ds_read_b128 v[162:165], v139 offset:50176
	ds_read_b128 v[166:169], v139 offset:51200
	ds_read_b128 v[170:173], v139 offset:52224
	ds_read_b128 v[174:177], v139 offset:53248
	ds_read_b128 v[178:181], v139 offset:54272
	ds_read_b128 v[196:199], v139 offset:55296
	ds_read_b128 v[200:203], v139 offset:56320
	global_load_lds_dwordx4 v[182:183], off
	v_lshl_add_u64 v[182:183], v[224:225], 0, s[0:1]
	s_mov_b32 m0, s68
	s_nop 0
	global_load_lds_dwordx4 v[182:183], off
	s_add_u32 s24, s24, 0x200080
	s_addc_u32 s25, s25, 0
	s_add_i32 s26, s26, s17
	v_lshl_add_u64 v[182:183], s[24:25], 0, v[186:187]
	s_mov_b32 m0, s26
	s_nop 0
	global_load_lds_dwordx4 v[182:183], off
	v_lshl_add_u64 v[182:183], s[24:25], 0, v[128:129]
	s_add_i32 m0, s26, 0x2000
	s_nop 0
	global_load_lds_dwordx4 v[182:183], off
	s_waitcnt vmcnt(8)
	s_waitcnt lgkmcnt(0)
	s_barrier
	s_setprio 1
	v_mfma_f32_16x16x32_bf16 v[60:63], v[140:143], v[156:159], v[60:63]
	v_mfma_f32_16x16x32_bf16 v[56:59], v[148:151], v[156:159], v[56:59]
	v_mfma_f32_16x16x32_bf16 v[44:47], v[140:143], v[166:169], v[44:47]
	v_mfma_f32_16x16x32_bf16 v[40:43], v[148:151], v[166:169], v[40:43]
	v_mfma_f32_16x16x32_bf16 v[32:35], v[140:143], v[174:177], v[32:35]
	v_mfma_f32_16x16x32_bf16 v[24:27], v[148:151], v[174:177], v[24:27]
	v_mfma_f32_16x16x32_bf16 v[16:19], v[140:143], v[196:199], v[16:19]
	v_mfma_f32_16x16x32_bf16 v[8:11], v[148:151], v[196:199], v[8:11]
	v_mfma_f32_16x16x32_bf16 v[60:63], v[144:147], v[162:165], v[60:63]
	v_mfma_f32_16x16x32_bf16 v[56:59], v[152:155], v[162:165], v[56:59]
	v_mfma_f32_16x16x32_bf16 v[44:47], v[144:147], v[170:173], v[44:47]
	v_mfma_f32_16x16x32_bf16 v[40:43], v[152:155], v[170:173], v[40:43]
	v_mfma_f32_16x16x32_bf16 v[32:35], v[144:147], v[178:181], v[32:35]
	v_mfma_f32_16x16x32_bf16 v[24:27], v[152:155], v[178:181], v[24:27]
	v_mfma_f32_16x16x32_bf16 v[16:19], v[144:147], v[200:203], v[16:19]
	v_mfma_f32_16x16x32_bf16 v[8:11], v[152:155], v[200:203], v[8:11]
	v_mfma_f32_16x16x32_bf16 v[52:55], v[204:207], v[156:159], v[52:55]
	v_mfma_f32_16x16x32_bf16 v[48:51], v[212:215], v[156:159], v[48:51]
	v_mfma_f32_16x16x32_bf16 v[36:39], v[204:207], v[166:169], v[36:39]
	v_mfma_f32_16x16x32_bf16 v[28:31], v[212:215], v[166:169], v[28:31]
	v_mfma_f32_16x16x32_bf16 v[20:23], v[204:207], v[174:177], v[20:23]
	v_mfma_f32_16x16x32_bf16 v[12:15], v[212:215], v[174:177], v[12:15]
	v_mfma_f32_16x16x32_bf16 v[4:7], v[204:207], v[196:199], v[4:7]
	v_mfma_f32_16x16x32_bf16 v[0:3], v[212:215], v[196:199], v[0:3]
	v_mfma_f32_16x16x32_bf16 v[52:55], v[208:211], v[162:165], v[52:55]
	v_mfma_f32_16x16x32_bf16 v[48:51], v[216:219], v[162:165], v[48:51]
	v_mfma_f32_16x16x32_bf16 v[36:39], v[208:211], v[170:173], v[36:39]
	v_mfma_f32_16x16x32_bf16 v[28:31], v[216:219], v[170:173], v[28:31]
	v_mfma_f32_16x16x32_bf16 v[20:23], v[208:211], v[178:181], v[20:23]
	v_mfma_f32_16x16x32_bf16 v[12:15], v[216:219], v[178:181], v[12:15]
	v_mfma_f32_16x16x32_bf16 v[4:7], v[208:211], v[200:203], v[4:7]
	v_mfma_f32_16x16x32_bf16 v[0:3], v[216:219], v[200:203], v[0:3]
	s_setprio 0
	s_add_i32 s60, s60, 2
	s_add_u32 vcc_lo, vcc_lo, 0x100
	s_addc_u32 vcc_hi, vcc_hi, 0
	s_cmpk_gt_u32 s60, 0x7d
	s_barrier
	s_cbranch_scc0 .LBB0_940
	s_add_u32 s24, s19, 0xffffff00
	s_addc_u32 s25, s4, -1
	s_andn2_b64 vcc, exec, s[44:45]
	s_cbranch_vccnz .LBB0_931
	v_mov_b32_e32 v0, 0
	s_mov_b32 s18, s28
	s_mov_b32 s56, s38
	s_mov_b64 s[2:3], s[20:21]
	s_mov_b32 s69, s57
	v_mov_b32_e32 v1, v0
	v_mov_b32_e32 v2, v0
	v_mov_b32_e32 v3, v0
	v_mov_b32_e32 v4, v0
	v_mov_b32_e32 v5, v0
	v_mov_b32_e32 v6, v0
	v_mov_b32_e32 v7, v0
	v_mov_b32_e32 v12, v0
	v_mov_b32_e32 v13, v0
	v_mov_b32_e32 v14, v0
	v_mov_b32_e32 v15, v0
	v_mov_b32_e32 v20, v0
	v_mov_b32_e32 v21, v0
	v_mov_b32_e32 v22, v0
	v_mov_b32_e32 v23, v0
	v_mov_b32_e32 v28, v0
	v_mov_b32_e32 v29, v0
	v_mov_b32_e32 v30, v0
	v_mov_b32_e32 v31, v0
	v_mov_b32_e32 v36, v0
	v_mov_b32_e32 v37, v0
	v_mov_b32_e32 v38, v0
	v_mov_b32_e32 v39, v0
	v_mov_b32_e32 v48, v0
	v_mov_b32_e32 v49, v0
	v_mov_b32_e32 v50, v0
	v_mov_b32_e32 v51, v0
	v_mov_b32_e32 v52, v0
	v_mov_b32_e32 v53, v0
	v_mov_b32_e32 v54, v0
	v_mov_b32_e32 v55, v0
	v_mov_b32_e32 v8, v0
	v_mov_b32_e32 v9, v0
	v_mov_b32_e32 v10, v0
	v_mov_b32_e32 v11, v0
	v_mov_b32_e32 v16, v0
	v_mov_b32_e32 v17, v0
	v_mov_b32_e32 v18, v0
	v_mov_b32_e32 v19, v0
	v_mov_b32_e32 v24, v0
	v_mov_b32_e32 v25, v0
	v_mov_b32_e32 v26, v0
	v_mov_b32_e32 v27, v0
	v_mov_b32_e32 v32, v0
	v_mov_b32_e32 v33, v0
	v_mov_b32_e32 v34, v0
	v_mov_b32_e32 v35, v0
	v_mov_b32_e32 v40, v0
	v_mov_b32_e32 v41, v0
	v_mov_b32_e32 v42, v0
	v_mov_b32_e32 v43, v0
	v_mov_b32_e32 v44, v0
	v_mov_b32_e32 v45, v0
	v_mov_b32_e32 v46, v0
	v_mov_b32_e32 v47, v0
	v_mov_b32_e32 v56, v0
	v_mov_b32_e32 v57, v0
	v_mov_b32_e32 v58, v0
	v_mov_b32_e32 v59, v0
	v_mov_b32_e32 v60, v0
	v_mov_b32_e32 v61, v0
	v_mov_b32_e32 v62, v0
	v_mov_b32_e32 v63, v0
	v_mov_b32_e32 v64, v0
	v_mov_b32_e32 v65, v0
	v_mov_b32_e32 v66, v0
	v_mov_b32_e32 v67, v0
	v_mov_b32_e32 v68, v0
	v_mov_b32_e32 v69, v0
	v_mov_b32_e32 v70, v0
	v_mov_b32_e32 v71, v0
	v_mov_b32_e32 v80, v0
	v_mov_b32_e32 v81, v0
	v_mov_b32_e32 v82, v0
	v_mov_b32_e32 v83, v0
	v_mov_b32_e32 v84, v0
	v_mov_b32_e32 v85, v0
	v_mov_b32_e32 v86, v0
	v_mov_b32_e32 v87, v0
	v_mov_b32_e32 v96, v0
	v_mov_b32_e32 v97, v0
	v_mov_b32_e32 v98, v0
	v_mov_b32_e32 v99, v0
	v_mov_b32_e32 v100, v0
	v_mov_b32_e32 v101, v0
	v_mov_b32_e32 v102, v0
	v_mov_b32_e32 v103, v0
	v_mov_b32_e32 v112, v0
	v_mov_b32_e32 v113, v0
	v_mov_b32_e32 v114, v0
	v_mov_b32_e32 v115, v0
	v_mov_b32_e32 v116, v0
	v_mov_b32_e32 v117, v0
	v_mov_b32_e32 v118, v0
	v_mov_b32_e32 v119, v0
	v_mov_b32_e32 v72, v0
	v_mov_b32_e32 v73, v0
	v_mov_b32_e32 v74, v0
	v_mov_b32_e32 v75, v0
	v_mov_b32_e32 v76, v0
	v_mov_b32_e32 v77, v0
	v_mov_b32_e32 v78, v0
	v_mov_b32_e32 v79, v0
	v_mov_b32_e32 v88, v0
	v_mov_b32_e32 v89, v0
	v_mov_b32_e32 v90, v0
	v_mov_b32_e32 v91, v0
	v_mov_b32_e32 v92, v0
	v_mov_b32_e32 v93, v0
	v_mov_b32_e32 v94, v0
	v_mov_b32_e32 v95, v0
	v_mov_b32_e32 v104, v0
	v_mov_b32_e32 v105, v0
	v_mov_b32_e32 v106, v0
	v_mov_b32_e32 v107, v0
	v_mov_b32_e32 v108, v0
	v_mov_b32_e32 v109, v0
	v_mov_b32_e32 v110, v0
	v_mov_b32_e32 v111, v0
	v_mov_b32_e32 v120, v0
	v_mov_b32_e32 v121, v0
	v_mov_b32_e32 v122, v0
	v_mov_b32_e32 v123, v0
	v_mov_b32_e32 v124, v0
	v_mov_b32_e32 v125, v0
	v_mov_b32_e32 v126, v0
	v_mov_b32_e32 v127, v0
	s_andn2_b64 vcc, exec, s[42:43]
	s_cbranch_vccnz .LBB0_932
